# k15b + first K-loop iteration peeled in the 7 main GEMM loops (first MFMA per accumulator takes C=0; per-unit accumulator clears removed)
# baseline (speedup 1.0000x reference)
;     __host__ __device__ bool next(int i, Unit& u) const { const int idx = first + i; if (idx >= last) return false; u.pm = idx >> 2; u.pn = idx & 3; return true; }
; #define PG8_STAGE(bufoff, gbase, voff) do { _Pragma("unroll") for (int _i = 0; _i < 2; ++_i) \
;         __builtin_amdgcn_global_load_lds((const unsigned*)((const char*)(gbase) + (voff)[_i]), (PG8_LAS unsigned*)(lds + (bufoff) + ldsw + _i * 8192), 16, 0, 0); } while (0)
; #define PG8_LDA(dst, b, h) do { _Pragma("unroll") for (int m = 0; m < 4; ++m) _Pragma("unroll") for (int k = 0; k < 2; ++k) dst[m][k] = *(const PG8_LAS bf16x8*)(lds + PG8_SA(b, h) + aoff + m * 2048 + k * 1024); } while (0)
; #define PG8_LDB(dst, b, h) do { _Pragma("unroll") for (int n = 0; n < 2; ++n) _Pragma("unroll") for (int k = 0; k < 2; ++k) dst[n][k] = *(const PG8_LAS bf16x8*)(lds + PG8_SB(b, h) + boff + n * 2048 + k * 1024); } while (0)
; #define PG8_WAIT_V(n) asm volatile("s_waitcnt vmcnt(" #n ")" ::: "memory")
; #define PG8_WAIT_L(n) asm volatile("s_waitcnt lgkmcnt(" #n ")" ::: "memory")
; #define PG8_BAR __builtin_amdgcn_s_barrier()
; template <class Epi, class Sched, bool ALIGN_EPI = false, bool SP2 = false>
; __device__ __forceinline__ void gemm_phase(PG8_LAS unsigned char* lds, const Gemm g, const Sched& S, const Epi& E) {
;     ...
;     for (;;) {
;         const bool has_next = S.next(ui + 1, nxt);
;         const char* nA = has_next ? (const char*)g.A + (size_t)nxt.pm * tstep : cA; const char* nB = has_next ? (const char*)g.Bt + (size_t)nxt.pn * tstep : cB;
;         asm volatile(".p2align 8");
;         for (int t = 0; t < nt; t += 2) {
;             const bool last = (t == nt - 2);
;             const char* a1 = cA + (size_t)(t + 1) * kstep;
;             const char* a2 = last ? nA : cA + (size_t)(t + 2) * kstep; const char* b2 = last ? nB : cB + (size_t)(t + 2) * kstep;
;             const char* a3 = a2 + kstep; const char* b3 = b2 + kstep;
;             if (last && has_next) S.a_ready(nxt);
;             if constexpr (SP2) {
;             PG8_LDB(B0, 0, 0); PG8_LDB(B1, 0, 1); PG8_SCHED; PG8_LDA(At, 0, 0); PG8_STAGE(PG8_SA(1, 1), a1 + hstep, voffA);
;             PG8_WAIT_V(8); PG8_WAIT_L(0); PG8_BAR; PG8_MMA(0, 0, At, B0); PG8_MMA(0, 1, At, B1); PG8_BAR; PG8_SCHED;
;             PG8_LDA(At, 0, 1); PG8_STAGE(PG8_SB(0, 0), b2, voffB); PG8_STAGE(PG8_SB(0, 1), b2 + hstep, voffB); PG8_STAGE(PG8_SA(0, 0), a2, voffA);
.LBB0_262:
	s_andn2_b64 vcc, exec, s[20:21]
	s_waitcnt vmcnt(0)
	s_waitcnt lgkmcnt(0)
	.p2align 8
	s_cbranch_vccnz .Lpz_k264
	s_add_u32 s40, s40, 0x80
	s_addc_u32 s41, s41, 0
	s_add_u32 s33, s42, 0x100
	s_addc_u32 s38, s43, 0
	s_mov_b32 s42, 0
.Lpeel_k264:
	ds_read_b128 v[148:151], v168
	ds_read_b128 v[152:155], v168 offset:1024
	ds_read_b128 v[156:159], v168 offset:2048
	ds_read_b128 v[160:163], v168 offset:3072
	ds_read_b128 v[174:177], v169
	ds_read_b128 v[178:181], v169 offset:1024
	ds_read_b128 v[182:185], v169 offset:2048
	ds_read_b128 v[186:189], v169 offset:3072
	s_add_i32 s71, s42, 2
	s_add_u32 s72, s40, 0x80
	s_addc_u32 s43, s41, 0
	s_cmp_eq_u32 s63, s42
	s_cselect_b32 s42, s8, s72
	s_cselect_b32 s43, s9, s43
	s_cselect_b32 s73, s37, s38
	s_cselect_b32 s72, s36, s33
	v_lshl_add_u64 v[164:165], s[40:41], 0, v[140:141]
	s_add_i32 m0, s56, 0xc000
	ds_read_b128 v[194:197], v170
	ds_read_b128 v[198:201], v170 offset:1024
	ds_read_b128 v[202:205], v170 offset:2048
	ds_read_b128 v[206:209], v170 offset:3072
	ds_read_b128 v[210:213], v170 offset:4096
	ds_read_b128 v[214:217], v170 offset:5120
	ds_read_b128 v[218:221], v170 offset:6144
	ds_read_b128 v[222:225], v170 offset:7168
	global_load_lds_dwordx4 v[164:165], off
	v_lshl_add_u64 v[164:165], s[40:41], 0, v[142:143]
	s_add_i32 m0, s56, 0xe000
	s_nop 0
	global_load_lds_dwordx4 v[164:165], off
	s_waitcnt vmcnt(8)
	s_waitcnt lgkmcnt(0)
	s_barrier
	s_setprio 1
	s_waitcnt lgkmcnt(0)
	v_mfma_f32_16x16x32_bf16 v[120:123], v[148:151], v[194:197], 0
	v_mfma_f32_16x16x32_bf16 v[116:119], v[156:159], v[194:197], 0
	v_mfma_f32_16x16x32_bf16 v[108:111], v[148:151], v[202:205], 0
	v_mfma_f32_16x16x32_bf16 v[100:103], v[156:159], v[202:205], 0
	v_mfma_f32_16x16x32_bf16 v[92:95], v[148:151], v[210:213], 0
	v_mfma_f32_16x16x32_bf16 v[84:87], v[156:159], v[210:213], 0
	v_mfma_f32_16x16x32_bf16 v[76:79], v[148:151], v[218:221], 0
	v_mfma_f32_16x16x32_bf16 v[68:71], v[156:159], v[218:221], 0
	v_mfma_f32_16x16x32_bf16 v[120:123], v[152:155], v[198:201], v[120:123]
	v_mfma_f32_16x16x32_bf16 v[116:119], v[160:163], v[198:201], v[116:119]
	v_mfma_f32_16x16x32_bf16 v[108:111], v[152:155], v[206:209], v[108:111]
	v_mfma_f32_16x16x32_bf16 v[100:103], v[160:163], v[206:209], v[100:103]
	v_mfma_f32_16x16x32_bf16 v[92:95], v[152:155], v[214:217], v[92:95]
	v_mfma_f32_16x16x32_bf16 v[84:87], v[160:163], v[214:217], v[84:87]
	v_mfma_f32_16x16x32_bf16 v[76:79], v[152:155], v[222:225], v[76:79]
	v_mfma_f32_16x16x32_bf16 v[68:71], v[160:163], v[222:225], v[68:71]
	s_setprio 0
	s_setprio 1
	v_mfma_f32_16x16x32_bf16 v[124:127], v[174:177], v[194:197], 0
	v_mfma_f32_16x16x32_bf16 v[112:115], v[182:185], v[194:197], 0
	v_mfma_f32_16x16x32_bf16 v[104:107], v[174:177], v[202:205], 0
	v_mfma_f32_16x16x32_bf16 v[96:99], v[182:185], v[202:205], 0
	v_mfma_f32_16x16x32_bf16 v[88:91], v[174:177], v[210:213], 0
	v_mfma_f32_16x16x32_bf16 v[80:83], v[182:185], v[210:213], 0
	v_mfma_f32_16x16x32_bf16 v[72:75], v[174:177], v[218:221], 0
	v_mfma_f32_16x16x32_bf16 v[64:67], v[182:185], v[218:221], 0
	v_mfma_f32_16x16x32_bf16 v[124:127], v[178:181], v[198:201], v[124:127]
	v_mfma_f32_16x16x32_bf16 v[112:115], v[186:189], v[198:201], v[112:115]
	v_mfma_f32_16x16x32_bf16 v[104:107], v[178:181], v[206:209], v[104:107]
	v_mfma_f32_16x16x32_bf16 v[96:99], v[186:189], v[206:209], v[96:99]
	v_mfma_f32_16x16x32_bf16 v[88:91], v[178:181], v[214:217], v[88:91]
	v_mfma_f32_16x16x32_bf16 v[80:83], v[186:189], v[214:217], v[80:83]
	v_mfma_f32_16x16x32_bf16 v[72:75], v[178:181], v[222:225], v[72:75]
	v_mfma_f32_16x16x32_bf16 v[64:67], v[186:189], v[222:225], v[64:67]
	s_setprio 0
	s_barrier
	s_add_i32 s74, s66, s3
	v_lshl_add_u64 v[164:165], s[72:73], 0, v[134:135]
	s_mov_b32 m0, s74
	ds_read_b128 v[194:197], v170 offset:16384
	ds_read_b128 v[198:201], v170 offset:17408
	ds_read_b128 v[202:205], v170 offset:18432
	ds_read_b128 v[206:209], v170 offset:19456
	ds_read_b128 v[210:213], v170 offset:20480
	ds_read_b128 v[214:217], v170 offset:21504
	ds_read_b128 v[218:221], v170 offset:22528
	ds_read_b128 v[222:225], v170 offset:23552
	global_load_lds_dwordx4 v[164:165], off
	s_add_i32 m0, s74, 0x2000
	v_lshl_add_u64 v[190:191], s[72:73], 0, v[130:131]
	s_add_u32 s72, s72, s12
	s_addc_u32 s73, s73, s13
	s_add_i32 s74, s67, s3
	global_load_lds_dwordx4 v[190:191], off
	v_lshl_add_u64 v[226:227], s[72:73], 0, v[134:135]
	s_mov_b32 m0, s74
	v_lshl_add_u64 v[228:229], s[72:73], 0, v[130:131]
	global_load_lds_dwordx4 v[226:227], off
	s_add_i32 m0, s74, 0x2000
	v_lshl_add_u64 v[230:231], s[42:43], 0, v[136:137]
	global_load_lds_dwordx4 v[228:229], off
	s_mov_b32 m0, s56
	v_lshl_add_u64 v[232:233], s[42:43], 0, v[132:133]
	global_load_lds_dwordx4 v[230:231], off
	s_mov_b32 m0, s57
	s_nop 0
	global_load_lds_dwordx4 v[232:233], off
	s_cmp_lg_u32 s71, 2
	s_cbranch_scc1 .Lss_p1_skip_pl
	s_lshl_b32 s84, s4, 14
	s_mov_b32 s85, 0
	s_add_i32 m0, s56, 0x20000
	v_lshl_add_u64 v[238:239], v[236:237], 0, s[84:85]
	s_add_u32 s84, s84, 0x2000
	global_load_lds_dwordx4 v[238:239], off
	s_add_i32 m0, s56, 0x22000
	v_lshl_add_u64 v[238:239], v[236:237], 0, s[84:85]
	global_load_lds_dwordx4 v[238:239], off
; #define PG8_STAGE(bufoff, gbase, voff) do { _Pragma("unroll") for (int _i = 0; _i < 2; ++_i) \
;         __builtin_amdgcn_global_load_lds((const unsigned*)((const char*)(gbase) + (voff)[_i]), (PG8_LAS unsigned*)(lds + (bufoff) + ldsw + _i * 8192), 16, 0, 0); } while (0)
; #define PG8_LDA(dst, b, h) do { _Pragma("unroll") for (int m = 0; m < 4; ++m) _Pragma("unroll") for (int k = 0; k < 2; ++k) dst[m][k] = *(const PG8_LAS bf16x8*)(lds + PG8_SA(b, h) + aoff + m * 2048 + k * 1024); } while (0)
; #define PG8_LDB(dst, b, h) do { _Pragma("unroll") for (int n = 0; n < 2; ++n) _Pragma("unroll") for (int k = 0; k < 2; ++k) dst[n][k] = *(const PG8_LAS bf16x8*)(lds + PG8_SB(b, h) + boff + n * 2048 + k * 1024); } while (0)
; #define PG8_MMA(ai, bj, At, Bt) do { __builtin_amdgcn_s_setprio(1); _Pragma("unroll") for (int m = 0; m < 4; ++m) _Pragma("unroll") for (int n = 0; n < 2; ++n) _Pragma("unroll") for (int k = 0; k < 2; ++k) \
;         acc[ai][bj][m][n] = __builtin_amdgcn_mfma_f32_16x16x32_bf16(Bt[n][k], At[m][k], acc[ai][bj][m][n], 0, 0, 0); __builtin_amdgcn_s_setprio(0); } while (0)
; #define PG8_WAIT_V(n) asm volatile("s_waitcnt vmcnt(" #n ")" ::: "memory")
; #define PG8_WAIT_L(n) asm volatile("s_waitcnt lgkmcnt(" #n ")" ::: "memory")
; #define PG8_BAR __builtin_amdgcn_s_barrier()
; #define PG8_SCHED __builtin_amdgcn_sched_barrier(0)
; template <class Epi, class Sched, bool ALIGN_EPI = false, bool SP2 = false>
; __device__ __forceinline__ void gemm_phase(PG8_LAS unsigned char* lds, const Gemm g, const Sched& S, const Epi& E) {
;     ...
;             PG8_WAIT_V(8); PG8_WAIT_L(0); PG8_BAR; PG8_MMA(0, 0, At, B0); PG8_MMA(0, 1, At, B1); PG8_BAR; PG8_SCHED;
;             PG8_LDA(At, 0, 1); PG8_STAGE(PG8_SB(0, 0), b2, voffB); PG8_STAGE(PG8_SB(0, 1), b2 + hstep, voffB); PG8_STAGE(PG8_SA(0, 0), a2, voffA);
;             PG8_WAIT_V(8); PG8_WAIT_L(0); PG8_BAR; PG8_MMA(1, 0, At, B0); PG8_MMA(1, 1, At, B1); PG8_BAR; PG8_SCHED;
;             PG8_LDB(B0, 1, 0); PG8_LDB(B1, 1, 1); PG8_SCHED; PG8_LDA(At, 1, 0); PG8_STAGE(PG8_SA(0, 1), a2 + hstep, voffA);
;             PG8_WAIT_V(8); PG8_WAIT_L(0); PG8_BAR; PG8_MMA(0, 0, At, B0); PG8_MMA(0, 1, At, B1); PG8_BAR; PG8_SCHED;
.Lss_p1_skip_pl:
	s_waitcnt vmcnt(8)
	s_waitcnt lgkmcnt(0)
	s_barrier
	s_setprio 1
	s_waitcnt lgkmcnt(0)
	v_mfma_f32_16x16x32_bf16 v[60:63], v[148:151], v[194:197], 0
	v_mfma_f32_16x16x32_bf16 v[52:55], v[156:159], v[194:197], 0
	v_mfma_f32_16x16x32_bf16 v[44:47], v[148:151], v[202:205], 0
	v_mfma_f32_16x16x32_bf16 v[36:39], v[156:159], v[202:205], 0
	v_mfma_f32_16x16x32_bf16 v[28:31], v[148:151], v[210:213], 0
	v_mfma_f32_16x16x32_bf16 v[20:23], v[156:159], v[210:213], 0
	v_mfma_f32_16x16x32_bf16 v[12:15], v[148:151], v[218:221], 0
	v_mfma_f32_16x16x32_bf16 v[4:7], v[156:159], v[218:221], 0
	v_mfma_f32_16x16x32_bf16 v[60:63], v[152:155], v[198:201], v[60:63]
	v_mfma_f32_16x16x32_bf16 v[52:55], v[160:163], v[198:201], v[52:55]
	v_mfma_f32_16x16x32_bf16 v[44:47], v[152:155], v[206:209], v[44:47]
	v_mfma_f32_16x16x32_bf16 v[36:39], v[160:163], v[206:209], v[36:39]
	v_mfma_f32_16x16x32_bf16 v[28:31], v[152:155], v[214:217], v[28:31]
	v_mfma_f32_16x16x32_bf16 v[20:23], v[160:163], v[214:217], v[20:23]
	v_mfma_f32_16x16x32_bf16 v[12:15], v[152:155], v[222:225], v[12:15]
	v_mfma_f32_16x16x32_bf16 v[4:7], v[160:163], v[222:225], v[4:7]
	s_setprio 0
	s_setprio 1
	v_mfma_f32_16x16x32_bf16 v[56:59], v[174:177], v[194:197], 0
	v_mfma_f32_16x16x32_bf16 v[48:51], v[182:185], v[194:197], 0
	v_mfma_f32_16x16x32_bf16 v[40:43], v[174:177], v[202:205], 0
	v_mfma_f32_16x16x32_bf16 v[32:35], v[182:185], v[202:205], 0
	v_mfma_f32_16x16x32_bf16 v[24:27], v[174:177], v[210:213], 0
	v_mfma_f32_16x16x32_bf16 v[16:19], v[182:185], v[210:213], 0
	v_mfma_f32_16x16x32_bf16 v[8:11], v[174:177], v[218:221], 0
	v_mfma_f32_16x16x32_bf16 v[0:3], v[182:185], v[218:221], 0
	v_mfma_f32_16x16x32_bf16 v[56:59], v[178:181], v[198:201], v[56:59]
	v_mfma_f32_16x16x32_bf16 v[48:51], v[186:189], v[198:201], v[48:51]
	v_mfma_f32_16x16x32_bf16 v[40:43], v[178:181], v[206:209], v[40:43]
	v_mfma_f32_16x16x32_bf16 v[32:35], v[186:189], v[206:209], v[32:35]
	v_mfma_f32_16x16x32_bf16 v[24:27], v[178:181], v[214:217], v[24:27]
	v_mfma_f32_16x16x32_bf16 v[16:19], v[186:189], v[214:217], v[16:19]
	v_mfma_f32_16x16x32_bf16 v[8:11], v[178:181], v[222:225], v[8:11]
	v_mfma_f32_16x16x32_bf16 v[0:3], v[186:189], v[222:225], v[0:3]
	s_setprio 0
	s_barrier
	s_add_i32 s72, 0, 0x18000
	v_add_u32_e32 v128, s72, v166
	s_add_i32 s73, 0, 0x1c000
	ds_read_b128 v[148:151], v128
	ds_read_b128 v[152:155], v128 offset:1024
	ds_read_b128 v[156:159], v128 offset:2048
	ds_read_b128 v[160:163], v128 offset:3072
	v_add_u32_e32 v128, s73, v166
	ds_read_b128 v[174:177], v128
	ds_read_b128 v[178:181], v128 offset:1024
	ds_read_b128 v[182:185], v128 offset:2048
	ds_read_b128 v[186:189], v128 offset:3072
	s_add_u32 s42, s42, s12
	s_addc_u32 s43, s43, s13
	s_mov_b32 m0, s58
	v_lshl_add_u64 v[234:235], s[42:43], 0, v[136:137]
	ds_read_b128 v[194:197], v170 offset:32768
	ds_read_b128 v[198:201], v170 offset:33792
	ds_read_b128 v[202:205], v170 offset:34816
	ds_read_b128 v[206:209], v170 offset:35840
	ds_read_b128 v[210:213], v170 offset:36864
	ds_read_b128 v[214:217], v170 offset:37888
	ds_read_b128 v[218:221], v170 offset:38912
	ds_read_b128 v[222:225], v170 offset:39936
	global_load_lds_dwordx4 v[234:235], off
	v_lshl_add_u64 v[234:235], s[42:43], 0, v[132:133]
	s_mov_b32 m0, s59
	s_nop 0
	global_load_lds_dwordx4 v[234:235], off
	s_waitcnt vmcnt(8)
	s_waitcnt lgkmcnt(0)
	s_barrier
	s_setprio 1
	s_waitcnt lgkmcnt(0)
	v_mfma_f32_16x16x32_bf16 v[120:123], v[148:151], v[194:197], v[120:123]
	v_mfma_f32_16x16x32_bf16 v[116:119], v[156:159], v[194:197], v[116:119]
	v_mfma_f32_16x16x32_bf16 v[108:111], v[148:151], v[202:205], v[108:111]
	v_mfma_f32_16x16x32_bf16 v[100:103], v[156:159], v[202:205], v[100:103]
	v_mfma_f32_16x16x32_bf16 v[92:95], v[148:151], v[210:213], v[92:95]
	v_mfma_f32_16x16x32_bf16 v[84:87], v[156:159], v[210:213], v[84:87]
	v_mfma_f32_16x16x32_bf16 v[76:79], v[148:151], v[218:221], v[76:79]
	v_mfma_f32_16x16x32_bf16 v[68:71], v[156:159], v[218:221], v[68:71]
	v_mfma_f32_16x16x32_bf16 v[120:123], v[152:155], v[198:201], v[120:123]
	v_mfma_f32_16x16x32_bf16 v[116:119], v[160:163], v[198:201], v[116:119]
	v_mfma_f32_16x16x32_bf16 v[108:111], v[152:155], v[206:209], v[108:111]
	v_mfma_f32_16x16x32_bf16 v[100:103], v[160:163], v[206:209], v[100:103]
	v_mfma_f32_16x16x32_bf16 v[92:95], v[152:155], v[214:217], v[92:95]
	v_mfma_f32_16x16x32_bf16 v[84:87], v[160:163], v[214:217], v[84:87]
	v_mfma_f32_16x16x32_bf16 v[76:79], v[152:155], v[222:225], v[76:79]
	v_mfma_f32_16x16x32_bf16 v[68:71], v[160:163], v[222:225], v[68:71]
	s_setprio 0
	s_setprio 1
	v_mfma_f32_16x16x32_bf16 v[124:127], v[174:177], v[194:197], v[124:127]
	v_mfma_f32_16x16x32_bf16 v[112:115], v[182:185], v[194:197], v[112:115]
	v_mfma_f32_16x16x32_bf16 v[104:107], v[174:177], v[202:205], v[104:107]
	v_mfma_f32_16x16x32_bf16 v[96:99], v[182:185], v[202:205], v[96:99]
	v_mfma_f32_16x16x32_bf16 v[88:91], v[174:177], v[210:213], v[88:91]
	v_mfma_f32_16x16x32_bf16 v[80:83], v[182:185], v[210:213], v[80:83]
	v_mfma_f32_16x16x32_bf16 v[72:75], v[174:177], v[218:221], v[72:75]
	v_mfma_f32_16x16x32_bf16 v[64:67], v[182:185], v[218:221], v[64:67]
	v_mfma_f32_16x16x32_bf16 v[124:127], v[178:181], v[198:201], v[124:127]
	v_mfma_f32_16x16x32_bf16 v[112:115], v[186:189], v[198:201], v[112:115]
	v_mfma_f32_16x16x32_bf16 v[104:107], v[178:181], v[206:209], v[104:107]
	v_mfma_f32_16x16x32_bf16 v[96:99], v[186:189], v[206:209], v[96:99]
	v_mfma_f32_16x16x32_bf16 v[88:91], v[178:181], v[214:217], v[88:91]
	v_mfma_f32_16x16x32_bf16 v[80:83], v[186:189], v[214:217], v[80:83]
	v_mfma_f32_16x16x32_bf16 v[72:75], v[178:181], v[222:225], v[72:75]
	v_mfma_f32_16x16x32_bf16 v[64:67], v[186:189], v[222:225], v[64:67]
	s_setprio 0
	s_barrier
; #define PG8_STAGE(bufoff, gbase, voff) do { _Pragma("unroll") for (int _i = 0; _i < 2; ++_i) \
;         __builtin_amdgcn_global_load_lds((const unsigned*)((const char*)(gbase) + (voff)[_i]), (PG8_LAS unsigned*)(lds + (bufoff) + ldsw + _i * 8192), 16, 0, 0); } while (0)
; #define PG8_LDA(dst, b, h) do { _Pragma("unroll") for (int m = 0; m < 4; ++m) _Pragma("unroll") for (int k = 0; k < 2; ++k) dst[m][k] = *(const PG8_LAS bf16x8*)(lds + PG8_SA(b, h) + aoff + m * 2048 + k * 1024); } while (0)
; #define PG8_MMA(ai, bj, At, Bt) do { __builtin_amdgcn_s_setprio(1); _Pragma("unroll") for (int m = 0; m < 4; ++m) _Pragma("unroll") for (int n = 0; n < 2; ++n) _Pragma("unroll") for (int k = 0; k < 2; ++k) \
;         acc[ai][bj][m][n] = __builtin_amdgcn_mfma_f32_16x16x32_bf16(Bt[n][k], At[m][k], acc[ai][bj][m][n], 0, 0, 0); __builtin_amdgcn_s_setprio(0); } while (0)
; #define PG8_WAIT_V(n) asm volatile("s_waitcnt vmcnt(" #n ")" ::: "memory")
; #define PG8_WAIT_L(n) asm volatile("s_waitcnt lgkmcnt(" #n ")" ::: "memory")
; #define PG8_BAR __builtin_amdgcn_s_barrier()
; #define PG8_SCHED __builtin_amdgcn_sched_barrier(0)
; template <class Epi, class Sched, bool ALIGN_EPI = false, bool SP2 = false>
; __device__ __forceinline__ void gemm_phase(PG8_LAS unsigned char* lds, const Gemm g, const Sched& S, const Epi& E) {
;     ...
;     f32x4 acc[2][2][4][2];
; #pragma unroll
;     for (int a = 0; a < 2; ++a)
; #pragma unroll
;         for (int b = 0; b < 2; ++b)
; #pragma unroll
;             for (int m = 0; m < 4; ++m)
; #pragma unroll
;                 for (int n = 0; n < 2; ++n) acc[a][b][m][n] = (f32x4){0.f, 0.f, 0.f, 0.f};
;     ...
;             PG8_WAIT_V(8); PG8_WAIT_L(0); PG8_BAR; PG8_MMA(0, 0, At, B0); PG8_MMA(0, 1, At, B1); PG8_BAR; PG8_SCHED;
;             PG8_LDA(At, 1, 1); PG8_STAGE(PG8_SB(1, 0), b3, voffB); PG8_STAGE(PG8_SB(1, 1), b3 + hstep, voffB); PG8_STAGE(PG8_SA(1, 0), a3, voffA);
;             PG8_WAIT_V(8); PG8_WAIT_L(0); PG8_BAR; PG8_MMA(1, 0, At, B0); PG8_MMA(1, 1, At, B1); PG8_BAR; PG8_SCHED;
	s_add_i32 s42, s72, s3
	v_lshl_add_u64 v[164:165], v[164:165], 0, s[18:19]
	s_mov_b32 m0, s42
	ds_read_b128 v[194:197], v170 offset:49152
	ds_read_b128 v[198:201], v170 offset:50176
	ds_read_b128 v[202:205], v170 offset:51200
	ds_read_b128 v[206:209], v170 offset:52224
	ds_read_b128 v[210:213], v170 offset:53248
	ds_read_b128 v[214:217], v170 offset:54272
	ds_read_b128 v[218:221], v170 offset:55296
	ds_read_b128 v[222:225], v170 offset:56320
	global_load_lds_dwordx4 v[164:165], off
	v_lshl_add_u64 v[164:165], v[190:191], 0, s[18:19]
	s_add_i32 m0, s42, 0x2000
	s_add_i32 s42, s73, s3
	global_load_lds_dwordx4 v[164:165], off
	v_lshl_add_u64 v[164:165], v[226:227], 0, s[18:19]
	s_mov_b32 m0, s42
	s_nop 0
	global_load_lds_dwordx4 v[164:165], off
	v_lshl_add_u64 v[164:165], v[228:229], 0, s[18:19]
	s_add_i32 m0, s42, 0x2000
	s_nop 0
	global_load_lds_dwordx4 v[164:165], off
	v_lshl_add_u64 v[164:165], v[230:231], 0, s[18:19]
	s_mov_b32 m0, s48
	s_nop 0
	global_load_lds_dwordx4 v[164:165], off
	v_lshl_add_u64 v[164:165], v[232:233], 0, s[18:19]
	s_mov_b32 m0, s61
	s_nop 0
	global_load_lds_dwordx4 v[164:165], off
	s_waitcnt vmcnt(8)
	s_waitcnt lgkmcnt(0)
	s_barrier
	s_setprio 1
	s_waitcnt lgkmcnt(0)
	v_mfma_f32_16x16x32_bf16 v[60:63], v[148:151], v[194:197], v[60:63]
	v_mfma_f32_16x16x32_bf16 v[52:55], v[156:159], v[194:197], v[52:55]
	v_mfma_f32_16x16x32_bf16 v[44:47], v[148:151], v[202:205], v[44:47]
	v_mfma_f32_16x16x32_bf16 v[36:39], v[156:159], v[202:205], v[36:39]
	v_mfma_f32_16x16x32_bf16 v[28:31], v[148:151], v[210:213], v[28:31]
	v_mfma_f32_16x16x32_bf16 v[20:23], v[156:159], v[210:213], v[20:23]
	v_mfma_f32_16x16x32_bf16 v[12:15], v[148:151], v[218:221], v[12:15]
	v_mfma_f32_16x16x32_bf16 v[4:7], v[156:159], v[218:221], v[4:7]
	v_mfma_f32_16x16x32_bf16 v[60:63], v[152:155], v[198:201], v[60:63]
	v_mfma_f32_16x16x32_bf16 v[52:55], v[160:163], v[198:201], v[52:55]
	v_mfma_f32_16x16x32_bf16 v[44:47], v[152:155], v[206:209], v[44:47]
	v_mfma_f32_16x16x32_bf16 v[36:39], v[160:163], v[206:209], v[36:39]
	v_mfma_f32_16x16x32_bf16 v[28:31], v[152:155], v[214:217], v[28:31]
	v_mfma_f32_16x16x32_bf16 v[20:23], v[160:163], v[214:217], v[20:23]
	v_mfma_f32_16x16x32_bf16 v[12:15], v[152:155], v[222:225], v[12:15]
	v_mfma_f32_16x16x32_bf16 v[4:7], v[160:163], v[222:225], v[4:7]
	s_setprio 0
	s_setprio 1
	v_mfma_f32_16x16x32_bf16 v[56:59], v[174:177], v[194:197], v[56:59]
	v_mfma_f32_16x16x32_bf16 v[48:51], v[182:185], v[194:197], v[48:51]
	v_mfma_f32_16x16x32_bf16 v[40:43], v[174:177], v[202:205], v[40:43]
	v_mfma_f32_16x16x32_bf16 v[32:35], v[182:185], v[202:205], v[32:35]
	v_mfma_f32_16x16x32_bf16 v[24:27], v[174:177], v[210:213], v[24:27]
	v_mfma_f32_16x16x32_bf16 v[16:19], v[182:185], v[210:213], v[16:19]
	v_mfma_f32_16x16x32_bf16 v[8:11], v[174:177], v[218:221], v[8:11]
	v_mfma_f32_16x16x32_bf16 v[0:3], v[182:185], v[218:221], v[0:3]
	v_mfma_f32_16x16x32_bf16 v[56:59], v[178:181], v[198:201], v[56:59]
	v_mfma_f32_16x16x32_bf16 v[48:51], v[186:189], v[198:201], v[48:51]
	v_mfma_f32_16x16x32_bf16 v[40:43], v[178:181], v[206:209], v[40:43]
	v_mfma_f32_16x16x32_bf16 v[32:35], v[186:189], v[206:209], v[32:35]
	v_mfma_f32_16x16x32_bf16 v[24:27], v[178:181], v[214:217], v[24:27]
	v_mfma_f32_16x16x32_bf16 v[16:19], v[186:189], v[214:217], v[16:19]
	v_mfma_f32_16x16x32_bf16 v[8:11], v[178:181], v[222:225], v[8:11]
	v_mfma_f32_16x16x32_bf16 v[0:3], v[186:189], v[222:225], v[0:3]
	s_setprio 0
	s_barrier
	s_add_u32 s40, s40, 0x100
	s_addc_u32 s41, s41, 0
	s_add_u32 s33, s33, 0x100
	s_addc_u32 s38, s38, 0
	s_cmp_ge_i32 s71, s62
	s_mov_b32 s42, s71
	s_cbranch_scc0 .LBB0_264
	s_branch .Lpx_k264
.Lpz_k264:
	v_mov_b64_e32 v[0:1], 0
	v_mov_b64_e32 v[2:3], 0
	v_mov_b64_e32 v[4:5], 0
	v_mov_b64_e32 v[6:7], 0
	v_mov_b64_e32 v[8:9], 0
	v_mov_b64_e32 v[10:11], 0
	v_mov_b64_e32 v[12:13], 0
	v_mov_b64_e32 v[14:15], 0
	v_mov_b64_e32 v[16:17], 0
	v_mov_b64_e32 v[18:19], 0
	v_mov_b64_e32 v[20:21], 0
	v_mov_b64_e32 v[22:23], 0
	v_mov_b64_e32 v[24:25], 0
	v_mov_b64_e32 v[26:27], 0
	v_mov_b64_e32 v[28:29], 0
	v_mov_b64_e32 v[30:31], 0
	v_mov_b64_e32 v[32:33], 0
	v_mov_b64_e32 v[34:35], 0
	v_mov_b64_e32 v[36:37], 0
	v_mov_b64_e32 v[38:39], 0
	v_mov_b64_e32 v[40:41], 0
	v_mov_b64_e32 v[42:43], 0
	v_mov_b64_e32 v[44:45], 0
	v_mov_b64_e32 v[46:47], 0
	v_mov_b64_e32 v[48:49], 0
	v_mov_b64_e32 v[50:51], 0
	v_mov_b64_e32 v[52:53], 0
	v_mov_b64_e32 v[54:55], 0
	v_mov_b64_e32 v[56:57], 0
	v_mov_b64_e32 v[58:59], 0
	v_mov_b64_e32 v[60:61], 0
	v_mov_b64_e32 v[62:63], 0
	v_mov_b64_e32 v[64:65], 0
	v_mov_b64_e32 v[66:67], 0
	v_mov_b64_e32 v[68:69], 0
	v_mov_b64_e32 v[70:71], 0
	v_mov_b64_e32 v[72:73], 0
	v_mov_b64_e32 v[74:75], 0
	v_mov_b64_e32 v[76:77], 0
	v_mov_b64_e32 v[78:79], 0
	v_mov_b64_e32 v[80:81], 0
	v_mov_b64_e32 v[82:83], 0
	v_mov_b64_e32 v[84:85], 0
	v_mov_b64_e32 v[86:87], 0
	v_mov_b64_e32 v[88:89], 0
	v_mov_b64_e32 v[90:91], 0
	v_mov_b64_e32 v[92:93], 0
	v_mov_b64_e32 v[94:95], 0
	v_mov_b64_e32 v[96:97], 0
	v_mov_b64_e32 v[98:99], 0
	v_mov_b64_e32 v[100:101], 0
	v_mov_b64_e32 v[102:103], 0
	v_mov_b64_e32 v[104:105], 0
	v_mov_b64_e32 v[106:107], 0
	v_mov_b64_e32 v[108:109], 0
	v_mov_b64_e32 v[110:111], 0
	v_mov_b64_e32 v[112:113], 0
	v_mov_b64_e32 v[114:115], 0
	v_mov_b64_e32 v[116:117], 0
	v_mov_b64_e32 v[118:119], 0
	v_mov_b64_e32 v[120:121], 0
	v_mov_b64_e32 v[122:123], 0
	v_mov_b64_e32 v[124:125], 0
	v_mov_b64_e32 v[126:127], 0
	s_branch .LBB0_265

; #define PG8_BAR __builtin_amdgcn_s_barrier()
; template <class Epi, class Sched, bool ALIGN_EPI = false, bool SP2 = false>
; __device__ __forceinline__ void gemm_phase(PG8_LAS unsigned char* lds, const Gemm g, const Sched& S, const Epi& E) {
;     ...
;         if constexpr (ALIGN_EPI) { if (wr == 0) PG8_BAR; }
.Lpx_k264:
.LBB0_265:
	s_and_b64 vcc, exec, s[22:23]
	s_cbranch_vccz .LBB0_267
	s_barrier

;     __host__ __device__ bool next(int i, Unit& u) const { const int idx = first + i; if (idx >= last) return false; u.pm = idx >> 2; u.pn = idx & 3; return true; }
; #define PG8_STAGE(bufoff, gbase, voff) do { _Pragma("unroll") for (int _i = 0; _i < 2; ++_i) \
;         __builtin_amdgcn_global_load_lds((const unsigned*)((const char*)(gbase) + (voff)[_i]), (PG8_LAS unsigned*)(lds + (bufoff) + ldsw + _i * 8192), 16, 0, 0); } while (0)
; #define PG8_LDA(dst, b, h) do { _Pragma("unroll") for (int m = 0; m < 4; ++m) _Pragma("unroll") for (int k = 0; k < 2; ++k) dst[m][k] = *(const PG8_LAS bf16x8*)(lds + PG8_SA(b, h) + aoff + m * 2048 + k * 1024); } while (0)
; #define PG8_LDB(dst, b, h) do { _Pragma("unroll") for (int n = 0; n < 2; ++n) _Pragma("unroll") for (int k = 0; k < 2; ++k) dst[n][k] = *(const PG8_LAS bf16x8*)(lds + PG8_SB(b, h) + boff + n * 2048 + k * 1024); } while (0)
; #define PG8_BAR __builtin_amdgcn_s_barrier()
; template <class Epi, class Sched, bool ALIGN_EPI = false, bool SP2 = false>
; __device__ __forceinline__ void gemm_phase(PG8_LAS unsigned char* lds, const Gemm g, const Sched& S, const Epi& E) {
;     ...
;     f32x4 acc[2][2][4][2];
; #pragma unroll
;     for (int a = 0; a < 2; ++a)
; #pragma unroll
;         for (int b = 0; b < 2; ++b)
; #pragma unroll
;             for (int m = 0; m < 4; ++m)
; #pragma unroll
;                 for (int n = 0; n < 2; ++n) acc[a][b][m][n] = (f32x4){0.f, 0.f, 0.f, 0.f};
;     ...
;     for (;;) {
;         const bool has_next = S.next(ui + 1, nxt);
;         const char* nA = has_next ? (const char*)g.A + (size_t)nxt.pm * tstep : cA; const char* nB = has_next ? (const char*)g.Bt + (size_t)nxt.pn * tstep : cB;
;         asm volatile(".p2align 8");
;         for (int t = 0; t < nt; t += 2) {
;             const bool last = (t == nt - 2);
;             const char* a1 = cA + (size_t)(t + 1) * kstep;
;             const char* a2 = last ? nA : cA + (size_t)(t + 2) * kstep; const char* b2 = last ? nB : cB + (size_t)(t + 2) * kstep;
;             const char* a3 = a2 + kstep; const char* b3 = b2 + kstep;
;             if (last && has_next) S.a_ready(nxt);
;             if constexpr (SP2) {
;             PG8_LDB(B0, 0, 0); PG8_LDB(B1, 0, 1); PG8_SCHED; PG8_LDA(At, 0, 0); PG8_STAGE(PG8_SA(1, 1), a1 + hstep, voffA);
;             PG8_WAIT_V(8); PG8_WAIT_L(0); PG8_BAR; PG8_MMA(0, 0, At, B0); PG8_MMA(0, 1, At, B1); PG8_BAR; PG8_SCHED;
.LBB0_366:
	v_mov_b64_e32 v[64:65], 0
	v_mov_b64_e32 v[66:67], 0
	v_mov_b64_e32 v[68:69], 0
	v_mov_b64_e32 v[70:71], 0
	v_mov_b64_e32 v[72:73], 0
	v_mov_b64_e32 v[74:75], 0
	v_mov_b64_e32 v[76:77], 0
	v_mov_b64_e32 v[78:79], 0
	v_mov_b64_e32 v[80:81], 0
	v_mov_b64_e32 v[82:83], 0
	v_mov_b64_e32 v[84:85], 0
	v_mov_b64_e32 v[86:87], 0
	v_mov_b64_e32 v[88:89], 0
	v_mov_b64_e32 v[90:91], 0
	v_mov_b64_e32 v[92:93], 0
	v_mov_b64_e32 v[94:95], 0
	v_mov_b64_e32 v[96:97], 0
	v_mov_b64_e32 v[98:99], 0
	v_mov_b64_e32 v[100:101], 0
	v_mov_b64_e32 v[102:103], 0
	v_mov_b64_e32 v[104:105], 0
	v_mov_b64_e32 v[106:107], 0
	v_mov_b64_e32 v[108:109], 0
	v_mov_b64_e32 v[110:111], 0
	v_mov_b64_e32 v[112:113], 0
	v_mov_b64_e32 v[114:115], 0
	v_mov_b64_e32 v[116:117], 0
	v_mov_b64_e32 v[118:119], 0
	v_mov_b64_e32 v[120:121], 0
	v_mov_b64_e32 v[122:123], 0
	v_mov_b64_e32 v[124:125], 0
	v_mov_b64_e32 v[126:127], 0
	v_mov_b64_e32 v[144:145], 0
	v_mov_b64_e32 v[146:147], 0
	v_mov_b64_e32 v[148:149], 0
	v_mov_b64_e32 v[150:151], 0
	v_mov_b64_e32 v[154:155], 0
	v_mov_b64_e32 v[156:157], 0
	v_mov_b64_e32 v[158:159], 0
	v_mov_b64_e32 v[160:161], 0
	v_mov_b64_e32 v[164:165], 0
	v_mov_b64_e32 v[166:167], 0
	v_mov_b64_e32 v[168:169], 0
	v_mov_b64_e32 v[170:171], 0
	v_mov_b64_e32 v[172:173], 0
	v_mov_b64_e32 v[174:175], 0
	v_mov_b64_e32 v[176:177], 0
	v_mov_b64_e32 v[178:179], 0
	v_mov_b64_e32 v[184:185], 0
	v_mov_b64_e32 v[186:187], 0
	v_mov_b64_e32 v[188:189], 0
	v_mov_b64_e32 v[190:191], 0
	v_mov_b64_e32 v[194:195], 0
	v_mov_b64_e32 v[196:197], 0
	v_mov_b64_e32 v[198:199], 0
	v_mov_b64_e32 v[200:201], 0
	v_mov_b64_e32 v[208:209], 0
	v_mov_b64_e32 v[212:213], 0
	v_mov_b64_e32 v[214:215], 0
	v_mov_b64_e32 v[216:217], 0
	v_mov_b64_e32 v[222:223], 0
	v_mov_b64_e32 v[224:225], 0
	v_mov_b64_e32 v[226:227], 0
	v_mov_b64_e32 v[228:229], 0
	s_andn2_b64 vcc, exec, s[40:41]
	.p2align 8
	s_cbranch_vccnz .LBB0_370
	s_add_u32 s58, s58, 0x80
	s_addc_u32 s59, s59, 0
	s_add_u32 s4, s60, 0x100
	s_addc_u32 s5, s61, 0
	s_mov_b32 s33, 0
	s_waitcnt lgkmcnt(0)
	s_waitcnt vmcnt(0)
.Lpeel_k368:
	ds_read_b128 v[144:147], v248
	ds_read_b128 v[148:151], v248 offset:1024
	ds_read_b128 v[152:155], v248 offset:2048
	ds_read_b128 v[156:159], v248 offset:3072
	ds_read_b128 v[160:163], v249
	ds_read_b128 v[164:167], v249 offset:1024
	ds_read_b128 v[168:171], v249 offset:2048
	ds_read_b128 v[172:175], v249 offset:3072
	s_add_i32 s38, s33, 2
	s_add_u32 s60, s58, 0x80
	s_addc_u32 s61, s59, 0
	s_cmp_eq_u32 s68, s33
	s_cselect_b32 s61, s11, s61
	s_cselect_b32 s60, s10, s60
	s_cselect_b32 s79, s57, s5
	s_cselect_b32 s78, s56, s4
	v_lshl_add_u64 v[210:211], s[58:59], 0, v[138:139]
	s_add_i32 m0, s39, 0xc000
	ds_read_b128 v[176:179], v250
	ds_read_b128 v[180:183], v250 offset:1024
	ds_read_b128 v[184:187], v250 offset:2048
	ds_read_b128 v[188:191], v250 offset:3072
	ds_read_b128 v[194:197], v250 offset:4096
	ds_read_b128 v[198:201], v250 offset:5120
	ds_read_b128 v[202:205], v250 offset:6144
	ds_read_b128 v[206:209], v250 offset:7168
	global_load_lds_dwordx4 v[210:211], off
	v_lshl_add_u64 v[210:211], s[58:59], 0, v[140:141]
	s_add_i32 m0, s39, 0xe000
	s_nop 0
	global_load_lds_dwordx4 v[210:211], off
	s_waitcnt vmcnt(8)
	s_waitcnt lgkmcnt(0)
	s_barrier
	s_setprio 1
	s_waitcnt lgkmcnt(0)
	v_mfma_f32_16x16x32_bf16 v[124:127], v[144:147], v[176:179], 0
	v_mfma_f32_16x16x32_bf16 v[120:123], v[152:155], v[176:179], 0
	v_mfma_f32_16x16x32_bf16 v[116:119], v[144:147], v[184:187], 0
	v_mfma_f32_16x16x32_bf16 v[112:115], v[152:155], v[184:187], 0
	v_mfma_f32_16x16x32_bf16 v[104:107], v[144:147], v[194:197], 0
	v_mfma_f32_16x16x32_bf16 v[96:99], v[152:155], v[194:197], 0
	v_mfma_f32_16x16x32_bf16 v[88:91], v[144:147], v[202:205], 0
	v_mfma_f32_16x16x32_bf16 v[80:83], v[152:155], v[202:205], 0
	v_mfma_f32_16x16x32_bf16 v[124:127], v[148:151], v[180:183], v[124:127]
	v_mfma_f32_16x16x32_bf16 v[120:123], v[156:159], v[180:183], v[120:123]
	v_mfma_f32_16x16x32_bf16 v[116:119], v[148:151], v[188:191], v[116:119]
	v_mfma_f32_16x16x32_bf16 v[112:115], v[156:159], v[188:191], v[112:115]
	v_mfma_f32_16x16x32_bf16 v[104:107], v[148:151], v[198:201], v[104:107]
	v_mfma_f32_16x16x32_bf16 v[96:99], v[156:159], v[198:201], v[96:99]
	v_mfma_f32_16x16x32_bf16 v[88:91], v[148:151], v[206:209], v[88:91]
	v_mfma_f32_16x16x32_bf16 v[80:83], v[156:159], v[206:209], v[80:83]
	s_setprio 0
	s_setprio 1
	v_mfma_f32_16x16x32_bf16 v[108:111], v[160:163], v[176:179], 0
	v_mfma_f32_16x16x32_bf16 v[100:103], v[168:171], v[176:179], 0
	v_mfma_f32_16x16x32_bf16 v[92:95], v[160:163], v[184:187], 0
	v_mfma_f32_16x16x32_bf16 v[84:87], v[168:171], v[184:187], 0
	v_mfma_f32_16x16x32_bf16 v[76:79], v[160:163], v[194:197], 0
	v_mfma_f32_16x16x32_bf16 v[72:75], v[168:171], v[194:197], 0
	v_mfma_f32_16x16x32_bf16 v[68:71], v[160:163], v[202:205], 0
	v_mfma_f32_16x16x32_bf16 v[64:67], v[168:171], v[202:205], 0
	v_mfma_f32_16x16x32_bf16 v[108:111], v[164:167], v[180:183], v[108:111]
	v_mfma_f32_16x16x32_bf16 v[100:103], v[172:175], v[180:183], v[100:103]
	v_mfma_f32_16x16x32_bf16 v[92:95], v[164:167], v[188:191], v[92:95]
	v_mfma_f32_16x16x32_bf16 v[84:87], v[172:175], v[188:191], v[84:87]
	v_mfma_f32_16x16x32_bf16 v[76:79], v[164:167], v[198:201], v[76:79]
	v_mfma_f32_16x16x32_bf16 v[72:75], v[172:175], v[198:201], v[72:75]
	v_mfma_f32_16x16x32_bf16 v[68:71], v[164:167], v[206:209], v[68:71]
	v_mfma_f32_16x16x32_bf16 v[64:67], v[172:175], v[206:209], v[64:67]
	s_setprio 0
	s_barrier
; #define PG8_STAGE(bufoff, gbase, voff) do { _Pragma("unroll") for (int _i = 0; _i < 2; ++_i) \
;         __builtin_amdgcn_global_load_lds((const unsigned*)((const char*)(gbase) + (voff)[_i]), (PG8_LAS unsigned*)(lds + (bufoff) + ldsw + _i * 8192), 16, 0, 0); } while (0)
; #define PG8_LDA(dst, b, h) do { _Pragma("unroll") for (int m = 0; m < 4; ++m) _Pragma("unroll") for (int k = 0; k < 2; ++k) dst[m][k] = *(const PG8_LAS bf16x8*)(lds + PG8_SA(b, h) + aoff + m * 2048 + k * 1024); } while (0)
; #define PG8_LDB(dst, b, h) do { _Pragma("unroll") for (int n = 0; n < 2; ++n) _Pragma("unroll") for (int k = 0; k < 2; ++k) dst[n][k] = *(const PG8_LAS bf16x8*)(lds + PG8_SB(b, h) + boff + n * 2048 + k * 1024); } while (0)
; #define PG8_MMA(ai, bj, At, Bt) do { __builtin_amdgcn_s_setprio(1); _Pragma("unroll") for (int m = 0; m < 4; ++m) _Pragma("unroll") for (int n = 0; n < 2; ++n) _Pragma("unroll") for (int k = 0; k < 2; ++k) \
;         acc[ai][bj][m][n] = __builtin_amdgcn_mfma_f32_16x16x32_bf16(Bt[n][k], At[m][k], acc[ai][bj][m][n], 0, 0, 0); __builtin_amdgcn_s_setprio(0); } while (0)
; #define PG8_WAIT_V(n) asm volatile("s_waitcnt vmcnt(" #n ")" ::: "memory")
; #define PG8_WAIT_L(n) asm volatile("s_waitcnt lgkmcnt(" #n ")" ::: "memory")
; #define PG8_BAR __builtin_amdgcn_s_barrier()
; #define PG8_SCHED __builtin_amdgcn_sched_barrier(0)
; template <class Epi, class Sched, bool ALIGN_EPI = false, bool SP2 = false>
; __device__ __forceinline__ void gemm_phase(PG8_LAS unsigned char* lds, const Gemm g, const Sched& S, const Epi& E) {
;     ...
;             PG8_LDA(At, 0, 1); PG8_STAGE(PG8_SB(0, 0), b2, voffB); PG8_STAGE(PG8_SB(0, 1), b2 + hstep, voffB); PG8_STAGE(PG8_SA(0, 0), a2, voffA);
;             PG8_WAIT_V(8); PG8_WAIT_L(0); PG8_BAR; PG8_MMA(1, 0, At, B0); PG8_MMA(1, 1, At, B1); PG8_BAR; PG8_SCHED;
;             PG8_LDB(B0, 1, 0); PG8_LDB(B1, 1, 1); PG8_SCHED; PG8_LDA(At, 1, 0); PG8_STAGE(PG8_SA(0, 1), a2 + hstep, voffA);
	s_add_i32 s33, s72, s3
	v_lshl_add_u64 v[210:211], s[78:79], 0, v[132:133]
	s_mov_b32 m0, s33
	ds_read_b128 v[176:179], v250 offset:16384
	ds_read_b128 v[180:183], v250 offset:17408
	ds_read_b128 v[184:187], v250 offset:18432
	ds_read_b128 v[188:191], v250 offset:19456
	ds_read_b128 v[194:197], v250 offset:20480
	ds_read_b128 v[198:201], v250 offset:21504
	ds_read_b128 v[202:205], v250 offset:22528
	ds_read_b128 v[206:209], v250 offset:23552
	global_load_lds_dwordx4 v[210:211], off
	s_add_i32 m0, s33, 0x2000
	v_lshl_add_u64 v[212:213], s[78:79], 0, v[136:137]
	s_add_u32 s78, s78, s16
	s_addc_u32 s79, s79, s17
	s_add_i32 s33, s73, s3
	global_load_lds_dwordx4 v[212:213], off
	v_lshl_add_u64 v[214:215], s[78:79], 0, v[132:133]
	s_mov_b32 m0, s33
	v_lshl_add_u64 v[216:217], s[78:79], 0, v[136:137]
	global_load_lds_dwordx4 v[214:215], off
	s_add_i32 m0, s33, 0x2000
	v_lshl_add_u64 v[218:219], s[60:61], 0, v[130:131]
	global_load_lds_dwordx4 v[216:217], off
	s_mov_b32 m0, s39
	v_lshl_add_u64 v[220:221], s[60:61], 0, v[134:135]
	global_load_lds_dwordx4 v[218:219], off
	s_mov_b32 m0, s49
	s_nop 0
	global_load_lds_dwordx4 v[220:221], off
	s_waitcnt vmcnt(8)
	s_waitcnt lgkmcnt(0)
	s_barrier
	s_setprio 1
	s_waitcnt lgkmcnt(0)
	v_mfma_f32_16x16x32_bf16 v[60:63], v[144:147], v[176:179], 0
	v_mfma_f32_16x16x32_bf16 v[56:59], v[152:155], v[176:179], 0
	v_mfma_f32_16x16x32_bf16 v[52:55], v[144:147], v[184:187], 0
	v_mfma_f32_16x16x32_bf16 v[48:51], v[152:155], v[184:187], 0
	v_mfma_f32_16x16x32_bf16 v[40:43], v[144:147], v[194:197], 0
	v_mfma_f32_16x16x32_bf16 v[32:35], v[152:155], v[194:197], 0
	v_mfma_f32_16x16x32_bf16 v[24:27], v[144:147], v[202:205], 0
	v_mfma_f32_16x16x32_bf16 v[16:19], v[152:155], v[202:205], 0
	v_mfma_f32_16x16x32_bf16 v[60:63], v[148:151], v[180:183], v[60:63]
	v_mfma_f32_16x16x32_bf16 v[56:59], v[156:159], v[180:183], v[56:59]
	v_mfma_f32_16x16x32_bf16 v[52:55], v[148:151], v[188:191], v[52:55]
	v_mfma_f32_16x16x32_bf16 v[48:51], v[156:159], v[188:191], v[48:51]
	v_mfma_f32_16x16x32_bf16 v[40:43], v[148:151], v[198:201], v[40:43]
	v_mfma_f32_16x16x32_bf16 v[32:35], v[156:159], v[198:201], v[32:35]
	v_mfma_f32_16x16x32_bf16 v[24:27], v[148:151], v[206:209], v[24:27]
	v_mfma_f32_16x16x32_bf16 v[16:19], v[156:159], v[206:209], v[16:19]
	s_setprio 0
	s_setprio 1
	v_mfma_f32_16x16x32_bf16 v[44:47], v[160:163], v[176:179], 0
	v_mfma_f32_16x16x32_bf16 v[36:39], v[168:171], v[176:179], 0
	v_mfma_f32_16x16x32_bf16 v[28:31], v[160:163], v[184:187], 0
	v_mfma_f32_16x16x32_bf16 v[20:23], v[168:171], v[184:187], 0
	v_mfma_f32_16x16x32_bf16 v[12:15], v[160:163], v[194:197], 0
	v_mfma_f32_16x16x32_bf16 v[8:11], v[168:171], v[194:197], 0
	v_mfma_f32_16x16x32_bf16 v[4:7], v[160:163], v[202:205], 0
	v_mfma_f32_16x16x32_bf16 v[0:3], v[168:171], v[202:205], 0
	v_mfma_f32_16x16x32_bf16 v[44:47], v[164:167], v[180:183], v[44:47]
	v_mfma_f32_16x16x32_bf16 v[36:39], v[172:175], v[180:183], v[36:39]
	v_mfma_f32_16x16x32_bf16 v[28:31], v[164:167], v[188:191], v[28:31]
	v_mfma_f32_16x16x32_bf16 v[20:23], v[172:175], v[188:191], v[20:23]
	v_mfma_f32_16x16x32_bf16 v[12:15], v[164:167], v[198:201], v[12:15]
	v_mfma_f32_16x16x32_bf16 v[8:11], v[172:175], v[198:201], v[8:11]
	v_mfma_f32_16x16x32_bf16 v[4:7], v[164:167], v[206:209], v[4:7]
	v_mfma_f32_16x16x32_bf16 v[0:3], v[172:175], v[206:209], v[0:3]
	s_setprio 0
	s_barrier
	s_add_i32 s33, 0, 0x18000
	v_add_u32_e32 v128, s33, v193
	s_add_i32 s77, 0, 0x1c000
	ds_read_b128 v[144:147], v128
	ds_read_b128 v[148:151], v128 offset:1024
	ds_read_b128 v[152:155], v128 offset:2048
	ds_read_b128 v[156:159], v128 offset:3072
	v_add_u32_e32 v128, s77, v193
	ds_read_b128 v[160:163], v128
	ds_read_b128 v[164:167], v128 offset:1024
	ds_read_b128 v[168:171], v128 offset:2048
	ds_read_b128 v[172:175], v128 offset:3072
	s_add_u32 s60, s60, s16
	s_addc_u32 s61, s61, s17
	s_mov_b32 m0, s62
	v_lshl_add_u64 v[222:223], s[60:61], 0, v[130:131]
	ds_read_b128 v[176:179], v250 offset:32768
	ds_read_b128 v[180:183], v250 offset:33792
	ds_read_b128 v[184:187], v250 offset:34816
	ds_read_b128 v[188:191], v250 offset:35840
	ds_read_b128 v[194:197], v250 offset:36864
	ds_read_b128 v[198:201], v250 offset:37888
	ds_read_b128 v[202:205], v250 offset:38912
	ds_read_b128 v[206:209], v250 offset:39936
	global_load_lds_dwordx4 v[222:223], off
	v_lshl_add_u64 v[222:223], s[60:61], 0, v[134:135]
	s_mov_b32 m0, s63
	s_nop 0
	global_load_lds_dwordx4 v[222:223], off
	s_waitcnt vmcnt(8)
	s_waitcnt lgkmcnt(0)
	s_barrier
; #define PG8_STAGE(bufoff, gbase, voff) do { _Pragma("unroll") for (int _i = 0; _i < 2; ++_i) \
;         __builtin_amdgcn_global_load_lds((const unsigned*)((const char*)(gbase) + (voff)[_i]), (PG8_LAS unsigned*)(lds + (bufoff) + ldsw + _i * 8192), 16, 0, 0); } while (0)
; #define PG8_LDA(dst, b, h) do { _Pragma("unroll") for (int m = 0; m < 4; ++m) _Pragma("unroll") for (int k = 0; k < 2; ++k) dst[m][k] = *(const PG8_LAS bf16x8*)(lds + PG8_SA(b, h) + aoff + m * 2048 + k * 1024); } while (0)
; #define PG8_MMA(ai, bj, At, Bt) do { __builtin_amdgcn_s_setprio(1); _Pragma("unroll") for (int m = 0; m < 4; ++m) _Pragma("unroll") for (int n = 0; n < 2; ++n) _Pragma("unroll") for (int k = 0; k < 2; ++k) \
;         acc[ai][bj][m][n] = __builtin_amdgcn_mfma_f32_16x16x32_bf16(Bt[n][k], At[m][k], acc[ai][bj][m][n], 0, 0, 0); __builtin_amdgcn_s_setprio(0); } while (0)
; #define PG8_WAIT_V(n) asm volatile("s_waitcnt vmcnt(" #n ")" ::: "memory")
; #define PG8_WAIT_L(n) asm volatile("s_waitcnt lgkmcnt(" #n ")" ::: "memory")
; #define PG8_BAR __builtin_amdgcn_s_barrier()
; #define PG8_SCHED __builtin_amdgcn_sched_barrier(0)
; template <class Epi, class Sched, bool ALIGN_EPI = false, bool SP2 = false>
; __device__ __forceinline__ void gemm_phase(PG8_LAS unsigned char* lds, const Gemm g, const Sched& S, const Epi& E) {
;     ...
;             PG8_WAIT_V(8); PG8_WAIT_L(0); PG8_BAR; PG8_MMA(0, 0, At, B0); PG8_MMA(0, 1, At, B1); PG8_BAR; PG8_SCHED;
;             PG8_LDA(At, 1, 1); PG8_STAGE(PG8_SB(1, 0), b3, voffB); PG8_STAGE(PG8_SB(1, 1), b3 + hstep, voffB); PG8_STAGE(PG8_SA(1, 0), a3, voffA);
;             PG8_WAIT_V(8); PG8_WAIT_L(0); PG8_BAR; PG8_MMA(1, 0, At, B0); PG8_MMA(1, 1, At, B1); PG8_BAR; PG8_SCHED;
	s_setprio 1
	s_waitcnt lgkmcnt(0)
	v_mfma_f32_16x16x32_bf16 v[124:127], v[144:147], v[176:179], v[124:127]
	v_mfma_f32_16x16x32_bf16 v[120:123], v[152:155], v[176:179], v[120:123]
	v_mfma_f32_16x16x32_bf16 v[116:119], v[144:147], v[184:187], v[116:119]
	v_mfma_f32_16x16x32_bf16 v[112:115], v[152:155], v[184:187], v[112:115]
	v_mfma_f32_16x16x32_bf16 v[104:107], v[144:147], v[194:197], v[104:107]
	v_mfma_f32_16x16x32_bf16 v[96:99], v[152:155], v[194:197], v[96:99]
	v_mfma_f32_16x16x32_bf16 v[88:91], v[144:147], v[202:205], v[88:91]
	v_mfma_f32_16x16x32_bf16 v[80:83], v[152:155], v[202:205], v[80:83]
	v_mfma_f32_16x16x32_bf16 v[124:127], v[148:151], v[180:183], v[124:127]
	v_mfma_f32_16x16x32_bf16 v[120:123], v[156:159], v[180:183], v[120:123]
	v_mfma_f32_16x16x32_bf16 v[116:119], v[148:151], v[188:191], v[116:119]
	v_mfma_f32_16x16x32_bf16 v[112:115], v[156:159], v[188:191], v[112:115]
	v_mfma_f32_16x16x32_bf16 v[104:107], v[148:151], v[198:201], v[104:107]
	v_mfma_f32_16x16x32_bf16 v[96:99], v[156:159], v[198:201], v[96:99]
	v_mfma_f32_16x16x32_bf16 v[88:91], v[148:151], v[206:209], v[88:91]
	v_mfma_f32_16x16x32_bf16 v[80:83], v[156:159], v[206:209], v[80:83]
	s_setprio 0
	s_setprio 1
	v_mfma_f32_16x16x32_bf16 v[108:111], v[160:163], v[176:179], v[108:111]
	v_mfma_f32_16x16x32_bf16 v[100:103], v[168:171], v[176:179], v[100:103]
	v_mfma_f32_16x16x32_bf16 v[92:95], v[160:163], v[184:187], v[92:95]
	v_mfma_f32_16x16x32_bf16 v[84:87], v[168:171], v[184:187], v[84:87]
	v_mfma_f32_16x16x32_bf16 v[76:79], v[160:163], v[194:197], v[76:79]
	v_mfma_f32_16x16x32_bf16 v[72:75], v[168:171], v[194:197], v[72:75]
	v_mfma_f32_16x16x32_bf16 v[68:71], v[160:163], v[202:205], v[68:71]
	v_mfma_f32_16x16x32_bf16 v[64:67], v[168:171], v[202:205], v[64:67]
	v_mfma_f32_16x16x32_bf16 v[108:111], v[164:167], v[180:183], v[108:111]
	v_mfma_f32_16x16x32_bf16 v[100:103], v[172:175], v[180:183], v[100:103]
	v_mfma_f32_16x16x32_bf16 v[92:95], v[164:167], v[188:191], v[92:95]
	v_mfma_f32_16x16x32_bf16 v[84:87], v[172:175], v[188:191], v[84:87]
	v_mfma_f32_16x16x32_bf16 v[76:79], v[164:167], v[198:201], v[76:79]
	v_mfma_f32_16x16x32_bf16 v[72:75], v[172:175], v[198:201], v[72:75]
	v_mfma_f32_16x16x32_bf16 v[68:71], v[164:167], v[206:209], v[68:71]
	v_mfma_f32_16x16x32_bf16 v[64:67], v[172:175], v[206:209], v[64:67]
	s_setprio 0
	s_barrier
	s_add_i32 s33, s33, s3
	v_lshl_add_u64 v[210:211], v[210:211], 0, s[36:37]
	s_mov_b32 m0, s33
	ds_read_b128 v[176:179], v250 offset:49152
	ds_read_b128 v[180:183], v250 offset:50176
	ds_read_b128 v[184:187], v250 offset:51200
	ds_read_b128 v[188:191], v250 offset:52224
	ds_read_b128 v[194:197], v250 offset:53248
	ds_read_b128 v[198:201], v250 offset:54272
	ds_read_b128 v[202:205], v250 offset:55296
	ds_read_b128 v[206:209], v250 offset:56320
	global_load_lds_dwordx4 v[210:211], off
	v_lshl_add_u64 v[210:211], v[212:213], 0, s[36:37]
	s_add_i32 m0, s33, 0x2000
	s_add_i32 s33, s77, s3
	global_load_lds_dwordx4 v[210:211], off
	v_lshl_add_u64 v[210:211], v[214:215], 0, s[36:37]
	s_mov_b32 m0, s33
	s_nop 0
	global_load_lds_dwordx4 v[210:211], off
	v_lshl_add_u64 v[210:211], v[216:217], 0, s[36:37]
	s_add_i32 m0, s33, 0x2000
	s_nop 0
	global_load_lds_dwordx4 v[210:211], off
	v_lshl_add_u64 v[210:211], v[218:219], 0, s[36:37]
	s_mov_b32 m0, s64
	s_nop 0
	global_load_lds_dwordx4 v[210:211], off
	v_lshl_add_u64 v[210:211], v[220:221], 0, s[36:37]
	s_mov_b32 m0, s65
	s_nop 0
	global_load_lds_dwordx4 v[210:211], off
	s_waitcnt vmcnt(8)
	s_waitcnt lgkmcnt(0)
	s_barrier
	s_setprio 1
	s_waitcnt lgkmcnt(0)
	v_mfma_f32_16x16x32_bf16 v[60:63], v[144:147], v[176:179], v[60:63]
	v_mfma_f32_16x16x32_bf16 v[56:59], v[152:155], v[176:179], v[56:59]
	v_mfma_f32_16x16x32_bf16 v[52:55], v[144:147], v[184:187], v[52:55]
	v_mfma_f32_16x16x32_bf16 v[48:51], v[152:155], v[184:187], v[48:51]
	v_mfma_f32_16x16x32_bf16 v[40:43], v[144:147], v[194:197], v[40:43]
	v_mfma_f32_16x16x32_bf16 v[32:35], v[152:155], v[194:197], v[32:35]
	v_mfma_f32_16x16x32_bf16 v[24:27], v[144:147], v[202:205], v[24:27]
	v_mfma_f32_16x16x32_bf16 v[16:19], v[152:155], v[202:205], v[16:19]
	v_mfma_f32_16x16x32_bf16 v[60:63], v[148:151], v[180:183], v[60:63]
	v_mfma_f32_16x16x32_bf16 v[56:59], v[156:159], v[180:183], v[56:59]
	v_mfma_f32_16x16x32_bf16 v[52:55], v[148:151], v[188:191], v[52:55]
	v_mfma_f32_16x16x32_bf16 v[48:51], v[156:159], v[188:191], v[48:51]
	v_mfma_f32_16x16x32_bf16 v[40:43], v[148:151], v[198:201], v[40:43]
	v_mfma_f32_16x16x32_bf16 v[32:35], v[156:159], v[198:201], v[32:35]
	v_mfma_f32_16x16x32_bf16 v[24:27], v[148:151], v[206:209], v[24:27]
	v_mfma_f32_16x16x32_bf16 v[16:19], v[156:159], v[206:209], v[16:19]
	s_setprio 0
	s_setprio 1
	v_mfma_f32_16x16x32_bf16 v[44:47], v[160:163], v[176:179], v[44:47]
	v_mfma_f32_16x16x32_bf16 v[36:39], v[168:171], v[176:179], v[36:39]
	v_mfma_f32_16x16x32_bf16 v[28:31], v[160:163], v[184:187], v[28:31]
	v_mfma_f32_16x16x32_bf16 v[20:23], v[168:171], v[184:187], v[20:23]
	v_mfma_f32_16x16x32_bf16 v[12:15], v[160:163], v[194:197], v[12:15]
	v_mfma_f32_16x16x32_bf16 v[8:11], v[168:171], v[194:197], v[8:11]
	v_mfma_f32_16x16x32_bf16 v[4:7], v[160:163], v[202:205], v[4:7]
	v_mfma_f32_16x16x32_bf16 v[0:3], v[168:171], v[202:205], v[0:3]
	v_mfma_f32_16x16x32_bf16 v[44:47], v[164:167], v[180:183], v[44:47]
	v_mfma_f32_16x16x32_bf16 v[36:39], v[172:175], v[180:183], v[36:39]
	v_mfma_f32_16x16x32_bf16 v[28:31], v[164:167], v[188:191], v[28:31]
	v_mfma_f32_16x16x32_bf16 v[20:23], v[172:175], v[188:191], v[20:23]
	v_mfma_f32_16x16x32_bf16 v[12:15], v[164:167], v[198:201], v[12:15]
	v_mfma_f32_16x16x32_bf16 v[8:11], v[172:175], v[198:201], v[8:11]
	v_mfma_f32_16x16x32_bf16 v[4:7], v[164:167], v[206:209], v[4:7]
	v_mfma_f32_16x16x32_bf16 v[0:3], v[172:175], v[206:209], v[0:3]
	s_setprio 0
	s_barrier
	s_add_u32 s58, s58, 0x100
	s_addc_u32 s59, s59, 0
	s_add_u32 s4, s4, 0x100
	s_addc_u32 s5, s5, 0
	s_cmp_ge_i32 s38, s67
	s_mov_b32 s33, s38
	s_cbranch_scc0 .LBB0_368
	s_branch .Lpx_k368

;     __device__ __forceinline__ void operator()(const f32x4 (&acc)[2][2][4][2], const Unit& u, int wr, int wc, int fr, int fq) const {
;     ...
;                     v0 += acc[ai][bj][m][0] * alpha; v1 += acc[ai][bj][m][1] * alpha;
.Lpx_k368:
	v_pk_mul_f32 v[222:223], v[126:127], 0.5 op_sel_hi:[1,0]
	v_pk_mul_f32 v[224:225], v[124:125], 0.5 op_sel_hi:[1,0]
	v_pk_mul_f32 v[226:227], v[122:123], 0.5 op_sel_hi:[1,0]
	v_pk_mul_f32 v[228:229], v[120:121], 0.5 op_sel_hi:[1,0]
	v_pk_mul_f32 v[216:217], v[110:111], 0.5 op_sel_hi:[1,0]
	v_pk_mul_f32 v[214:215], v[108:109], 0.5 op_sel_hi:[1,0]
	v_pk_mul_f32 v[212:213], v[102:103], 0.5 op_sel_hi:[1,0]
	v_pk_mul_f32 v[208:209], v[100:101], 0.5 op_sel_hi:[1,0]
	v_pk_mul_f32 v[200:201], v[118:119], 0.5 op_sel_hi:[1,0]
	v_pk_mul_f32 v[198:199], v[116:117], 0.5 op_sel_hi:[1,0]
	v_pk_mul_f32 v[196:197], v[114:115], 0.5 op_sel_hi:[1,0]
	v_pk_mul_f32 v[194:195], v[112:113], 0.5 op_sel_hi:[1,0]
	v_pk_mul_f32 v[190:191], v[94:95], 0.5 op_sel_hi:[1,0]
	v_pk_mul_f32 v[188:189], v[92:93], 0.5 op_sel_hi:[1,0]
	v_pk_mul_f32 v[186:187], v[86:87], 0.5 op_sel_hi:[1,0]
	v_pk_mul_f32 v[184:185], v[84:85], 0.5 op_sel_hi:[1,0]
	v_pk_mul_f32 v[178:179], v[106:107], 0.5 op_sel_hi:[1,0]
	v_pk_mul_f32 v[176:177], v[104:105], 0.5 op_sel_hi:[1,0]
	v_pk_mul_f32 v[174:175], v[98:99], 0.5 op_sel_hi:[1,0]
	v_pk_mul_f32 v[172:173], v[96:97], 0.5 op_sel_hi:[1,0]
	v_pk_mul_f32 v[170:171], v[78:79], 0.5 op_sel_hi:[1,0]
	v_pk_mul_f32 v[168:169], v[76:77], 0.5 op_sel_hi:[1,0]
	v_pk_mul_f32 v[166:167], v[74:75], 0.5 op_sel_hi:[1,0]
	v_pk_mul_f32 v[164:165], v[72:73], 0.5 op_sel_hi:[1,0]
	v_pk_mul_f32 v[160:161], v[90:91], 0.5 op_sel_hi:[1,0]
	v_pk_mul_f32 v[158:159], v[88:89], 0.5 op_sel_hi:[1,0]
	v_pk_mul_f32 v[156:157], v[82:83], 0.5 op_sel_hi:[1,0]
	v_pk_mul_f32 v[154:155], v[80:81], 0.5 op_sel_hi:[1,0]
	v_pk_mul_f32 v[150:151], v[70:71], 0.5 op_sel_hi:[1,0]
	v_pk_mul_f32 v[148:149], v[68:69], 0.5 op_sel_hi:[1,0]
	v_pk_mul_f32 v[146:147], v[66:67], 0.5 op_sel_hi:[1,0]
	v_pk_mul_f32 v[144:145], v[64:65], 0.5 op_sel_hi:[1,0]
	v_pk_mul_f32 v[126:127], v[62:63], 0.5 op_sel_hi:[1,0]
	v_pk_mul_f32 v[124:125], v[60:61], 0.5 op_sel_hi:[1,0]
	v_pk_mul_f32 v[122:123], v[58:59], 0.5 op_sel_hi:[1,0]
	v_pk_mul_f32 v[120:121], v[56:57], 0.5 op_sel_hi:[1,0]
	v_pk_mul_f32 v[118:119], v[46:47], 0.5 op_sel_hi:[1,0]
	v_pk_mul_f32 v[116:117], v[44:45], 0.5 op_sel_hi:[1,0]
	v_pk_mul_f32 v[114:115], v[38:39], 0.5 op_sel_hi:[1,0]
	v_pk_mul_f32 v[112:113], v[36:37], 0.5 op_sel_hi:[1,0]
	v_pk_mul_f32 v[110:111], v[54:55], 0.5 op_sel_hi:[1,0]
	v_pk_mul_f32 v[108:109], v[52:53], 0.5 op_sel_hi:[1,0]
	v_pk_mul_f32 v[106:107], v[50:51], 0.5 op_sel_hi:[1,0]
	v_pk_mul_f32 v[104:105], v[48:49], 0.5 op_sel_hi:[1,0]
	v_pk_mul_f32 v[102:103], v[30:31], 0.5 op_sel_hi:[1,0]
	v_pk_mul_f32 v[100:101], v[28:29], 0.5 op_sel_hi:[1,0]
	v_pk_mul_f32 v[98:99], v[22:23], 0.5 op_sel_hi:[1,0]
	v_pk_mul_f32 v[96:97], v[20:21], 0.5 op_sel_hi:[1,0]
	v_pk_mul_f32 v[94:95], v[42:43], 0.5 op_sel_hi:[1,0]
	v_pk_mul_f32 v[92:93], v[40:41], 0.5 op_sel_hi:[1,0]
	v_pk_mul_f32 v[90:91], v[34:35], 0.5 op_sel_hi:[1,0]
	v_pk_mul_f32 v[88:89], v[32:33], 0.5 op_sel_hi:[1,0]
	v_pk_mul_f32 v[86:87], v[14:15], 0.5 op_sel_hi:[1,0]
	v_pk_mul_f32 v[84:85], v[12:13], 0.5 op_sel_hi:[1,0]
	v_pk_mul_f32 v[82:83], v[10:11], 0.5 op_sel_hi:[1,0]
	v_pk_mul_f32 v[80:81], v[8:9], 0.5 op_sel_hi:[1,0]
	v_pk_mul_f32 v[78:79], v[26:27], 0.5 op_sel_hi:[1,0]
	v_pk_mul_f32 v[76:77], v[24:25], 0.5 op_sel_hi:[1,0]
	v_pk_mul_f32 v[74:75], v[18:19], 0.5 op_sel_hi:[1,0]
	v_pk_mul_f32 v[72:73], v[16:17], 0.5 op_sel_hi:[1,0]
	v_pk_mul_f32 v[70:71], v[6:7], 0.5 op_sel_hi:[1,0]
	v_pk_mul_f32 v[68:69], v[4:5], 0.5 op_sel_hi:[1,0]
	v_pk_mul_f32 v[66:67], v[2:3], 0.5 op_sel_hi:[1,0]
	v_pk_mul_f32 v[64:65], v[0:1], 0.5 op_sel_hi:[1,0]

;     __host__ __device__ bool next(int i, Unit& u) const { const int idx = first + i; if (idx >= last) return false; u.pm = idx >> 2; u.pn = idx & 3; return true; }
; #define PG8_STAGE(bufoff, gbase, voff) do { _Pragma("unroll") for (int _i = 0; _i < 2; ++_i) \
;         __builtin_amdgcn_global_load_lds((const unsigned*)((const char*)(gbase) + (voff)[_i]), (PG8_LAS unsigned*)(lds + (bufoff) + ldsw + _i * 8192), 16, 0, 0); } while (0)
; #define PG8_LDA(dst, b, h) do { _Pragma("unroll") for (int m = 0; m < 4; ++m) _Pragma("unroll") for (int k = 0; k < 2; ++k) dst[m][k] = *(const PG8_LAS bf16x8*)(lds + PG8_SA(b, h) + aoff + m * 2048 + k * 1024); } while (0)
; #define PG8_LDB(dst, b, h) do { _Pragma("unroll") for (int n = 0; n < 2; ++n) _Pragma("unroll") for (int k = 0; k < 2; ++k) dst[n][k] = *(const PG8_LAS bf16x8*)(lds + PG8_SB(b, h) + boff + n * 2048 + k * 1024); } while (0)
; #define PG8_WAIT_V(n) asm volatile("s_waitcnt vmcnt(" #n ")" ::: "memory")
; #define PG8_WAIT_L(n) asm volatile("s_waitcnt lgkmcnt(" #n ")" ::: "memory")
; #define PG8_BAR __builtin_amdgcn_s_barrier()
; template <class Epi, class Sched, bool ALIGN_EPI = false, bool SP2 = false>
; __device__ __forceinline__ void gemm_phase(PG8_LAS unsigned char* lds, const Gemm g, const Sched& S, const Epi& E) {
;     ...
;     for (;;) {
;         const bool has_next = S.next(ui + 1, nxt);
;         const char* nA = has_next ? (const char*)g.A + (size_t)nxt.pm * tstep : cA; const char* nB = has_next ? (const char*)g.Bt + (size_t)nxt.pn * tstep : cB;
;         asm volatile(".p2align 8");
;         for (int t = 0; t < nt; t += 2) {
;             const bool last = (t == nt - 2);
;             const char* a1 = cA + (size_t)(t + 1) * kstep;
;             const char* a2 = last ? nA : cA + (size_t)(t + 2) * kstep; const char* b2 = last ? nB : cB + (size_t)(t + 2) * kstep;
;             const char* a3 = a2 + kstep; const char* b3 = b2 + kstep;
;             if (last && has_next) S.a_ready(nxt);
;             if constexpr (SP2) {
;             PG8_LDB(B0, 0, 0); PG8_LDB(B1, 0, 1); PG8_SCHED; PG8_LDA(At, 0, 0); PG8_STAGE(PG8_SA(1, 1), a1 + hstep, voffA);
;             PG8_WAIT_V(8); PG8_WAIT_L(0); PG8_BAR; PG8_MMA(0, 0, At, B0); PG8_MMA(0, 1, At, B1); PG8_BAR; PG8_SCHED;
;             PG8_LDA(At, 0, 1); PG8_STAGE(PG8_SB(0, 0), b2, voffB); PG8_STAGE(PG8_SB(0, 1), b2 + hstep, voffB); PG8_STAGE(PG8_SA(0, 0), a2, voffA);
.LBB0_471:
	s_andn2_b64 vcc, exec, s[56:57]
	s_waitcnt vmcnt(0)
	s_waitcnt lgkmcnt(0)
	.p2align 8
	s_cbranch_vccnz .Lpz_k473
	s_add_u32 s10, s14, 0x80
	s_addc_u32 s11, s15, 0
	s_add_u32 s5, s12, 0x100
	s_addc_u32 s14, s13, 0
	s_mov_b32 s12, 0
.Lpeel_k473:
	ds_read_b128 v[150:153], v190
	ds_read_b128 v[154:157], v190 offset:1024
	ds_read_b128 v[158:161], v190 offset:2048
	ds_read_b128 v[162:165], v190 offset:3072
	ds_read_b128 v[166:169], v191
	ds_read_b128 v[170:173], v191 offset:1024
	ds_read_b128 v[174:177], v191 offset:2048
	ds_read_b128 v[178:181], v191 offset:3072
	s_add_i32 s15, s12, 2
	s_add_u32 s33, s10, 0x80
	s_addc_u32 s13, s11, 0
	s_cmp_eq_u32 s73, s12
	s_cselect_b32 s12, s60, s33
	s_cselect_b32 s13, s61, s13
	s_cselect_b32 s65, s63, s14
	s_cselect_b32 s64, s62, s5
	v_lshl_add_u64 v[186:187], s[10:11], 0, v[142:143]
	s_add_i32 m0, s66, 0xc000
	ds_read_b128 v[182:185], v193
	ds_read_b128 v[196:199], v193 offset:1024
	ds_read_b128 v[200:203], v193 offset:2048
	ds_read_b128 v[204:207], v193 offset:3072
	ds_read_b128 v[208:211], v193 offset:4096
	ds_read_b128 v[212:215], v193 offset:5120
	ds_read_b128 v[216:219], v193 offset:6144
	ds_read_b128 v[220:223], v193 offset:7168
	global_load_lds_dwordx4 v[186:187], off
	v_lshl_add_u64 v[186:187], s[10:11], 0, v[144:145]
	s_add_i32 m0, s66, 0xe000
	s_nop 0
	global_load_lds_dwordx4 v[186:187], off
	s_waitcnt vmcnt(8)
	s_waitcnt lgkmcnt(0)
	s_barrier
	s_setprio 1
	s_waitcnt lgkmcnt(0)
	v_mfma_f32_16x16x32_bf16 v[124:127], v[150:153], v[182:185], 0
	v_mfma_f32_16x16x32_bf16 v[120:123], v[158:161], v[182:185], 0
	v_mfma_f32_16x16x32_bf16 v[108:111], v[150:153], v[200:203], 0
	v_mfma_f32_16x16x32_bf16 v[104:107], v[158:161], v[200:203], 0
	v_mfma_f32_16x16x32_bf16 v[92:95], v[150:153], v[208:211], 0
	v_mfma_f32_16x16x32_bf16 v[88:91], v[158:161], v[208:211], 0
	v_mfma_f32_16x16x32_bf16 v[76:79], v[150:153], v[216:219], 0
	v_mfma_f32_16x16x32_bf16 v[72:75], v[158:161], v[216:219], 0
	v_mfma_f32_16x16x32_bf16 v[124:127], v[154:157], v[196:199], v[124:127]
	v_mfma_f32_16x16x32_bf16 v[120:123], v[162:165], v[196:199], v[120:123]
	v_mfma_f32_16x16x32_bf16 v[108:111], v[154:157], v[204:207], v[108:111]
	v_mfma_f32_16x16x32_bf16 v[104:107], v[162:165], v[204:207], v[104:107]
	v_mfma_f32_16x16x32_bf16 v[92:95], v[154:157], v[212:215], v[92:95]
	v_mfma_f32_16x16x32_bf16 v[88:91], v[162:165], v[212:215], v[88:91]
	v_mfma_f32_16x16x32_bf16 v[76:79], v[154:157], v[220:223], v[76:79]
	v_mfma_f32_16x16x32_bf16 v[72:75], v[162:165], v[220:223], v[72:75]
	s_setprio 0
	s_setprio 1
	v_mfma_f32_16x16x32_bf16 v[116:119], v[166:169], v[182:185], 0
	v_mfma_f32_16x16x32_bf16 v[112:115], v[174:177], v[182:185], 0
	v_mfma_f32_16x16x32_bf16 v[100:103], v[166:169], v[200:203], 0
	v_mfma_f32_16x16x32_bf16 v[96:99], v[174:177], v[200:203], 0
	v_mfma_f32_16x16x32_bf16 v[84:87], v[166:169], v[208:211], 0
	v_mfma_f32_16x16x32_bf16 v[80:83], v[174:177], v[208:211], 0
	v_mfma_f32_16x16x32_bf16 v[68:71], v[166:169], v[216:219], 0
	v_mfma_f32_16x16x32_bf16 v[64:67], v[174:177], v[216:219], 0
	v_mfma_f32_16x16x32_bf16 v[116:119], v[170:173], v[196:199], v[116:119]
	v_mfma_f32_16x16x32_bf16 v[112:115], v[178:181], v[196:199], v[112:115]
	v_mfma_f32_16x16x32_bf16 v[100:103], v[170:173], v[204:207], v[100:103]
	v_mfma_f32_16x16x32_bf16 v[96:99], v[178:181], v[204:207], v[96:99]
	v_mfma_f32_16x16x32_bf16 v[84:87], v[170:173], v[212:215], v[84:87]
	v_mfma_f32_16x16x32_bf16 v[80:83], v[178:181], v[212:215], v[80:83]
	v_mfma_f32_16x16x32_bf16 v[68:71], v[170:173], v[220:223], v[68:71]
	v_mfma_f32_16x16x32_bf16 v[64:67], v[178:181], v[220:223], v[64:67]
	s_setprio 0
	s_barrier
	s_add_i32 s33, s78, s49
	v_lshl_add_u64 v[186:187], s[64:65], 0, v[132:133]
	s_mov_b32 m0, s33
	ds_read_b128 v[182:185], v193 offset:16384
	ds_read_b128 v[196:199], v193 offset:17408
	ds_read_b128 v[200:203], v193 offset:18432
	ds_read_b128 v[204:207], v193 offset:19456
	ds_read_b128 v[208:211], v193 offset:20480
	ds_read_b128 v[212:215], v193 offset:21504
	ds_read_b128 v[216:219], v193 offset:22528
	ds_read_b128 v[220:223], v193 offset:23552
	global_load_lds_dwordx4 v[186:187], off
	s_add_i32 m0, s33, 0x2000
	v_lshl_add_u64 v[224:225], s[64:65], 0, v[136:137]
	s_add_u32 s64, s64, s18
	s_addc_u32 s65, s65, s19
	s_add_i32 s33, s79, s49
	global_load_lds_dwordx4 v[224:225], off
	v_lshl_add_u64 v[226:227], s[64:65], 0, v[132:133]
	s_mov_b32 m0, s33
	v_lshl_add_u64 v[228:229], s[64:65], 0, v[136:137]
	global_load_lds_dwordx4 v[226:227], off
	s_add_i32 m0, s33, 0x2000
	v_lshl_add_u64 v[230:231], s[12:13], 0, v[130:131]
	global_load_lds_dwordx4 v[228:229], off
	s_mov_b32 m0, s66
	v_lshl_add_u64 v[232:233], s[12:13], 0, v[134:135]
	global_load_lds_dwordx4 v[230:231], off
	s_mov_b32 m0, s67
	s_nop 0
	global_load_lds_dwordx4 v[232:233], off
	s_waitcnt vmcnt(8)
	s_waitcnt lgkmcnt(0)
	s_barrier
; #define PG8_STAGE(bufoff, gbase, voff) do { _Pragma("unroll") for (int _i = 0; _i < 2; ++_i) \
;         __builtin_amdgcn_global_load_lds((const unsigned*)((const char*)(gbase) + (voff)[_i]), (PG8_LAS unsigned*)(lds + (bufoff) + ldsw + _i * 8192), 16, 0, 0); } while (0)
; #define PG8_LDA(dst, b, h) do { _Pragma("unroll") for (int m = 0; m < 4; ++m) _Pragma("unroll") for (int k = 0; k < 2; ++k) dst[m][k] = *(const PG8_LAS bf16x8*)(lds + PG8_SA(b, h) + aoff + m * 2048 + k * 1024); } while (0)
; #define PG8_LDB(dst, b, h) do { _Pragma("unroll") for (int n = 0; n < 2; ++n) _Pragma("unroll") for (int k = 0; k < 2; ++k) dst[n][k] = *(const PG8_LAS bf16x8*)(lds + PG8_SB(b, h) + boff + n * 2048 + k * 1024); } while (0)
; #define PG8_MMA(ai, bj, At, Bt) do { __builtin_amdgcn_s_setprio(1); _Pragma("unroll") for (int m = 0; m < 4; ++m) _Pragma("unroll") for (int n = 0; n < 2; ++n) _Pragma("unroll") for (int k = 0; k < 2; ++k) \
;         acc[ai][bj][m][n] = __builtin_amdgcn_mfma_f32_16x16x32_bf16(Bt[n][k], At[m][k], acc[ai][bj][m][n], 0, 0, 0); __builtin_amdgcn_s_setprio(0); } while (0)
; #define PG8_WAIT_V(n) asm volatile("s_waitcnt vmcnt(" #n ")" ::: "memory")
; #define PG8_WAIT_L(n) asm volatile("s_waitcnt lgkmcnt(" #n ")" ::: "memory")
; #define PG8_BAR __builtin_amdgcn_s_barrier()
; #define PG8_SCHED __builtin_amdgcn_sched_barrier(0)
; template <class Epi, class Sched, bool ALIGN_EPI = false, bool SP2 = false>
; __device__ __forceinline__ void gemm_phase(PG8_LAS unsigned char* lds, const Gemm g, const Sched& S, const Epi& E) {
;     ...
;             PG8_WAIT_V(8); PG8_WAIT_L(0); PG8_BAR; PG8_MMA(1, 0, At, B0); PG8_MMA(1, 1, At, B1); PG8_BAR; PG8_SCHED;
;             PG8_LDB(B0, 1, 0); PG8_LDB(B1, 1, 1); PG8_SCHED; PG8_LDA(At, 1, 0); PG8_STAGE(PG8_SA(0, 1), a2 + hstep, voffA);
;             PG8_WAIT_V(8); PG8_WAIT_L(0); PG8_BAR; PG8_MMA(0, 0, At, B0); PG8_MMA(0, 1, At, B1); PG8_BAR; PG8_SCHED;
	s_setprio 1
	s_waitcnt lgkmcnt(0)
	v_mfma_f32_16x16x32_bf16 v[60:63], v[150:153], v[182:185], 0
	v_mfma_f32_16x16x32_bf16 v[56:59], v[158:161], v[182:185], 0
	v_mfma_f32_16x16x32_bf16 v[44:47], v[150:153], v[200:203], 0
	v_mfma_f32_16x16x32_bf16 v[40:43], v[158:161], v[200:203], 0
	v_mfma_f32_16x16x32_bf16 v[28:31], v[150:153], v[208:211], 0
	v_mfma_f32_16x16x32_bf16 v[24:27], v[158:161], v[208:211], 0
	v_mfma_f32_16x16x32_bf16 v[12:15], v[150:153], v[216:219], 0
	v_mfma_f32_16x16x32_bf16 v[8:11], v[158:161], v[216:219], 0
	v_mfma_f32_16x16x32_bf16 v[60:63], v[154:157], v[196:199], v[60:63]
	v_mfma_f32_16x16x32_bf16 v[56:59], v[162:165], v[196:199], v[56:59]
	v_mfma_f32_16x16x32_bf16 v[44:47], v[154:157], v[204:207], v[44:47]
	v_mfma_f32_16x16x32_bf16 v[40:43], v[162:165], v[204:207], v[40:43]
	v_mfma_f32_16x16x32_bf16 v[28:31], v[154:157], v[212:215], v[28:31]
	v_mfma_f32_16x16x32_bf16 v[24:27], v[162:165], v[212:215], v[24:27]
	v_mfma_f32_16x16x32_bf16 v[12:15], v[154:157], v[220:223], v[12:15]
	v_mfma_f32_16x16x32_bf16 v[8:11], v[162:165], v[220:223], v[8:11]
	s_setprio 0
	s_setprio 1
	v_mfma_f32_16x16x32_bf16 v[52:55], v[166:169], v[182:185], 0
	v_mfma_f32_16x16x32_bf16 v[48:51], v[174:177], v[182:185], 0
	v_mfma_f32_16x16x32_bf16 v[36:39], v[166:169], v[200:203], 0
	v_mfma_f32_16x16x32_bf16 v[32:35], v[174:177], v[200:203], 0
	v_mfma_f32_16x16x32_bf16 v[20:23], v[166:169], v[208:211], 0
	v_mfma_f32_16x16x32_bf16 v[16:19], v[174:177], v[208:211], 0
	v_mfma_f32_16x16x32_bf16 v[4:7], v[166:169], v[216:219], 0
	v_mfma_f32_16x16x32_bf16 v[0:3], v[174:177], v[216:219], 0
	v_mfma_f32_16x16x32_bf16 v[52:55], v[170:173], v[196:199], v[52:55]
	v_mfma_f32_16x16x32_bf16 v[48:51], v[178:181], v[196:199], v[48:51]
	v_mfma_f32_16x16x32_bf16 v[36:39], v[170:173], v[204:207], v[36:39]
	v_mfma_f32_16x16x32_bf16 v[32:35], v[178:181], v[204:207], v[32:35]
	v_mfma_f32_16x16x32_bf16 v[20:23], v[170:173], v[212:215], v[20:23]
	v_mfma_f32_16x16x32_bf16 v[16:19], v[178:181], v[212:215], v[16:19]
	v_mfma_f32_16x16x32_bf16 v[4:7], v[170:173], v[220:223], v[4:7]
	v_mfma_f32_16x16x32_bf16 v[0:3], v[178:181], v[220:223], v[0:3]
	s_setprio 0
	s_barrier
	s_add_i32 s33, 0, 0x18000
	v_add_u32_e32 v128, s33, v188
	s_add_i32 s38, 0, 0x1c000
	ds_read_b128 v[150:153], v128
	ds_read_b128 v[154:157], v128 offset:1024
	ds_read_b128 v[158:161], v128 offset:2048
	ds_read_b128 v[162:165], v128 offset:3072
	v_add_u32_e32 v128, s38, v188
	ds_read_b128 v[166:169], v128
	ds_read_b128 v[170:173], v128 offset:1024
	ds_read_b128 v[174:177], v128 offset:2048
	ds_read_b128 v[178:181], v128 offset:3072
	s_add_u32 s12, s12, s18
	s_addc_u32 s13, s13, s19
	s_mov_b32 m0, s68
	v_lshl_add_u64 v[234:235], s[12:13], 0, v[130:131]
	ds_read_b128 v[182:185], v193 offset:32768
	ds_read_b128 v[196:199], v193 offset:33792
	ds_read_b128 v[200:203], v193 offset:34816
	ds_read_b128 v[204:207], v193 offset:35840
	ds_read_b128 v[208:211], v193 offset:36864
	ds_read_b128 v[212:215], v193 offset:37888
	ds_read_b128 v[216:219], v193 offset:38912
	ds_read_b128 v[220:223], v193 offset:39936
	global_load_lds_dwordx4 v[234:235], off
	v_lshl_add_u64 v[234:235], s[12:13], 0, v[134:135]
	s_mov_b32 m0, s69
	s_nop 0
	global_load_lds_dwordx4 v[234:235], off
	s_waitcnt vmcnt(8)
	s_waitcnt lgkmcnt(0)
	s_barrier
	s_setprio 1
	s_waitcnt lgkmcnt(0)
	v_mfma_f32_16x16x32_bf16 v[124:127], v[150:153], v[182:185], v[124:127]
	v_mfma_f32_16x16x32_bf16 v[120:123], v[158:161], v[182:185], v[120:123]
	v_mfma_f32_16x16x32_bf16 v[108:111], v[150:153], v[200:203], v[108:111]
	v_mfma_f32_16x16x32_bf16 v[104:107], v[158:161], v[200:203], v[104:107]
	v_mfma_f32_16x16x32_bf16 v[92:95], v[150:153], v[208:211], v[92:95]
	v_mfma_f32_16x16x32_bf16 v[88:91], v[158:161], v[208:211], v[88:91]
	v_mfma_f32_16x16x32_bf16 v[76:79], v[150:153], v[216:219], v[76:79]
	v_mfma_f32_16x16x32_bf16 v[72:75], v[158:161], v[216:219], v[72:75]
	v_mfma_f32_16x16x32_bf16 v[124:127], v[154:157], v[196:199], v[124:127]
	v_mfma_f32_16x16x32_bf16 v[120:123], v[162:165], v[196:199], v[120:123]
	v_mfma_f32_16x16x32_bf16 v[108:111], v[154:157], v[204:207], v[108:111]
	v_mfma_f32_16x16x32_bf16 v[104:107], v[162:165], v[204:207], v[104:107]
	v_mfma_f32_16x16x32_bf16 v[92:95], v[154:157], v[212:215], v[92:95]
	v_mfma_f32_16x16x32_bf16 v[88:91], v[162:165], v[212:215], v[88:91]
	v_mfma_f32_16x16x32_bf16 v[76:79], v[154:157], v[220:223], v[76:79]
	v_mfma_f32_16x16x32_bf16 v[72:75], v[162:165], v[220:223], v[72:75]
	s_setprio 0
	s_setprio 1
	v_mfma_f32_16x16x32_bf16 v[116:119], v[166:169], v[182:185], v[116:119]
	v_mfma_f32_16x16x32_bf16 v[112:115], v[174:177], v[182:185], v[112:115]
	v_mfma_f32_16x16x32_bf16 v[100:103], v[166:169], v[200:203], v[100:103]
	v_mfma_f32_16x16x32_bf16 v[96:99], v[174:177], v[200:203], v[96:99]
	v_mfma_f32_16x16x32_bf16 v[84:87], v[166:169], v[208:211], v[84:87]
	v_mfma_f32_16x16x32_bf16 v[80:83], v[174:177], v[208:211], v[80:83]
	v_mfma_f32_16x16x32_bf16 v[68:71], v[166:169], v[216:219], v[68:71]
	v_mfma_f32_16x16x32_bf16 v[64:67], v[174:177], v[216:219], v[64:67]
	v_mfma_f32_16x16x32_bf16 v[116:119], v[170:173], v[196:199], v[116:119]
	v_mfma_f32_16x16x32_bf16 v[112:115], v[178:181], v[196:199], v[112:115]
	v_mfma_f32_16x16x32_bf16 v[100:103], v[170:173], v[204:207], v[100:103]
	v_mfma_f32_16x16x32_bf16 v[96:99], v[178:181], v[204:207], v[96:99]
	v_mfma_f32_16x16x32_bf16 v[84:87], v[170:173], v[212:215], v[84:87]
	v_mfma_f32_16x16x32_bf16 v[80:83], v[178:181], v[212:215], v[80:83]
	v_mfma_f32_16x16x32_bf16 v[68:71], v[170:173], v[220:223], v[68:71]
	v_mfma_f32_16x16x32_bf16 v[64:67], v[178:181], v[220:223], v[64:67]
	s_setprio 0
	s_barrier
; #define PG8_STAGE(bufoff, gbase, voff) do { _Pragma("unroll") for (int _i = 0; _i < 2; ++_i) \
;         __builtin_amdgcn_global_load_lds((const unsigned*)((const char*)(gbase) + (voff)[_i]), (PG8_LAS unsigned*)(lds + (bufoff) + ldsw + _i * 8192), 16, 0, 0); } while (0)
; #define PG8_LDA(dst, b, h) do { _Pragma("unroll") for (int m = 0; m < 4; ++m) _Pragma("unroll") for (int k = 0; k < 2; ++k) dst[m][k] = *(const PG8_LAS bf16x8*)(lds + PG8_SA(b, h) + aoff + m * 2048 + k * 1024); } while (0)
; #define PG8_MMA(ai, bj, At, Bt) do { __builtin_amdgcn_s_setprio(1); _Pragma("unroll") for (int m = 0; m < 4; ++m) _Pragma("unroll") for (int n = 0; n < 2; ++n) _Pragma("unroll") for (int k = 0; k < 2; ++k) \
;         acc[ai][bj][m][n] = __builtin_amdgcn_mfma_f32_16x16x32_bf16(Bt[n][k], At[m][k], acc[ai][bj][m][n], 0, 0, 0); __builtin_amdgcn_s_setprio(0); } while (0)
; #define PG8_WAIT_V(n) asm volatile("s_waitcnt vmcnt(" #n ")" ::: "memory")
; #define PG8_WAIT_L(n) asm volatile("s_waitcnt lgkmcnt(" #n ")" ::: "memory")
; #define PG8_BAR __builtin_amdgcn_s_barrier()
; #define PG8_SCHED __builtin_amdgcn_sched_barrier(0)
; template <class Epi, class Sched, bool ALIGN_EPI = false, bool SP2 = false>
; __device__ __forceinline__ void gemm_phase(PG8_LAS unsigned char* lds, const Gemm g, const Sched& S, const Epi& E) {
;     ...
;             PG8_LDA(At, 1, 1); PG8_STAGE(PG8_SB(1, 0), b3, voffB); PG8_STAGE(PG8_SB(1, 1), b3 + hstep, voffB); PG8_STAGE(PG8_SA(1, 0), a3, voffA);
;             PG8_WAIT_V(8); PG8_WAIT_L(0); PG8_BAR; PG8_MMA(1, 0, At, B0); PG8_MMA(1, 1, At, B1); PG8_BAR; PG8_SCHED;
	s_add_i32 s12, s33, s49
	v_lshl_add_u64 v[186:187], v[186:187], 0, s[42:43]
	s_mov_b32 m0, s12
	ds_read_b128 v[182:185], v193 offset:49152
	ds_read_b128 v[196:199], v193 offset:50176
	ds_read_b128 v[200:203], v193 offset:51200
	ds_read_b128 v[204:207], v193 offset:52224
	ds_read_b128 v[208:211], v193 offset:53248
	ds_read_b128 v[212:215], v193 offset:54272
	ds_read_b128 v[216:219], v193 offset:55296
	ds_read_b128 v[220:223], v193 offset:56320
	global_load_lds_dwordx4 v[186:187], off
	v_lshl_add_u64 v[186:187], v[224:225], 0, s[42:43]
	s_add_i32 m0, s12, 0x2000
	s_add_i32 s12, s38, s49
	global_load_lds_dwordx4 v[186:187], off
	v_lshl_add_u64 v[186:187], v[226:227], 0, s[42:43]
	s_mov_b32 m0, s12
	s_nop 0
	global_load_lds_dwordx4 v[186:187], off
	v_lshl_add_u64 v[186:187], v[228:229], 0, s[42:43]
	s_add_i32 m0, s12, 0x2000
	s_nop 0
	global_load_lds_dwordx4 v[186:187], off
	v_lshl_add_u64 v[186:187], v[230:231], 0, s[42:43]
	s_mov_b32 m0, s70
	s_nop 0
	global_load_lds_dwordx4 v[186:187], off
	v_lshl_add_u64 v[186:187], v[232:233], 0, s[42:43]
	s_mov_b32 m0, s71
	s_nop 0
	global_load_lds_dwordx4 v[186:187], off
	s_waitcnt vmcnt(8)
	s_waitcnt lgkmcnt(0)
	s_barrier
	s_setprio 1
	s_waitcnt lgkmcnt(0)
	v_mfma_f32_16x16x32_bf16 v[60:63], v[150:153], v[182:185], v[60:63]
	v_mfma_f32_16x16x32_bf16 v[56:59], v[158:161], v[182:185], v[56:59]
	v_mfma_f32_16x16x32_bf16 v[44:47], v[150:153], v[200:203], v[44:47]
	v_mfma_f32_16x16x32_bf16 v[40:43], v[158:161], v[200:203], v[40:43]
	v_mfma_f32_16x16x32_bf16 v[28:31], v[150:153], v[208:211], v[28:31]
	v_mfma_f32_16x16x32_bf16 v[24:27], v[158:161], v[208:211], v[24:27]
	v_mfma_f32_16x16x32_bf16 v[12:15], v[150:153], v[216:219], v[12:15]
	v_mfma_f32_16x16x32_bf16 v[8:11], v[158:161], v[216:219], v[8:11]
	v_mfma_f32_16x16x32_bf16 v[60:63], v[154:157], v[196:199], v[60:63]
	v_mfma_f32_16x16x32_bf16 v[56:59], v[162:165], v[196:199], v[56:59]
	v_mfma_f32_16x16x32_bf16 v[44:47], v[154:157], v[204:207], v[44:47]
	v_mfma_f32_16x16x32_bf16 v[40:43], v[162:165], v[204:207], v[40:43]
	v_mfma_f32_16x16x32_bf16 v[28:31], v[154:157], v[212:215], v[28:31]
	v_mfma_f32_16x16x32_bf16 v[24:27], v[162:165], v[212:215], v[24:27]
	v_mfma_f32_16x16x32_bf16 v[12:15], v[154:157], v[220:223], v[12:15]
	v_mfma_f32_16x16x32_bf16 v[8:11], v[162:165], v[220:223], v[8:11]
	s_setprio 0
	s_setprio 1
	v_mfma_f32_16x16x32_bf16 v[52:55], v[166:169], v[182:185], v[52:55]
	v_mfma_f32_16x16x32_bf16 v[48:51], v[174:177], v[182:185], v[48:51]
	v_mfma_f32_16x16x32_bf16 v[36:39], v[166:169], v[200:203], v[36:39]
	v_mfma_f32_16x16x32_bf16 v[32:35], v[174:177], v[200:203], v[32:35]
	v_mfma_f32_16x16x32_bf16 v[20:23], v[166:169], v[208:211], v[20:23]
	v_mfma_f32_16x16x32_bf16 v[16:19], v[174:177], v[208:211], v[16:19]
	v_mfma_f32_16x16x32_bf16 v[4:7], v[166:169], v[216:219], v[4:7]
	v_mfma_f32_16x16x32_bf16 v[0:3], v[174:177], v[216:219], v[0:3]
	v_mfma_f32_16x16x32_bf16 v[52:55], v[170:173], v[196:199], v[52:55]
	v_mfma_f32_16x16x32_bf16 v[48:51], v[178:181], v[196:199], v[48:51]
	v_mfma_f32_16x16x32_bf16 v[36:39], v[170:173], v[204:207], v[36:39]
	v_mfma_f32_16x16x32_bf16 v[32:35], v[178:181], v[204:207], v[32:35]
	v_mfma_f32_16x16x32_bf16 v[20:23], v[170:173], v[212:215], v[20:23]
	v_mfma_f32_16x16x32_bf16 v[16:19], v[178:181], v[212:215], v[16:19]
	v_mfma_f32_16x16x32_bf16 v[4:7], v[170:173], v[220:223], v[4:7]
	v_mfma_f32_16x16x32_bf16 v[0:3], v[178:181], v[220:223], v[0:3]
	s_setprio 0
	s_barrier
	s_add_u32 s10, s10, 0x100
	s_addc_u32 s11, s11, 0
	s_add_u32 s5, s5, 0x100
	s_addc_u32 s14, s14, 0
	s_cmp_ge_i32 s15, s72
	s_mov_b32 s12, s15
	s_cbranch_scc0 .LBB0_473
	s_branch .Lpx_k473

; #define PG8_BAR __builtin_amdgcn_s_barrier()
; template <class Epi, class Sched, bool ALIGN_EPI = false, bool SP2 = false>
; __device__ __forceinline__ void gemm_phase(PG8_LAS unsigned char* lds, const Gemm g, const Sched& S, const Epi& E) {
;     ...
;         if constexpr (ALIGN_EPI) { if (wr == 0) PG8_BAR; }
.Lpx_k473:
.LBB0_474:
	s_and_b64 vcc, exec, s[58:59]
	s_cbranch_vccz .LBB0_476
	s_barrier

;     __host__ __device__ bool next(int i, Unit& u) const { const int idx = first + i; if (idx >= last) return false; u.pm = idx >> 2; u.pn = idx & 3; return true; }
; #define PG8_STAGE(bufoff, gbase, voff) do { _Pragma("unroll") for (int _i = 0; _i < 2; ++_i) \
;         __builtin_amdgcn_global_load_lds((const unsigned*)((const char*)(gbase) + (voff)[_i]), (PG8_LAS unsigned*)(lds + (bufoff) + ldsw + _i * 8192), 16, 0, 0); } while (0)
; #define PG8_LDA(dst, b, h) do { _Pragma("unroll") for (int m = 0; m < 4; ++m) _Pragma("unroll") for (int k = 0; k < 2; ++k) dst[m][k] = *(const PG8_LAS bf16x8*)(lds + PG8_SA(b, h) + aoff + m * 2048 + k * 1024); } while (0)
; #define PG8_LDB(dst, b, h) do { _Pragma("unroll") for (int n = 0; n < 2; ++n) _Pragma("unroll") for (int k = 0; k < 2; ++k) dst[n][k] = *(const PG8_LAS bf16x8*)(lds + PG8_SB(b, h) + boff + n * 2048 + k * 1024); } while (0)
; #define PG8_WAIT_V(n) asm volatile("s_waitcnt vmcnt(" #n ")" ::: "memory")
; #define PG8_WAIT_L(n) asm volatile("s_waitcnt lgkmcnt(" #n ")" ::: "memory")
; #define PG8_BAR __builtin_amdgcn_s_barrier()
; template <class Epi, class Sched, bool ALIGN_EPI = false, bool SP2 = false>
; __device__ __forceinline__ void gemm_phase(PG8_LAS unsigned char* lds, const Gemm g, const Sched& S, const Epi& E) {
;     ...
;     for (;;) {
;         const bool has_next = S.next(ui + 1, nxt);
;         const char* nA = has_next ? (const char*)g.A + (size_t)nxt.pm * tstep : cA; const char* nB = has_next ? (const char*)g.Bt + (size_t)nxt.pn * tstep : cB;
;         asm volatile(".p2align 8");
;         for (int t = 0; t < nt; t += 2) {
;             const bool last = (t == nt - 2);
;             const char* a1 = cA + (size_t)(t + 1) * kstep;
;             const char* a2 = last ? nA : cA + (size_t)(t + 2) * kstep; const char* b2 = last ? nB : cB + (size_t)(t + 2) * kstep;
;             const char* a3 = a2 + kstep; const char* b3 = b2 + kstep;
;             if (last && has_next) S.a_ready(nxt);
;             if constexpr (SP2) {
;             PG8_LDB(B0, 0, 0); PG8_LDB(B1, 0, 1); PG8_SCHED; PG8_LDA(At, 0, 0); PG8_STAGE(PG8_SA(1, 1), a1 + hstep, voffA);
;             PG8_WAIT_V(8); PG8_WAIT_L(0); PG8_BAR; PG8_MMA(0, 0, At, B0); PG8_MMA(0, 1, At, B1); PG8_BAR; PG8_SCHED;
;             PG8_LDA(At, 0, 1); PG8_STAGE(PG8_SB(0, 0), b2, voffB); PG8_STAGE(PG8_SB(0, 1), b2 + hstep, voffB); PG8_STAGE(PG8_SA(0, 0), a2, voffA);
.LBB0_919:
	s_andn2_b64 vcc, exec, s[36:37]
	s_waitcnt vmcnt(0)
	.p2align 8
	s_cbranch_vccnz .Lpz_k921
	s_add_u32 s42, s42, 0x80
	s_addc_u32 s43, s43, 0
	s_add_u32 s5, s58, 0x100
	s_addc_u32 s33, s59, 0
	s_mov_b32 s58, 0
.Lpeel_k921:
	ds_read_b128 v[128:131], v247
	ds_read_b128 v[132:135], v247 offset:1024
	ds_read_b128 v[136:139], v247 offset:2048
	ds_read_b128 v[140:143], v247 offset:3072
	ds_read_b128 v[144:147], v248
	ds_read_b128 v[148:151], v248 offset:1024
	ds_read_b128 v[152:155], v248 offset:2048
	ds_read_b128 v[156:159], v248 offset:3072
	s_add_i32 s75, s58, 2
	s_add_u32 s76, s42, 0x80
	s_addc_u32 s59, s43, 0
	s_cmp_eq_u32 s66, s58
	s_cselect_b32 s58, s8, s76
	s_cselect_b32 s59, s9, s59
	s_cselect_b32 s77, s41, s33
	s_cselect_b32 s76, s40, s5
	v_lshl_add_u64 v[208:209], s[42:43], 0, v[202:203]
	s_add_i32 m0, s48, 0xc000
	ds_read_b128 v[160:163], v249
	ds_read_b128 v[164:167], v249 offset:1024
	ds_read_b128 v[168:171], v249 offset:2048
	ds_read_b128 v[172:175], v249 offset:3072
	ds_read_b128 v[176:179], v249 offset:4096
	ds_read_b128 v[180:183], v249 offset:5120
	ds_read_b128 v[184:187], v249 offset:6144
	ds_read_b128 v[188:191], v249 offset:7168
	global_load_lds_dwordx4 v[208:209], off
	v_lshl_add_u64 v[208:209], s[42:43], 0, v[204:205]
	s_add_i32 m0, s48, 0xe000
	s_nop 0
	global_load_lds_dwordx4 v[208:209], off
	s_waitcnt vmcnt(8)
	s_waitcnt lgkmcnt(0)
	s_barrier
	s_setprio 1
	s_waitcnt lgkmcnt(0)
	v_mfma_f32_16x16x32_bf16 v[120:123], v[128:131], v[160:163], 0
	v_mfma_f32_16x16x32_bf16 v[124:127], v[136:139], v[160:163], 0
	v_mfma_f32_16x16x32_bf16 v[108:111], v[128:131], v[168:171], 0
	v_mfma_f32_16x16x32_bf16 v[104:107], v[136:139], v[168:171], 0
	v_mfma_f32_16x16x32_bf16 v[92:95], v[128:131], v[176:179], 0
	v_mfma_f32_16x16x32_bf16 v[88:91], v[136:139], v[176:179], 0
	v_mfma_f32_16x16x32_bf16 v[76:79], v[128:131], v[184:187], 0
	v_mfma_f32_16x16x32_bf16 v[72:75], v[136:139], v[184:187], 0
	v_mfma_f32_16x16x32_bf16 v[120:123], v[132:135], v[164:167], v[120:123]
	v_mfma_f32_16x16x32_bf16 v[124:127], v[140:143], v[164:167], v[124:127]
	v_mfma_f32_16x16x32_bf16 v[108:111], v[132:135], v[172:175], v[108:111]
	v_mfma_f32_16x16x32_bf16 v[104:107], v[140:143], v[172:175], v[104:107]
	v_mfma_f32_16x16x32_bf16 v[92:95], v[132:135], v[180:183], v[92:95]
	v_mfma_f32_16x16x32_bf16 v[88:91], v[140:143], v[180:183], v[88:91]
	v_mfma_f32_16x16x32_bf16 v[76:79], v[132:135], v[188:191], v[76:79]
	v_mfma_f32_16x16x32_bf16 v[72:75], v[140:143], v[188:191], v[72:75]
	s_setprio 0
	s_setprio 1
	v_mfma_f32_16x16x32_bf16 v[116:119], v[144:147], v[160:163], 0
	v_mfma_f32_16x16x32_bf16 v[112:115], v[152:155], v[160:163], 0
	v_mfma_f32_16x16x32_bf16 v[100:103], v[144:147], v[168:171], 0
	v_mfma_f32_16x16x32_bf16 v[96:99], v[152:155], v[168:171], 0
	v_mfma_f32_16x16x32_bf16 v[84:87], v[144:147], v[176:179], 0
	v_mfma_f32_16x16x32_bf16 v[80:83], v[152:155], v[176:179], 0
	v_mfma_f32_16x16x32_bf16 v[68:71], v[144:147], v[184:187], 0
	v_mfma_f32_16x16x32_bf16 v[64:67], v[152:155], v[184:187], 0
	v_mfma_f32_16x16x32_bf16 v[116:119], v[148:151], v[164:167], v[116:119]
	v_mfma_f32_16x16x32_bf16 v[112:115], v[156:159], v[164:167], v[112:115]
	v_mfma_f32_16x16x32_bf16 v[100:103], v[148:151], v[172:175], v[100:103]
	v_mfma_f32_16x16x32_bf16 v[96:99], v[156:159], v[172:175], v[96:99]
	v_mfma_f32_16x16x32_bf16 v[84:87], v[148:151], v[180:183], v[84:87]
	v_mfma_f32_16x16x32_bf16 v[80:83], v[156:159], v[180:183], v[80:83]
	v_mfma_f32_16x16x32_bf16 v[68:71], v[148:151], v[188:191], v[68:71]
	v_mfma_f32_16x16x32_bf16 v[64:67], v[156:159], v[188:191], v[64:67]
	s_setprio 0
	s_barrier
	s_add_i32 s78, s70, s3
	v_lshl_add_u64 v[208:209], s[76:77], 0, v[196:197]
	s_mov_b32 m0, s78
	ds_read_b128 v[160:163], v249 offset:16384
	ds_read_b128 v[164:167], v249 offset:17408
	ds_read_b128 v[168:171], v249 offset:18432
	ds_read_b128 v[172:175], v249 offset:19456
	ds_read_b128 v[176:179], v249 offset:20480
	ds_read_b128 v[180:183], v249 offset:21504
	ds_read_b128 v[184:187], v249 offset:22528
	ds_read_b128 v[188:191], v249 offset:23552
	global_load_lds_dwordx4 v[208:209], off
	s_add_i32 m0, s78, 0x2000
	v_lshl_add_u64 v[210:211], s[76:77], 0, v[200:201]
	s_add_u32 s76, s76, s14
	s_addc_u32 s77, s77, s15
	s_add_i32 s78, s71, s3
	global_load_lds_dwordx4 v[210:211], off
	v_lshl_add_u64 v[212:213], s[76:77], 0, v[196:197]
	s_mov_b32 m0, s78
	v_lshl_add_u64 v[214:215], s[76:77], 0, v[200:201]
	global_load_lds_dwordx4 v[212:213], off
	s_add_i32 m0, s78, 0x2000
	v_lshl_add_u64 v[216:217], s[58:59], 0, v[194:195]
	global_load_lds_dwordx4 v[214:215], off
	s_mov_b32 m0, s48
	v_lshl_add_u64 v[218:219], s[58:59], 0, v[198:199]
	global_load_lds_dwordx4 v[216:217], off
	s_mov_b32 m0, s49
	s_nop 0
	global_load_lds_dwordx4 v[218:219], off
	s_waitcnt vmcnt(8)
	s_waitcnt lgkmcnt(0)
	s_barrier
; #define PG8_STAGE(bufoff, gbase, voff) do { _Pragma("unroll") for (int _i = 0; _i < 2; ++_i) \
;         __builtin_amdgcn_global_load_lds((const unsigned*)((const char*)(gbase) + (voff)[_i]), (PG8_LAS unsigned*)(lds + (bufoff) + ldsw + _i * 8192), 16, 0, 0); } while (0)
; #define PG8_LDA(dst, b, h) do { _Pragma("unroll") for (int m = 0; m < 4; ++m) _Pragma("unroll") for (int k = 0; k < 2; ++k) dst[m][k] = *(const PG8_LAS bf16x8*)(lds + PG8_SA(b, h) + aoff + m * 2048 + k * 1024); } while (0)
; #define PG8_LDB(dst, b, h) do { _Pragma("unroll") for (int n = 0; n < 2; ++n) _Pragma("unroll") for (int k = 0; k < 2; ++k) dst[n][k] = *(const PG8_LAS bf16x8*)(lds + PG8_SB(b, h) + boff + n * 2048 + k * 1024); } while (0)
; #define PG8_MMA(ai, bj, At, Bt) do { __builtin_amdgcn_s_setprio(1); _Pragma("unroll") for (int m = 0; m < 4; ++m) _Pragma("unroll") for (int n = 0; n < 2; ++n) _Pragma("unroll") for (int k = 0; k < 2; ++k) \
;         acc[ai][bj][m][n] = __builtin_amdgcn_mfma_f32_16x16x32_bf16(Bt[n][k], At[m][k], acc[ai][bj][m][n], 0, 0, 0); __builtin_amdgcn_s_setprio(0); } while (0)
; #define PG8_WAIT_V(n) asm volatile("s_waitcnt vmcnt(" #n ")" ::: "memory")
; #define PG8_WAIT_L(n) asm volatile("s_waitcnt lgkmcnt(" #n ")" ::: "memory")
; #define PG8_BAR __builtin_amdgcn_s_barrier()
; #define PG8_SCHED __builtin_amdgcn_sched_barrier(0)
; template <class Epi, class Sched, bool ALIGN_EPI = false, bool SP2 = false>
; __device__ __forceinline__ void gemm_phase(PG8_LAS unsigned char* lds, const Gemm g, const Sched& S, const Epi& E) {
;     ...
;             PG8_WAIT_V(8); PG8_WAIT_L(0); PG8_BAR; PG8_MMA(1, 0, At, B0); PG8_MMA(1, 1, At, B1); PG8_BAR; PG8_SCHED;
;             PG8_LDB(B0, 1, 0); PG8_LDB(B1, 1, 1); PG8_SCHED; PG8_LDA(At, 1, 0); PG8_STAGE(PG8_SA(0, 1), a2 + hstep, voffA);
;             PG8_WAIT_V(8); PG8_WAIT_L(0); PG8_BAR; PG8_MMA(0, 0, At, B0); PG8_MMA(0, 1, At, B1); PG8_BAR; PG8_SCHED;
	s_setprio 1
	s_waitcnt lgkmcnt(0)
	v_mfma_f32_16x16x32_bf16 v[60:63], v[128:131], v[160:163], 0
	v_mfma_f32_16x16x32_bf16 v[56:59], v[136:139], v[160:163], 0
	v_mfma_f32_16x16x32_bf16 v[44:47], v[128:131], v[168:171], 0
	v_mfma_f32_16x16x32_bf16 v[40:43], v[136:139], v[168:171], 0
	v_mfma_f32_16x16x32_bf16 v[28:31], v[128:131], v[176:179], 0
	v_mfma_f32_16x16x32_bf16 v[24:27], v[136:139], v[176:179], 0
	v_mfma_f32_16x16x32_bf16 v[12:15], v[128:131], v[184:187], 0
	v_mfma_f32_16x16x32_bf16 v[8:11], v[136:139], v[184:187], 0
	v_mfma_f32_16x16x32_bf16 v[60:63], v[132:135], v[164:167], v[60:63]
	v_mfma_f32_16x16x32_bf16 v[56:59], v[140:143], v[164:167], v[56:59]
	v_mfma_f32_16x16x32_bf16 v[44:47], v[132:135], v[172:175], v[44:47]
	v_mfma_f32_16x16x32_bf16 v[40:43], v[140:143], v[172:175], v[40:43]
	v_mfma_f32_16x16x32_bf16 v[28:31], v[132:135], v[180:183], v[28:31]
	v_mfma_f32_16x16x32_bf16 v[24:27], v[140:143], v[180:183], v[24:27]
	v_mfma_f32_16x16x32_bf16 v[12:15], v[132:135], v[188:191], v[12:15]
	v_mfma_f32_16x16x32_bf16 v[8:11], v[140:143], v[188:191], v[8:11]
	s_setprio 0
	s_setprio 1
	v_mfma_f32_16x16x32_bf16 v[52:55], v[144:147], v[160:163], 0
	v_mfma_f32_16x16x32_bf16 v[48:51], v[152:155], v[160:163], 0
	v_mfma_f32_16x16x32_bf16 v[36:39], v[144:147], v[168:171], 0
	v_mfma_f32_16x16x32_bf16 v[32:35], v[152:155], v[168:171], 0
	v_mfma_f32_16x16x32_bf16 v[20:23], v[144:147], v[176:179], 0
	v_mfma_f32_16x16x32_bf16 v[16:19], v[152:155], v[176:179], 0
	v_mfma_f32_16x16x32_bf16 v[4:7], v[144:147], v[184:187], 0
	v_mfma_f32_16x16x32_bf16 v[0:3], v[152:155], v[184:187], 0
	v_mfma_f32_16x16x32_bf16 v[52:55], v[148:151], v[164:167], v[52:55]
	v_mfma_f32_16x16x32_bf16 v[48:51], v[156:159], v[164:167], v[48:51]
	v_mfma_f32_16x16x32_bf16 v[36:39], v[148:151], v[172:175], v[36:39]
	v_mfma_f32_16x16x32_bf16 v[32:35], v[156:159], v[172:175], v[32:35]
	v_mfma_f32_16x16x32_bf16 v[20:23], v[148:151], v[180:183], v[20:23]
	v_mfma_f32_16x16x32_bf16 v[16:19], v[156:159], v[180:183], v[16:19]
	v_mfma_f32_16x16x32_bf16 v[4:7], v[148:151], v[188:191], v[4:7]
	v_mfma_f32_16x16x32_bf16 v[0:3], v[156:159], v[188:191], v[0:3]
	s_setprio 0
	s_barrier
	s_add_i32 s76, 0, 0x18000
	s_add_i32 s77, 0, 0x1c000
	v_add_u32_e32 v140, s76, v244
	v_add_u32_e32 v156, s77, v244
	ds_read_b128 v[128:131], v140
	ds_read_b128 v[132:135], v140 offset:1024
	ds_read_b128 v[136:139], v140 offset:2048
	ds_read_b128 v[140:143], v140 offset:3072
	ds_read_b128 v[144:147], v156
	ds_read_b128 v[148:151], v156 offset:1024
	ds_read_b128 v[152:155], v156 offset:2048
	ds_read_b128 v[156:159], v156 offset:3072
	s_add_u32 s58, s58, s14
	s_addc_u32 s59, s59, s15
	s_mov_b32 m0, s60
	v_lshl_add_u64 v[220:221], s[58:59], 0, v[194:195]
	ds_read_b128 v[160:163], v249 offset:32768
	ds_read_b128 v[164:167], v249 offset:33792
	ds_read_b128 v[168:171], v249 offset:34816
	ds_read_b128 v[172:175], v249 offset:35840
	ds_read_b128 v[176:179], v249 offset:36864
	ds_read_b128 v[180:183], v249 offset:37888
	ds_read_b128 v[184:187], v249 offset:38912
	ds_read_b128 v[188:191], v249 offset:39936
	global_load_lds_dwordx4 v[220:221], off
	v_lshl_add_u64 v[220:221], s[58:59], 0, v[198:199]
	s_mov_b32 m0, s61
	s_nop 0
	global_load_lds_dwordx4 v[220:221], off
	s_waitcnt vmcnt(8)
	s_waitcnt lgkmcnt(0)
	s_barrier
	s_setprio 1
	s_waitcnt lgkmcnt(0)
	v_mfma_f32_16x16x32_bf16 v[120:123], v[128:131], v[160:163], v[120:123]
	v_mfma_f32_16x16x32_bf16 v[124:127], v[136:139], v[160:163], v[124:127]
	v_mfma_f32_16x16x32_bf16 v[108:111], v[128:131], v[168:171], v[108:111]
	v_mfma_f32_16x16x32_bf16 v[104:107], v[136:139], v[168:171], v[104:107]
	v_mfma_f32_16x16x32_bf16 v[92:95], v[128:131], v[176:179], v[92:95]
	v_mfma_f32_16x16x32_bf16 v[88:91], v[136:139], v[176:179], v[88:91]
	v_mfma_f32_16x16x32_bf16 v[76:79], v[128:131], v[184:187], v[76:79]
	v_mfma_f32_16x16x32_bf16 v[72:75], v[136:139], v[184:187], v[72:75]
	v_mfma_f32_16x16x32_bf16 v[120:123], v[132:135], v[164:167], v[120:123]
	v_mfma_f32_16x16x32_bf16 v[124:127], v[140:143], v[164:167], v[124:127]
	v_mfma_f32_16x16x32_bf16 v[108:111], v[132:135], v[172:175], v[108:111]
	v_mfma_f32_16x16x32_bf16 v[104:107], v[140:143], v[172:175], v[104:107]
	v_mfma_f32_16x16x32_bf16 v[92:95], v[132:135], v[180:183], v[92:95]
	v_mfma_f32_16x16x32_bf16 v[88:91], v[140:143], v[180:183], v[88:91]
	v_mfma_f32_16x16x32_bf16 v[76:79], v[132:135], v[188:191], v[76:79]
	v_mfma_f32_16x16x32_bf16 v[72:75], v[140:143], v[188:191], v[72:75]
	s_setprio 0
	s_setprio 1
	v_mfma_f32_16x16x32_bf16 v[116:119], v[144:147], v[160:163], v[116:119]
	v_mfma_f32_16x16x32_bf16 v[112:115], v[152:155], v[160:163], v[112:115]
	v_mfma_f32_16x16x32_bf16 v[100:103], v[144:147], v[168:171], v[100:103]
	v_mfma_f32_16x16x32_bf16 v[96:99], v[152:155], v[168:171], v[96:99]
	v_mfma_f32_16x16x32_bf16 v[84:87], v[144:147], v[176:179], v[84:87]
	v_mfma_f32_16x16x32_bf16 v[80:83], v[152:155], v[176:179], v[80:83]
	v_mfma_f32_16x16x32_bf16 v[68:71], v[144:147], v[184:187], v[68:71]
	v_mfma_f32_16x16x32_bf16 v[64:67], v[152:155], v[184:187], v[64:67]
	v_mfma_f32_16x16x32_bf16 v[116:119], v[148:151], v[164:167], v[116:119]
	v_mfma_f32_16x16x32_bf16 v[112:115], v[156:159], v[164:167], v[112:115]
	v_mfma_f32_16x16x32_bf16 v[100:103], v[148:151], v[172:175], v[100:103]
	v_mfma_f32_16x16x32_bf16 v[96:99], v[156:159], v[172:175], v[96:99]
	v_mfma_f32_16x16x32_bf16 v[84:87], v[148:151], v[180:183], v[84:87]
	v_mfma_f32_16x16x32_bf16 v[80:83], v[156:159], v[180:183], v[80:83]
	v_mfma_f32_16x16x32_bf16 v[68:71], v[148:151], v[188:191], v[68:71]
	v_mfma_f32_16x16x32_bf16 v[64:67], v[156:159], v[188:191], v[64:67]
	s_setprio 0
	s_barrier
; #define PG8_STAGE(bufoff, gbase, voff) do { _Pragma("unroll") for (int _i = 0; _i < 2; ++_i) \
;         __builtin_amdgcn_global_load_lds((const unsigned*)((const char*)(gbase) + (voff)[_i]), (PG8_LAS unsigned*)(lds + (bufoff) + ldsw + _i * 8192), 16, 0, 0); } while (0)
; #define PG8_LDA(dst, b, h) do { _Pragma("unroll") for (int m = 0; m < 4; ++m) _Pragma("unroll") for (int k = 0; k < 2; ++k) dst[m][k] = *(const PG8_LAS bf16x8*)(lds + PG8_SA(b, h) + aoff + m * 2048 + k * 1024); } while (0)
; #define PG8_MMA(ai, bj, At, Bt) do { __builtin_amdgcn_s_setprio(1); _Pragma("unroll") for (int m = 0; m < 4; ++m) _Pragma("unroll") for (int n = 0; n < 2; ++n) _Pragma("unroll") for (int k = 0; k < 2; ++k) \
;         acc[ai][bj][m][n] = __builtin_amdgcn_mfma_f32_16x16x32_bf16(Bt[n][k], At[m][k], acc[ai][bj][m][n], 0, 0, 0); __builtin_amdgcn_s_setprio(0); } while (0)
; #define PG8_WAIT_V(n) asm volatile("s_waitcnt vmcnt(" #n ")" ::: "memory")
; #define PG8_WAIT_L(n) asm volatile("s_waitcnt lgkmcnt(" #n ")" ::: "memory")
; #define PG8_BAR __builtin_amdgcn_s_barrier()
; #define PG8_SCHED __builtin_amdgcn_sched_barrier(0)
; template <class Epi, class Sched, bool ALIGN_EPI = false, bool SP2 = false>
; __device__ __forceinline__ void gemm_phase(PG8_LAS unsigned char* lds, const Gemm g, const Sched& S, const Epi& E) {
;     ...
;             PG8_LDA(At, 1, 1); PG8_STAGE(PG8_SB(1, 0), b3, voffB); PG8_STAGE(PG8_SB(1, 1), b3 + hstep, voffB); PG8_STAGE(PG8_SA(1, 0), a3, voffA);
;             PG8_WAIT_V(8); PG8_WAIT_L(0); PG8_BAR; PG8_MMA(1, 0, At, B0); PG8_MMA(1, 1, At, B1); PG8_BAR; PG8_SCHED;
	s_add_i32 s58, s76, s3
	v_lshl_add_u64 v[208:209], v[208:209], 0, s[22:23]
	s_mov_b32 m0, s58
	ds_read_b128 v[160:163], v249 offset:49152
	ds_read_b128 v[164:167], v249 offset:50176
	ds_read_b128 v[168:171], v249 offset:51200
	ds_read_b128 v[172:175], v249 offset:52224
	ds_read_b128 v[176:179], v249 offset:53248
	ds_read_b128 v[180:183], v249 offset:54272
	ds_read_b128 v[184:187], v249 offset:55296
	ds_read_b128 v[188:191], v249 offset:56320
	global_load_lds_dwordx4 v[208:209], off
	v_lshl_add_u64 v[208:209], v[210:211], 0, s[22:23]
	s_add_i32 m0, s58, 0x2000
	s_add_i32 s58, s77, s3
	global_load_lds_dwordx4 v[208:209], off
	v_lshl_add_u64 v[208:209], v[212:213], 0, s[22:23]
	s_mov_b32 m0, s58
	s_nop 0
	global_load_lds_dwordx4 v[208:209], off
	v_lshl_add_u64 v[208:209], v[214:215], 0, s[22:23]
	s_add_i32 m0, s58, 0x2000
	s_nop 0
	global_load_lds_dwordx4 v[208:209], off
	v_lshl_add_u64 v[208:209], v[216:217], 0, s[22:23]
	s_mov_b32 m0, s62
	s_nop 0
	global_load_lds_dwordx4 v[208:209], off
	v_lshl_add_u64 v[208:209], v[218:219], 0, s[22:23]
	s_mov_b32 m0, s63
	s_nop 0
	global_load_lds_dwordx4 v[208:209], off
	s_waitcnt vmcnt(8)
	s_waitcnt lgkmcnt(0)
	s_barrier
	s_setprio 1
	s_waitcnt lgkmcnt(0)
	v_mfma_f32_16x16x32_bf16 v[60:63], v[128:131], v[160:163], v[60:63]
	v_mfma_f32_16x16x32_bf16 v[56:59], v[136:139], v[160:163], v[56:59]
	v_mfma_f32_16x16x32_bf16 v[44:47], v[128:131], v[168:171], v[44:47]
	v_mfma_f32_16x16x32_bf16 v[40:43], v[136:139], v[168:171], v[40:43]
	v_mfma_f32_16x16x32_bf16 v[28:31], v[128:131], v[176:179], v[28:31]
	v_mfma_f32_16x16x32_bf16 v[24:27], v[136:139], v[176:179], v[24:27]
	v_mfma_f32_16x16x32_bf16 v[12:15], v[128:131], v[184:187], v[12:15]
	v_mfma_f32_16x16x32_bf16 v[8:11], v[136:139], v[184:187], v[8:11]
	v_mfma_f32_16x16x32_bf16 v[60:63], v[132:135], v[164:167], v[60:63]
	v_mfma_f32_16x16x32_bf16 v[56:59], v[140:143], v[164:167], v[56:59]
	v_mfma_f32_16x16x32_bf16 v[44:47], v[132:135], v[172:175], v[44:47]
	v_mfma_f32_16x16x32_bf16 v[40:43], v[140:143], v[172:175], v[40:43]
	v_mfma_f32_16x16x32_bf16 v[28:31], v[132:135], v[180:183], v[28:31]
	v_mfma_f32_16x16x32_bf16 v[24:27], v[140:143], v[180:183], v[24:27]
	v_mfma_f32_16x16x32_bf16 v[12:15], v[132:135], v[188:191], v[12:15]
	v_mfma_f32_16x16x32_bf16 v[8:11], v[140:143], v[188:191], v[8:11]
	s_setprio 0
	s_setprio 1
	v_mfma_f32_16x16x32_bf16 v[52:55], v[144:147], v[160:163], v[52:55]
	v_mfma_f32_16x16x32_bf16 v[48:51], v[152:155], v[160:163], v[48:51]
	v_mfma_f32_16x16x32_bf16 v[36:39], v[144:147], v[168:171], v[36:39]
	v_mfma_f32_16x16x32_bf16 v[32:35], v[152:155], v[168:171], v[32:35]
	v_mfma_f32_16x16x32_bf16 v[20:23], v[144:147], v[176:179], v[20:23]
	v_mfma_f32_16x16x32_bf16 v[16:19], v[152:155], v[176:179], v[16:19]
	v_mfma_f32_16x16x32_bf16 v[4:7], v[144:147], v[184:187], v[4:7]
	v_mfma_f32_16x16x32_bf16 v[0:3], v[152:155], v[184:187], v[0:3]
	v_mfma_f32_16x16x32_bf16 v[52:55], v[148:151], v[164:167], v[52:55]
	v_mfma_f32_16x16x32_bf16 v[48:51], v[156:159], v[164:167], v[48:51]
	v_mfma_f32_16x16x32_bf16 v[36:39], v[148:151], v[172:175], v[36:39]
	v_mfma_f32_16x16x32_bf16 v[32:35], v[156:159], v[172:175], v[32:35]
	v_mfma_f32_16x16x32_bf16 v[20:23], v[148:151], v[180:183], v[20:23]
	v_mfma_f32_16x16x32_bf16 v[16:19], v[156:159], v[180:183], v[16:19]
	v_mfma_f32_16x16x32_bf16 v[4:7], v[148:151], v[188:191], v[4:7]
	v_mfma_f32_16x16x32_bf16 v[0:3], v[156:159], v[188:191], v[0:3]
	s_setprio 0
	s_barrier
	s_add_u32 s42, s42, 0x100
	s_addc_u32 s43, s43, 0
	s_add_u32 s5, s5, 0x100
	s_addc_u32 s33, s33, 0
	s_cmp_ge_i32 s75, s65
	s_mov_b32 s58, s75
	s_cbranch_scc0 .LBB0_921
	s_branch .Lpx_k921

; #define PG8_BAR __builtin_amdgcn_s_barrier()
; template <class Epi, class Sched, bool ALIGN_EPI = false, bool SP2 = false>
; __device__ __forceinline__ void gemm_phase(PG8_LAS unsigned char* lds, const Gemm g, const Sched& S, const Epi& E) {
;     ...
;         if constexpr (ALIGN_EPI) { if (wr == 0) PG8_BAR; }
.Lpx_k921:
.LBB0_922:
	s_and_b64 vcc, exec, s[38:39]
	s_cbranch_vccz .LBB0_924
	s_barrier

;     __host__ __device__ bool next(int i, Unit& u) const { const int idx = first + i; if (idx >= last) return false; u.pm = idx >> 2; u.pn = idx & 3; return true; }
; #define PG8_STAGE(bufoff, gbase, voff) do { _Pragma("unroll") for (int _i = 0; _i < 2; ++_i) \
;         __builtin_amdgcn_global_load_lds((const unsigned*)((const char*)(gbase) + (voff)[_i]), (PG8_LAS unsigned*)(lds + (bufoff) + ldsw + _i * 8192), 16, 0, 0); } while (0)
; #define PG8_LDA(dst, b, h) do { _Pragma("unroll") for (int m = 0; m < 4; ++m) _Pragma("unroll") for (int k = 0; k < 2; ++k) dst[m][k] = *(const PG8_LAS bf16x8*)(lds + PG8_SA(b, h) + aoff + m * 2048 + k * 1024); } while (0)
; #define PG8_LDB(dst, b, h) do { _Pragma("unroll") for (int n = 0; n < 2; ++n) _Pragma("unroll") for (int k = 0; k < 2; ++k) dst[n][k] = *(const PG8_LAS bf16x8*)(lds + PG8_SB(b, h) + boff + n * 2048 + k * 1024); } while (0)
; #define PG8_WAIT_V(n) asm volatile("s_waitcnt vmcnt(" #n ")" ::: "memory")
; #define PG8_WAIT_L(n) asm volatile("s_waitcnt lgkmcnt(" #n ")" ::: "memory")
; #define PG8_BAR __builtin_amdgcn_s_barrier()
; template <class Epi, class Sched, bool ALIGN_EPI = false, bool SP2 = false>
; __device__ __forceinline__ void gemm_phase(PG8_LAS unsigned char* lds, const Gemm g, const Sched& S, const Epi& E) {
;     ...
;     for (;;) {
;         const bool has_next = S.next(ui + 1, nxt);
;         const char* nA = has_next ? (const char*)g.A + (size_t)nxt.pm * tstep : cA; const char* nB = has_next ? (const char*)g.Bt + (size_t)nxt.pn * tstep : cB;
;         asm volatile(".p2align 8");
;         for (int t = 0; t < nt; t += 2) {
;             const bool last = (t == nt - 2);
;             const char* a1 = cA + (size_t)(t + 1) * kstep;
;             const char* a2 = last ? nA : cA + (size_t)(t + 2) * kstep; const char* b2 = last ? nB : cB + (size_t)(t + 2) * kstep;
;             const char* a3 = a2 + kstep; const char* b3 = b2 + kstep;
;             if (last && has_next) S.a_ready(nxt);
;             if constexpr (SP2) {
;             PG8_LDB(B0, 0, 0); PG8_LDB(B1, 0, 1); PG8_SCHED; PG8_LDA(At, 0, 0); PG8_STAGE(PG8_SA(1, 1), a1 + hstep, voffA);
;             PG8_WAIT_V(8); PG8_WAIT_L(0); PG8_BAR; PG8_MMA(0, 0, At, B0); PG8_MMA(0, 1, At, B1); PG8_BAR; PG8_SCHED;
;             PG8_LDA(At, 0, 1); PG8_STAGE(PG8_SB(0, 0), b2, voffB); PG8_STAGE(PG8_SB(0, 1), b2 + hstep, voffB); PG8_STAGE(PG8_SA(0, 0), a2, voffA);
.LBB0_1012:
	s_andn2_b64 vcc, exec, s[18:19]
	s_waitcnt vmcnt(0)
	.p2align 8
	s_cbranch_vccnz .Lpz_k1014
	s_add_u32 s36, s36, 0x80
	s_addc_u32 s37, s37, 0
	s_add_u32 s33, s38, 0x100
	s_addc_u32 s70, s39, 0
	s_mov_b32 s38, 0
.Lpeel_k1014:
	ds_read_b128 v[146:149], v167
	ds_read_b128 v[150:153], v167 offset:1024
	ds_read_b128 v[154:157], v167 offset:2048
	ds_read_b128 v[158:161], v167 offset:3072
	ds_read_b128 v[172:175], v168
	ds_read_b128 v[176:179], v168 offset:1024
	ds_read_b128 v[180:183], v168 offset:2048
	ds_read_b128 v[184:187], v168 offset:3072
	s_add_i32 s71, s38, 2
	s_add_u32 s72, s36, 0x80
	s_addc_u32 s39, s37, 0
	s_cmp_eq_u32 s62, s38
	s_cselect_b32 s38, s6, s72
	s_cselect_b32 s39, s7, s39
	s_cselect_b32 s73, s23, s70
	s_cselect_b32 s72, s22, s33
	v_lshl_add_u64 v[162:163], s[36:37], 0, v[138:139]
	s_add_i32 m0, s48, 0xc000
	ds_read_b128 v[188:191], v169
	ds_read_b128 v[194:197], v169 offset:1024
	ds_read_b128 v[198:201], v169 offset:2048
	ds_read_b128 v[202:205], v169 offset:3072
	ds_read_b128 v[206:209], v169 offset:4096
	ds_read_b128 v[210:213], v169 offset:5120
	ds_read_b128 v[214:217], v169 offset:6144
	ds_read_b128 v[218:221], v169 offset:7168
	global_load_lds_dwordx4 v[162:163], off
	v_lshl_add_u64 v[162:163], s[36:37], 0, v[140:141]
	s_add_i32 m0, s48, 0xe000
	s_nop 0
	global_load_lds_dwordx4 v[162:163], off
	s_waitcnt vmcnt(8)
	s_waitcnt lgkmcnt(0)
	s_barrier
	s_setprio 1
	s_waitcnt lgkmcnt(0)
	v_mfma_f32_16x16x32_bf16 v[120:123], v[146:149], v[188:191], 0
	v_mfma_f32_16x16x32_bf16 v[116:119], v[154:157], v[188:191], 0
	v_mfma_f32_16x16x32_bf16 v[108:111], v[146:149], v[198:201], 0
	v_mfma_f32_16x16x32_bf16 v[100:103], v[154:157], v[198:201], 0
	v_mfma_f32_16x16x32_bf16 v[92:95], v[146:149], v[206:209], 0
	v_mfma_f32_16x16x32_bf16 v[84:87], v[154:157], v[206:209], 0
	v_mfma_f32_16x16x32_bf16 v[76:79], v[146:149], v[214:217], 0
	v_mfma_f32_16x16x32_bf16 v[68:71], v[154:157], v[214:217], 0
	v_mfma_f32_16x16x32_bf16 v[120:123], v[150:153], v[194:197], v[120:123]
	v_mfma_f32_16x16x32_bf16 v[116:119], v[158:161], v[194:197], v[116:119]
	v_mfma_f32_16x16x32_bf16 v[108:111], v[150:153], v[202:205], v[108:111]
	v_mfma_f32_16x16x32_bf16 v[100:103], v[158:161], v[202:205], v[100:103]
	v_mfma_f32_16x16x32_bf16 v[92:95], v[150:153], v[210:213], v[92:95]
	v_mfma_f32_16x16x32_bf16 v[84:87], v[158:161], v[210:213], v[84:87]
	v_mfma_f32_16x16x32_bf16 v[76:79], v[150:153], v[218:221], v[76:79]
	v_mfma_f32_16x16x32_bf16 v[68:71], v[158:161], v[218:221], v[68:71]
	s_setprio 0
	s_setprio 1
	v_mfma_f32_16x16x32_bf16 v[124:127], v[172:175], v[188:191], 0
	v_mfma_f32_16x16x32_bf16 v[112:115], v[180:183], v[188:191], 0
	v_mfma_f32_16x16x32_bf16 v[104:107], v[172:175], v[198:201], 0
	v_mfma_f32_16x16x32_bf16 v[96:99], v[180:183], v[198:201], 0
	v_mfma_f32_16x16x32_bf16 v[88:91], v[172:175], v[206:209], 0
	v_mfma_f32_16x16x32_bf16 v[80:83], v[180:183], v[206:209], 0
	v_mfma_f32_16x16x32_bf16 v[72:75], v[172:175], v[214:217], 0
	v_mfma_f32_16x16x32_bf16 v[64:67], v[180:183], v[214:217], 0
	v_mfma_f32_16x16x32_bf16 v[124:127], v[176:179], v[194:197], v[124:127]
	v_mfma_f32_16x16x32_bf16 v[112:115], v[184:187], v[194:197], v[112:115]
	v_mfma_f32_16x16x32_bf16 v[104:107], v[176:179], v[202:205], v[104:107]
	v_mfma_f32_16x16x32_bf16 v[96:99], v[184:187], v[202:205], v[96:99]
	v_mfma_f32_16x16x32_bf16 v[88:91], v[176:179], v[210:213], v[88:91]
	v_mfma_f32_16x16x32_bf16 v[80:83], v[184:187], v[210:213], v[80:83]
	v_mfma_f32_16x16x32_bf16 v[72:75], v[176:179], v[218:221], v[72:75]
	v_mfma_f32_16x16x32_bf16 v[64:67], v[184:187], v[218:221], v[64:67]
	s_setprio 0
	s_barrier
	s_add_i32 s74, s65, s41
	v_lshl_add_u64 v[162:163], s[72:73], 0, v[132:133]
	s_mov_b32 m0, s74
	ds_read_b128 v[188:191], v169 offset:16384
	ds_read_b128 v[194:197], v169 offset:17408
	ds_read_b128 v[198:201], v169 offset:18432
	ds_read_b128 v[202:205], v169 offset:19456
	ds_read_b128 v[206:209], v169 offset:20480
	ds_read_b128 v[210:213], v169 offset:21504
	ds_read_b128 v[214:217], v169 offset:22528
	ds_read_b128 v[218:221], v169 offset:23552
	global_load_lds_dwordx4 v[162:163], off
	s_add_i32 m0, s74, 0x2000
	v_lshl_add_u64 v[222:223], s[72:73], 0, v[128:129]
	s_add_u32 s72, s72, s10
	s_addc_u32 s73, s73, s11
	s_add_i32 s74, s66, s41
	global_load_lds_dwordx4 v[222:223], off
	v_lshl_add_u64 v[224:225], s[72:73], 0, v[132:133]
	s_mov_b32 m0, s74
	v_lshl_add_u64 v[226:227], s[72:73], 0, v[128:129]
	global_load_lds_dwordx4 v[224:225], off
	s_add_i32 m0, s74, 0x2000
	v_lshl_add_u64 v[228:229], s[38:39], 0, v[134:135]
	global_load_lds_dwordx4 v[226:227], off
	s_mov_b32 m0, s48
	v_lshl_add_u64 v[230:231], s[38:39], 0, v[130:131]
	global_load_lds_dwordx4 v[228:229], off
	s_mov_b32 m0, s49
	s_nop 0
	global_load_lds_dwordx4 v[230:231], off
	s_cmp_lg_u32 s71, 2
	s_cbranch_scc1 .Lss_p6_skip_pl
	s_lshl_b32 s84, s4, 14
	s_mov_b32 s85, 0
	s_add_i32 m0, s48, 0x20000
	v_lshl_add_u64 v[238:239], v[236:237], 0, s[84:85]
	s_add_u32 s84, s84, 0x2000
	global_load_lds_dwordx4 v[238:239], off
	s_add_i32 m0, s48, 0x22000
	v_lshl_add_u64 v[238:239], v[236:237], 0, s[84:85]
	global_load_lds_dwordx4 v[238:239], off
; #define PG8_STAGE(bufoff, gbase, voff) do { _Pragma("unroll") for (int _i = 0; _i < 2; ++_i) \
;         __builtin_amdgcn_global_load_lds((const unsigned*)((const char*)(gbase) + (voff)[_i]), (PG8_LAS unsigned*)(lds + (bufoff) + ldsw + _i * 8192), 16, 0, 0); } while (0)
; #define PG8_LDA(dst, b, h) do { _Pragma("unroll") for (int m = 0; m < 4; ++m) _Pragma("unroll") for (int k = 0; k < 2; ++k) dst[m][k] = *(const PG8_LAS bf16x8*)(lds + PG8_SA(b, h) + aoff + m * 2048 + k * 1024); } while (0)
; #define PG8_LDB(dst, b, h) do { _Pragma("unroll") for (int n = 0; n < 2; ++n) _Pragma("unroll") for (int k = 0; k < 2; ++k) dst[n][k] = *(const PG8_LAS bf16x8*)(lds + PG8_SB(b, h) + boff + n * 2048 + k * 1024); } while (0)
; #define PG8_MMA(ai, bj, At, Bt) do { __builtin_amdgcn_s_setprio(1); _Pragma("unroll") for (int m = 0; m < 4; ++m) _Pragma("unroll") for (int n = 0; n < 2; ++n) _Pragma("unroll") for (int k = 0; k < 2; ++k) \
;         acc[ai][bj][m][n] = __builtin_amdgcn_mfma_f32_16x16x32_bf16(Bt[n][k], At[m][k], acc[ai][bj][m][n], 0, 0, 0); __builtin_amdgcn_s_setprio(0); } while (0)
; #define PG8_WAIT_V(n) asm volatile("s_waitcnt vmcnt(" #n ")" ::: "memory")
; #define PG8_WAIT_L(n) asm volatile("s_waitcnt lgkmcnt(" #n ")" ::: "memory")
; #define PG8_BAR __builtin_amdgcn_s_barrier()
; #define PG8_SCHED __builtin_amdgcn_sched_barrier(0)
; template <class Epi, class Sched, bool ALIGN_EPI = false, bool SP2 = false>
; __device__ __forceinline__ void gemm_phase(PG8_LAS unsigned char* lds, const Gemm g, const Sched& S, const Epi& E) {
;     ...
;             PG8_WAIT_V(8); PG8_WAIT_L(0); PG8_BAR; PG8_MMA(1, 0, At, B0); PG8_MMA(1, 1, At, B1); PG8_BAR; PG8_SCHED;
;             PG8_LDB(B0, 1, 0); PG8_LDB(B1, 1, 1); PG8_SCHED; PG8_LDA(At, 1, 0); PG8_STAGE(PG8_SA(0, 1), a2 + hstep, voffA);
;             PG8_WAIT_V(8); PG8_WAIT_L(0); PG8_BAR; PG8_MMA(0, 0, At, B0); PG8_MMA(0, 1, At, B1); PG8_BAR; PG8_SCHED;
.Lss_p6_skip_pl:
	s_waitcnt vmcnt(8)
	s_waitcnt lgkmcnt(0)
	s_barrier
	s_setprio 1
	s_waitcnt lgkmcnt(0)
	v_mfma_f32_16x16x32_bf16 v[60:63], v[146:149], v[188:191], 0
	v_mfma_f32_16x16x32_bf16 v[52:55], v[154:157], v[188:191], 0
	v_mfma_f32_16x16x32_bf16 v[44:47], v[146:149], v[198:201], 0
	v_mfma_f32_16x16x32_bf16 v[36:39], v[154:157], v[198:201], 0
	v_mfma_f32_16x16x32_bf16 v[28:31], v[146:149], v[206:209], 0
	v_mfma_f32_16x16x32_bf16 v[20:23], v[154:157], v[206:209], 0
	v_mfma_f32_16x16x32_bf16 v[12:15], v[146:149], v[214:217], 0
	v_mfma_f32_16x16x32_bf16 v[4:7], v[154:157], v[214:217], 0
	v_mfma_f32_16x16x32_bf16 v[60:63], v[150:153], v[194:197], v[60:63]
	v_mfma_f32_16x16x32_bf16 v[52:55], v[158:161], v[194:197], v[52:55]
	v_mfma_f32_16x16x32_bf16 v[44:47], v[150:153], v[202:205], v[44:47]
	v_mfma_f32_16x16x32_bf16 v[36:39], v[158:161], v[202:205], v[36:39]
	v_mfma_f32_16x16x32_bf16 v[28:31], v[150:153], v[210:213], v[28:31]
	v_mfma_f32_16x16x32_bf16 v[20:23], v[158:161], v[210:213], v[20:23]
	v_mfma_f32_16x16x32_bf16 v[12:15], v[150:153], v[218:221], v[12:15]
	v_mfma_f32_16x16x32_bf16 v[4:7], v[158:161], v[218:221], v[4:7]
	s_setprio 0
	s_setprio 1
	v_mfma_f32_16x16x32_bf16 v[56:59], v[172:175], v[188:191], 0
	v_mfma_f32_16x16x32_bf16 v[48:51], v[180:183], v[188:191], 0
	v_mfma_f32_16x16x32_bf16 v[40:43], v[172:175], v[198:201], 0
	v_mfma_f32_16x16x32_bf16 v[32:35], v[180:183], v[198:201], 0
	v_mfma_f32_16x16x32_bf16 v[24:27], v[172:175], v[206:209], 0
	v_mfma_f32_16x16x32_bf16 v[16:19], v[180:183], v[206:209], 0
	v_mfma_f32_16x16x32_bf16 v[8:11], v[172:175], v[214:217], 0
	v_mfma_f32_16x16x32_bf16 v[0:3], v[180:183], v[214:217], 0
	v_mfma_f32_16x16x32_bf16 v[56:59], v[176:179], v[194:197], v[56:59]
	v_mfma_f32_16x16x32_bf16 v[48:51], v[184:187], v[194:197], v[48:51]
	v_mfma_f32_16x16x32_bf16 v[40:43], v[176:179], v[202:205], v[40:43]
	v_mfma_f32_16x16x32_bf16 v[32:35], v[184:187], v[202:205], v[32:35]
	v_mfma_f32_16x16x32_bf16 v[24:27], v[176:179], v[210:213], v[24:27]
	v_mfma_f32_16x16x32_bf16 v[16:19], v[184:187], v[210:213], v[16:19]
	v_mfma_f32_16x16x32_bf16 v[8:11], v[176:179], v[218:221], v[8:11]
	v_mfma_f32_16x16x32_bf16 v[0:3], v[184:187], v[218:221], v[0:3]
	s_setprio 0
	s_barrier
	s_add_i32 s72, 0, 0x18000
	s_add_i32 s73, 0, 0x1c000
	v_add_u32_e32 v158, s72, v165
	v_add_u32_e32 v184, s73, v165
	ds_read_b128 v[146:149], v158
	ds_read_b128 v[150:153], v158 offset:1024
	ds_read_b128 v[154:157], v158 offset:2048
	ds_read_b128 v[158:161], v158 offset:3072
	ds_read_b128 v[172:175], v184
	ds_read_b128 v[176:179], v184 offset:1024
	ds_read_b128 v[180:183], v184 offset:2048
	ds_read_b128 v[184:187], v184 offset:3072
	s_add_u32 s38, s38, s10
	s_addc_u32 s39, s39, s11
	s_mov_b32 m0, s56
	v_lshl_add_u64 v[232:233], s[38:39], 0, v[134:135]
	ds_read_b128 v[188:191], v169 offset:32768
	ds_read_b128 v[194:197], v169 offset:33792
	ds_read_b128 v[198:201], v169 offset:34816
	ds_read_b128 v[202:205], v169 offset:35840
	ds_read_b128 v[206:209], v169 offset:36864
	ds_read_b128 v[210:213], v169 offset:37888
	ds_read_b128 v[214:217], v169 offset:38912
	ds_read_b128 v[218:221], v169 offset:39936
	global_load_lds_dwordx4 v[232:233], off
	v_lshl_add_u64 v[232:233], s[38:39], 0, v[130:131]
	s_mov_b32 m0, s57
	s_nop 0
	global_load_lds_dwordx4 v[232:233], off
	s_waitcnt vmcnt(8)
	s_waitcnt lgkmcnt(0)
	s_barrier
	s_setprio 1
	s_waitcnt lgkmcnt(0)
	v_mfma_f32_16x16x32_bf16 v[120:123], v[146:149], v[188:191], v[120:123]
	v_mfma_f32_16x16x32_bf16 v[116:119], v[154:157], v[188:191], v[116:119]
	v_mfma_f32_16x16x32_bf16 v[108:111], v[146:149], v[198:201], v[108:111]
	v_mfma_f32_16x16x32_bf16 v[100:103], v[154:157], v[198:201], v[100:103]
	v_mfma_f32_16x16x32_bf16 v[92:95], v[146:149], v[206:209], v[92:95]
	v_mfma_f32_16x16x32_bf16 v[84:87], v[154:157], v[206:209], v[84:87]
	v_mfma_f32_16x16x32_bf16 v[76:79], v[146:149], v[214:217], v[76:79]
	v_mfma_f32_16x16x32_bf16 v[68:71], v[154:157], v[214:217], v[68:71]
	v_mfma_f32_16x16x32_bf16 v[120:123], v[150:153], v[194:197], v[120:123]
	v_mfma_f32_16x16x32_bf16 v[116:119], v[158:161], v[194:197], v[116:119]
	v_mfma_f32_16x16x32_bf16 v[108:111], v[150:153], v[202:205], v[108:111]
	v_mfma_f32_16x16x32_bf16 v[100:103], v[158:161], v[202:205], v[100:103]
	v_mfma_f32_16x16x32_bf16 v[92:95], v[150:153], v[210:213], v[92:95]
	v_mfma_f32_16x16x32_bf16 v[84:87], v[158:161], v[210:213], v[84:87]
	v_mfma_f32_16x16x32_bf16 v[76:79], v[150:153], v[218:221], v[76:79]
	v_mfma_f32_16x16x32_bf16 v[68:71], v[158:161], v[218:221], v[68:71]
	s_setprio 0
	s_setprio 1
	v_mfma_f32_16x16x32_bf16 v[124:127], v[172:175], v[188:191], v[124:127]
	v_mfma_f32_16x16x32_bf16 v[112:115], v[180:183], v[188:191], v[112:115]
	v_mfma_f32_16x16x32_bf16 v[104:107], v[172:175], v[198:201], v[104:107]
	v_mfma_f32_16x16x32_bf16 v[96:99], v[180:183], v[198:201], v[96:99]
	v_mfma_f32_16x16x32_bf16 v[88:91], v[172:175], v[206:209], v[88:91]
	v_mfma_f32_16x16x32_bf16 v[80:83], v[180:183], v[206:209], v[80:83]
	v_mfma_f32_16x16x32_bf16 v[72:75], v[172:175], v[214:217], v[72:75]
	v_mfma_f32_16x16x32_bf16 v[64:67], v[180:183], v[214:217], v[64:67]
	v_mfma_f32_16x16x32_bf16 v[124:127], v[176:179], v[194:197], v[124:127]
	v_mfma_f32_16x16x32_bf16 v[112:115], v[184:187], v[194:197], v[112:115]
	v_mfma_f32_16x16x32_bf16 v[104:107], v[176:179], v[202:205], v[104:107]
	v_mfma_f32_16x16x32_bf16 v[96:99], v[184:187], v[202:205], v[96:99]
	v_mfma_f32_16x16x32_bf16 v[88:91], v[176:179], v[210:213], v[88:91]
	v_mfma_f32_16x16x32_bf16 v[80:83], v[184:187], v[210:213], v[80:83]
	v_mfma_f32_16x16x32_bf16 v[72:75], v[176:179], v[218:221], v[72:75]
	v_mfma_f32_16x16x32_bf16 v[64:67], v[184:187], v[218:221], v[64:67]
	s_setprio 0
	s_barrier
; #define PG8_STAGE(bufoff, gbase, voff) do { _Pragma("unroll") for (int _i = 0; _i < 2; ++_i) \
;         __builtin_amdgcn_global_load_lds((const unsigned*)((const char*)(gbase) + (voff)[_i]), (PG8_LAS unsigned*)(lds + (bufoff) + ldsw + _i * 8192), 16, 0, 0); } while (0)
; #define PG8_LDA(dst, b, h) do { _Pragma("unroll") for (int m = 0; m < 4; ++m) _Pragma("unroll") for (int k = 0; k < 2; ++k) dst[m][k] = *(const PG8_LAS bf16x8*)(lds + PG8_SA(b, h) + aoff + m * 2048 + k * 1024); } while (0)
; #define PG8_MMA(ai, bj, At, Bt) do { __builtin_amdgcn_s_setprio(1); _Pragma("unroll") for (int m = 0; m < 4; ++m) _Pragma("unroll") for (int n = 0; n < 2; ++n) _Pragma("unroll") for (int k = 0; k < 2; ++k) \
;         acc[ai][bj][m][n] = __builtin_amdgcn_mfma_f32_16x16x32_bf16(Bt[n][k], At[m][k], acc[ai][bj][m][n], 0, 0, 0); __builtin_amdgcn_s_setprio(0); } while (0)
; #define PG8_WAIT_V(n) asm volatile("s_waitcnt vmcnt(" #n ")" ::: "memory")
; #define PG8_WAIT_L(n) asm volatile("s_waitcnt lgkmcnt(" #n ")" ::: "memory")
; #define PG8_BAR __builtin_amdgcn_s_barrier()
; #define PG8_SCHED __builtin_amdgcn_sched_barrier(0)
; template <class Epi, class Sched, bool ALIGN_EPI = false, bool SP2 = false>
; __device__ __forceinline__ void gemm_phase(PG8_LAS unsigned char* lds, const Gemm g, const Sched& S, const Epi& E) {
;     ...
;             PG8_LDA(At, 1, 1); PG8_STAGE(PG8_SB(1, 0), b3, voffB); PG8_STAGE(PG8_SB(1, 1), b3 + hstep, voffB); PG8_STAGE(PG8_SA(1, 0), a3, voffA);
;             PG8_WAIT_V(8); PG8_WAIT_L(0); PG8_BAR; PG8_MMA(1, 0, At, B0); PG8_MMA(1, 1, At, B1); PG8_BAR; PG8_SCHED;
	s_add_i32 s38, s72, s41
	v_lshl_add_u64 v[162:163], v[162:163], 0, s[16:17]
	s_mov_b32 m0, s38
	ds_read_b128 v[188:191], v169 offset:49152
	ds_read_b128 v[194:197], v169 offset:50176
	ds_read_b128 v[198:201], v169 offset:51200
	ds_read_b128 v[202:205], v169 offset:52224
	ds_read_b128 v[206:209], v169 offset:53248
	ds_read_b128 v[210:213], v169 offset:54272
	ds_read_b128 v[214:217], v169 offset:55296
	ds_read_b128 v[218:221], v169 offset:56320
	global_load_lds_dwordx4 v[162:163], off
	v_lshl_add_u64 v[162:163], v[222:223], 0, s[16:17]
	s_add_i32 m0, s38, 0x2000
	s_add_i32 s38, s73, s41
	global_load_lds_dwordx4 v[162:163], off
	v_lshl_add_u64 v[162:163], v[224:225], 0, s[16:17]
	s_mov_b32 m0, s38
	s_nop 0
	global_load_lds_dwordx4 v[162:163], off
	v_lshl_add_u64 v[162:163], v[226:227], 0, s[16:17]
	s_add_i32 m0, s38, 0x2000
	s_nop 0
	global_load_lds_dwordx4 v[162:163], off
	v_lshl_add_u64 v[162:163], v[228:229], 0, s[16:17]
	s_mov_b32 m0, s59
	s_nop 0
	global_load_lds_dwordx4 v[162:163], off
	v_lshl_add_u64 v[162:163], v[230:231], 0, s[16:17]
	s_mov_b32 m0, s60
	s_nop 0
	global_load_lds_dwordx4 v[162:163], off
	s_waitcnt vmcnt(8)
	s_waitcnt lgkmcnt(0)
	s_barrier
	s_setprio 1
	s_waitcnt lgkmcnt(0)
	v_mfma_f32_16x16x32_bf16 v[60:63], v[146:149], v[188:191], v[60:63]
	v_mfma_f32_16x16x32_bf16 v[52:55], v[154:157], v[188:191], v[52:55]
	v_mfma_f32_16x16x32_bf16 v[44:47], v[146:149], v[198:201], v[44:47]
	v_mfma_f32_16x16x32_bf16 v[36:39], v[154:157], v[198:201], v[36:39]
	v_mfma_f32_16x16x32_bf16 v[28:31], v[146:149], v[206:209], v[28:31]
	v_mfma_f32_16x16x32_bf16 v[20:23], v[154:157], v[206:209], v[20:23]
	v_mfma_f32_16x16x32_bf16 v[12:15], v[146:149], v[214:217], v[12:15]
	v_mfma_f32_16x16x32_bf16 v[4:7], v[154:157], v[214:217], v[4:7]
	v_mfma_f32_16x16x32_bf16 v[60:63], v[150:153], v[194:197], v[60:63]
	v_mfma_f32_16x16x32_bf16 v[52:55], v[158:161], v[194:197], v[52:55]
	v_mfma_f32_16x16x32_bf16 v[44:47], v[150:153], v[202:205], v[44:47]
	v_mfma_f32_16x16x32_bf16 v[36:39], v[158:161], v[202:205], v[36:39]
	v_mfma_f32_16x16x32_bf16 v[28:31], v[150:153], v[210:213], v[28:31]
	v_mfma_f32_16x16x32_bf16 v[20:23], v[158:161], v[210:213], v[20:23]
	v_mfma_f32_16x16x32_bf16 v[12:15], v[150:153], v[218:221], v[12:15]
	v_mfma_f32_16x16x32_bf16 v[4:7], v[158:161], v[218:221], v[4:7]
	s_setprio 0
	s_setprio 1
	v_mfma_f32_16x16x32_bf16 v[56:59], v[172:175], v[188:191], v[56:59]
	v_mfma_f32_16x16x32_bf16 v[48:51], v[180:183], v[188:191], v[48:51]
	v_mfma_f32_16x16x32_bf16 v[40:43], v[172:175], v[198:201], v[40:43]
	v_mfma_f32_16x16x32_bf16 v[32:35], v[180:183], v[198:201], v[32:35]
	v_mfma_f32_16x16x32_bf16 v[24:27], v[172:175], v[206:209], v[24:27]
	v_mfma_f32_16x16x32_bf16 v[16:19], v[180:183], v[206:209], v[16:19]
	v_mfma_f32_16x16x32_bf16 v[8:11], v[172:175], v[214:217], v[8:11]
	v_mfma_f32_16x16x32_bf16 v[0:3], v[180:183], v[214:217], v[0:3]
	v_mfma_f32_16x16x32_bf16 v[56:59], v[176:179], v[194:197], v[56:59]
	v_mfma_f32_16x16x32_bf16 v[48:51], v[184:187], v[194:197], v[48:51]
	v_mfma_f32_16x16x32_bf16 v[40:43], v[176:179], v[202:205], v[40:43]
	v_mfma_f32_16x16x32_bf16 v[32:35], v[184:187], v[202:205], v[32:35]
	v_mfma_f32_16x16x32_bf16 v[24:27], v[176:179], v[210:213], v[24:27]
	v_mfma_f32_16x16x32_bf16 v[16:19], v[184:187], v[210:213], v[16:19]
	v_mfma_f32_16x16x32_bf16 v[8:11], v[176:179], v[218:221], v[8:11]
	v_mfma_f32_16x16x32_bf16 v[0:3], v[184:187], v[218:221], v[0:3]
	s_setprio 0
	s_barrier
	s_add_u32 s36, s36, 0x100
	s_addc_u32 s37, s37, 0
	s_add_u32 s33, s33, 0x100
	s_addc_u32 s70, s70, 0
	s_cmp_ge_i32 s71, s61
	s_mov_b32 s38, s71
	s_cbranch_scc0 .LBB0_1014
	s_branch .Lpx_k1014

; #define PG8_BAR __builtin_amdgcn_s_barrier()
; template <class Epi, class Sched, bool ALIGN_EPI = false, bool SP2 = false>
; __device__ __forceinline__ void gemm_phase(PG8_LAS unsigned char* lds, const Gemm g, const Sched& S, const Epi& E) {
;     ...
;         if constexpr (ALIGN_EPI) { if (wr == 0) PG8_BAR; }
.Lpx_k1014:
.LBB0_1015:
	s_and_b64 vcc, exec, s[20:21]
	s_cbranch_vccz .LBB0_1017
	s_barrier

;     __host__ __device__ bool next(int i, Unit& u) const { const int idx = first + i; if (idx >= last) return false; u.pm = idx >> 2; u.pn = idx & 3; return true; }
; #define PG8_STAGE(bufoff, gbase, voff) do { _Pragma("unroll") for (int _i = 0; _i < 2; ++_i) \
;         __builtin_amdgcn_global_load_lds((const unsigned*)((const char*)(gbase) + (voff)[_i]), (PG8_LAS unsigned*)(lds + (bufoff) + ldsw + _i * 8192), 16, 0, 0); } while (0)
; #define PG8_LDA(dst, b, h) do { _Pragma("unroll") for (int m = 0; m < 4; ++m) _Pragma("unroll") for (int k = 0; k < 2; ++k) dst[m][k] = *(const PG8_LAS bf16x8*)(lds + PG8_SA(b, h) + aoff + m * 2048 + k * 1024); } while (0)
; #define PG8_LDB(dst, b, h) do { _Pragma("unroll") for (int n = 0; n < 2; ++n) _Pragma("unroll") for (int k = 0; k < 2; ++k) dst[n][k] = *(const PG8_LAS bf16x8*)(lds + PG8_SB(b, h) + boff + n * 2048 + k * 1024); } while (0)
; #define PG8_BAR __builtin_amdgcn_s_barrier()
; template <class Epi, class Sched, bool ALIGN_EPI = false, bool SP2 = false>
; __device__ __forceinline__ void gemm_phase(PG8_LAS unsigned char* lds, const Gemm g, const Sched& S, const Epi& E) {
;     ...
;     f32x4 acc[2][2][4][2];
; #pragma unroll
;     for (int a = 0; a < 2; ++a)
; #pragma unroll
;         for (int b = 0; b < 2; ++b)
; #pragma unroll
;             for (int m = 0; m < 4; ++m)
; #pragma unroll
;                 for (int n = 0; n < 2; ++n) acc[a][b][m][n] = (f32x4){0.f, 0.f, 0.f, 0.f};
;     ...
;     for (;;) {
;         const bool has_next = S.next(ui + 1, nxt);
;         const char* nA = has_next ? (const char*)g.A + (size_t)nxt.pm * tstep : cA; const char* nB = has_next ? (const char*)g.Bt + (size_t)nxt.pn * tstep : cB;
;         asm volatile(".p2align 8");
;         for (int t = 0; t < nt; t += 2) {
;             const bool last = (t == nt - 2);
;             const char* a1 = cA + (size_t)(t + 1) * kstep;
;             const char* a2 = last ? nA : cA + (size_t)(t + 2) * kstep; const char* b2 = last ? nB : cB + (size_t)(t + 2) * kstep;
;             const char* a3 = a2 + kstep; const char* b3 = b2 + kstep;
;             if (last && has_next) S.a_ready(nxt);
;             if constexpr (SP2) {
;             PG8_LDB(B0, 0, 0); PG8_LDB(B1, 0, 1); PG8_SCHED; PG8_LDA(At, 0, 0); PG8_STAGE(PG8_SA(1, 1), a1 + hstep, voffA);
;             PG8_WAIT_V(8); PG8_WAIT_L(0); PG8_BAR; PG8_MMA(0, 0, At, B0); PG8_MMA(0, 1, At, B1); PG8_BAR; PG8_SCHED;
.LBB0_1116:
	v_mov_b64_e32 v[64:65], 0
	v_mov_b64_e32 v[66:67], 0
	v_mov_b64_e32 v[68:69], 0
	v_mov_b64_e32 v[70:71], 0
	v_mov_b64_e32 v[72:73], 0
	v_mov_b64_e32 v[74:75], 0
	v_mov_b64_e32 v[76:77], 0
	v_mov_b64_e32 v[78:79], 0
	v_mov_b64_e32 v[80:81], 0
	v_mov_b64_e32 v[82:83], 0
	v_mov_b64_e32 v[84:85], 0
	v_mov_b64_e32 v[86:87], 0
	v_mov_b64_e32 v[88:89], 0
	v_mov_b64_e32 v[90:91], 0
	v_mov_b64_e32 v[92:93], 0
	v_mov_b64_e32 v[94:95], 0
	v_mov_b64_e32 v[96:97], 0
	v_mov_b64_e32 v[98:99], 0
	v_mov_b64_e32 v[100:101], 0
	v_mov_b64_e32 v[102:103], 0
	v_mov_b64_e32 v[104:105], 0
	v_mov_b64_e32 v[106:107], 0
	v_mov_b64_e32 v[108:109], 0
	v_mov_b64_e32 v[110:111], 0
	v_mov_b64_e32 v[112:113], 0
	v_mov_b64_e32 v[114:115], 0
	v_mov_b64_e32 v[116:117], 0
	v_mov_b64_e32 v[118:119], 0
	v_mov_b64_e32 v[120:121], 0
	v_mov_b64_e32 v[122:123], 0
	v_mov_b64_e32 v[124:125], 0
	v_mov_b64_e32 v[126:127], 0
	v_mov_b64_e32 v[142:143], 0
	v_mov_b64_e32 v[144:145], 0
	v_mov_b64_e32 v[146:147], 0
	v_mov_b64_e32 v[148:149], 0
	v_mov_b64_e32 v[152:153], 0
	v_mov_b64_e32 v[154:155], 0
	v_mov_b64_e32 v[156:157], 0
	v_mov_b64_e32 v[158:159], 0
	v_mov_b64_e32 v[162:163], 0
	v_mov_b64_e32 v[164:165], 0
	v_mov_b64_e32 v[166:167], 0
	v_mov_b64_e32 v[168:169], 0
	v_mov_b64_e32 v[170:171], 0
	v_mov_b64_e32 v[172:173], 0
	v_mov_b64_e32 v[174:175], 0
	v_mov_b64_e32 v[176:177], 0
	v_mov_b64_e32 v[182:183], 0
	v_mov_b64_e32 v[184:185], 0
	v_mov_b64_e32 v[186:187], 0
	v_mov_b64_e32 v[188:189], 0
	v_mov_b64_e32 v[190:191], 0
	v_mov_b64_e32 v[194:195], 0
	v_mov_b64_e32 v[196:197], 0
	v_mov_b64_e32 v[198:199], 0
	v_mov_b64_e32 v[206:207], 0
	v_mov_b64_e32 v[210:211], 0
	v_mov_b64_e32 v[212:213], 0
	v_mov_b64_e32 v[214:215], 0
	v_mov_b64_e32 v[220:221], 0
	v_mov_b64_e32 v[222:223], 0
	v_mov_b64_e32 v[224:225], 0
	v_mov_b64_e32 v[226:227], 0
	s_andn2_b64 vcc, exec, s[36:37]
	.p2align 8
	s_cbranch_vccnz .LBB0_1120
	s_add_u32 s42, s42, 0x80
	s_addc_u32 s43, s43, 0
	s_add_u32 s4, s54, 0x100
	s_addc_u32 s5, s55, 0
	s_mov_b32 s33, 0
	s_waitcnt vmcnt(0)
.Lpeel_k1118:
	ds_read_b128 v[142:145], v247
	ds_read_b128 v[146:149], v247 offset:1024
	ds_read_b128 v[150:153], v247 offset:2048
	ds_read_b128 v[154:157], v247 offset:3072
	ds_read_b128 v[158:161], v248
	ds_read_b128 v[162:165], v248 offset:1024
	ds_read_b128 v[166:169], v248 offset:2048
	ds_read_b128 v[170:173], v248 offset:3072
	s_add_i32 s72, s33, 2
	s_add_u32 s54, s42, 0x80
	s_addc_u32 s55, s43, 0
	s_cmp_eq_u32 s62, s33
	s_cselect_b32 s55, s9, s55
	s_cselect_b32 s54, s8, s54
	s_cselect_b32 s75, s41, s5
	s_cselect_b32 s74, s40, s4
	v_lshl_add_u64 v[190:191], s[42:43], 0, v[136:137]
	s_add_i32 m0, s48, 0xc000
	ds_read_b128 v[174:177], v249
	ds_read_b128 v[178:181], v249 offset:1024
	ds_read_b128 v[182:185], v249 offset:2048
	ds_read_b128 v[186:189], v249 offset:3072
	ds_read_b128 v[194:197], v249 offset:4096
	ds_read_b128 v[198:201], v249 offset:5120
	ds_read_b128 v[202:205], v249 offset:6144
	ds_read_b128 v[206:209], v249 offset:7168
	global_load_lds_dwordx4 v[190:191], off
	v_lshl_add_u64 v[190:191], s[42:43], 0, v[138:139]
	s_add_i32 m0, s48, 0xe000
	s_nop 0
	global_load_lds_dwordx4 v[190:191], off
	s_waitcnt vmcnt(8)
	s_waitcnt lgkmcnt(0)
	s_barrier
	s_setprio 1
	s_waitcnt lgkmcnt(0)
	v_mfma_f32_16x16x32_bf16 v[124:127], v[142:145], v[174:177], 0
	v_mfma_f32_16x16x32_bf16 v[120:123], v[150:153], v[174:177], 0
	v_mfma_f32_16x16x32_bf16 v[116:119], v[142:145], v[182:185], 0
	v_mfma_f32_16x16x32_bf16 v[112:115], v[150:153], v[182:185], 0
	v_mfma_f32_16x16x32_bf16 v[104:107], v[142:145], v[194:197], 0
	v_mfma_f32_16x16x32_bf16 v[96:99], v[150:153], v[194:197], 0
	v_mfma_f32_16x16x32_bf16 v[88:91], v[142:145], v[202:205], 0
	v_mfma_f32_16x16x32_bf16 v[80:83], v[150:153], v[202:205], 0
	v_mfma_f32_16x16x32_bf16 v[124:127], v[146:149], v[178:181], v[124:127]
	v_mfma_f32_16x16x32_bf16 v[120:123], v[154:157], v[178:181], v[120:123]
	v_mfma_f32_16x16x32_bf16 v[116:119], v[146:149], v[186:189], v[116:119]
	v_mfma_f32_16x16x32_bf16 v[112:115], v[154:157], v[186:189], v[112:115]
	v_mfma_f32_16x16x32_bf16 v[104:107], v[146:149], v[198:201], v[104:107]
	v_mfma_f32_16x16x32_bf16 v[96:99], v[154:157], v[198:201], v[96:99]
	v_mfma_f32_16x16x32_bf16 v[88:91], v[146:149], v[206:209], v[88:91]
	v_mfma_f32_16x16x32_bf16 v[80:83], v[154:157], v[206:209], v[80:83]
	s_setprio 0
	s_setprio 1
	v_mfma_f32_16x16x32_bf16 v[108:111], v[158:161], v[174:177], 0
	v_mfma_f32_16x16x32_bf16 v[100:103], v[166:169], v[174:177], 0
	v_mfma_f32_16x16x32_bf16 v[92:95], v[158:161], v[182:185], 0
	v_mfma_f32_16x16x32_bf16 v[84:87], v[166:169], v[182:185], 0
	v_mfma_f32_16x16x32_bf16 v[76:79], v[158:161], v[194:197], 0
	v_mfma_f32_16x16x32_bf16 v[72:75], v[166:169], v[194:197], 0
	v_mfma_f32_16x16x32_bf16 v[68:71], v[158:161], v[202:205], 0
	v_mfma_f32_16x16x32_bf16 v[64:67], v[166:169], v[202:205], 0
	v_mfma_f32_16x16x32_bf16 v[108:111], v[162:165], v[178:181], v[108:111]
	v_mfma_f32_16x16x32_bf16 v[100:103], v[170:173], v[178:181], v[100:103]
	v_mfma_f32_16x16x32_bf16 v[92:95], v[162:165], v[186:189], v[92:95]
	v_mfma_f32_16x16x32_bf16 v[84:87], v[170:173], v[186:189], v[84:87]
	v_mfma_f32_16x16x32_bf16 v[76:79], v[162:165], v[198:201], v[76:79]
	v_mfma_f32_16x16x32_bf16 v[72:75], v[170:173], v[198:201], v[72:75]
	v_mfma_f32_16x16x32_bf16 v[68:71], v[162:165], v[206:209], v[68:71]
	v_mfma_f32_16x16x32_bf16 v[64:67], v[170:173], v[206:209], v[64:67]
	s_setprio 0
	s_barrier
; #define PG8_STAGE(bufoff, gbase, voff) do { _Pragma("unroll") for (int _i = 0; _i < 2; ++_i) \
;         __builtin_amdgcn_global_load_lds((const unsigned*)((const char*)(gbase) + (voff)[_i]), (PG8_LAS unsigned*)(lds + (bufoff) + ldsw + _i * 8192), 16, 0, 0); } while (0)
; #define PG8_LDA(dst, b, h) do { _Pragma("unroll") for (int m = 0; m < 4; ++m) _Pragma("unroll") for (int k = 0; k < 2; ++k) dst[m][k] = *(const PG8_LAS bf16x8*)(lds + PG8_SA(b, h) + aoff + m * 2048 + k * 1024); } while (0)
; #define PG8_LDB(dst, b, h) do { _Pragma("unroll") for (int n = 0; n < 2; ++n) _Pragma("unroll") for (int k = 0; k < 2; ++k) dst[n][k] = *(const PG8_LAS bf16x8*)(lds + PG8_SB(b, h) + boff + n * 2048 + k * 1024); } while (0)
; #define PG8_MMA(ai, bj, At, Bt) do { __builtin_amdgcn_s_setprio(1); _Pragma("unroll") for (int m = 0; m < 4; ++m) _Pragma("unroll") for (int n = 0; n < 2; ++n) _Pragma("unroll") for (int k = 0; k < 2; ++k) \
;         acc[ai][bj][m][n] = __builtin_amdgcn_mfma_f32_16x16x32_bf16(Bt[n][k], At[m][k], acc[ai][bj][m][n], 0, 0, 0); __builtin_amdgcn_s_setprio(0); } while (0)
; #define PG8_WAIT_V(n) asm volatile("s_waitcnt vmcnt(" #n ")" ::: "memory")
; #define PG8_WAIT_L(n) asm volatile("s_waitcnt lgkmcnt(" #n ")" ::: "memory")
; #define PG8_BAR __builtin_amdgcn_s_barrier()
; #define PG8_SCHED __builtin_amdgcn_sched_barrier(0)
; template <class Epi, class Sched, bool ALIGN_EPI = false, bool SP2 = false>
; __device__ __forceinline__ void gemm_phase(PG8_LAS unsigned char* lds, const Gemm g, const Sched& S, const Epi& E) {
;     ...
;             PG8_LDA(At, 0, 1); PG8_STAGE(PG8_SB(0, 0), b2, voffB); PG8_STAGE(PG8_SB(0, 1), b2 + hstep, voffB); PG8_STAGE(PG8_SA(0, 0), a2, voffA);
;             PG8_WAIT_V(8); PG8_WAIT_L(0); PG8_BAR; PG8_MMA(1, 0, At, B0); PG8_MMA(1, 1, At, B1); PG8_BAR; PG8_SCHED;
;             PG8_LDB(B0, 1, 0); PG8_LDB(B1, 1, 1); PG8_SCHED; PG8_LDA(At, 1, 0); PG8_STAGE(PG8_SA(0, 1), a2 + hstep, voffA);
	s_add_i32 s33, s66, s3
	v_lshl_add_u64 v[190:191], s[74:75], 0, v[130:131]
	s_mov_b32 m0, s33
	ds_read_b128 v[174:177], v249 offset:16384
	ds_read_b128 v[178:181], v249 offset:17408
	ds_read_b128 v[182:185], v249 offset:18432
	ds_read_b128 v[186:189], v249 offset:19456
	ds_read_b128 v[194:197], v249 offset:20480
	ds_read_b128 v[198:201], v249 offset:21504
	ds_read_b128 v[202:205], v249 offset:22528
	ds_read_b128 v[206:209], v249 offset:23552
	global_load_lds_dwordx4 v[190:191], off
	s_add_i32 m0, s33, 0x2000
	v_lshl_add_u64 v[210:211], s[74:75], 0, v[134:135]
	s_add_u32 s74, s74, s14
	s_addc_u32 s75, s75, s15
	s_add_i32 s33, s67, s3
	global_load_lds_dwordx4 v[210:211], off
	v_lshl_add_u64 v[212:213], s[74:75], 0, v[130:131]
	s_mov_b32 m0, s33
	v_lshl_add_u64 v[214:215], s[74:75], 0, v[134:135]
	global_load_lds_dwordx4 v[212:213], off
	s_add_i32 m0, s33, 0x2000
	v_lshl_add_u64 v[216:217], s[54:55], 0, v[128:129]
	global_load_lds_dwordx4 v[214:215], off
	s_mov_b32 m0, s48
	v_lshl_add_u64 v[218:219], s[54:55], 0, v[132:133]
	global_load_lds_dwordx4 v[216:217], off
	s_mov_b32 m0, s49
	s_nop 0
	global_load_lds_dwordx4 v[218:219], off
	s_waitcnt vmcnt(8)
	s_waitcnt lgkmcnt(0)
	s_barrier
	s_setprio 1
	s_waitcnt lgkmcnt(0)
	v_mfma_f32_16x16x32_bf16 v[60:63], v[142:145], v[174:177], 0
	v_mfma_f32_16x16x32_bf16 v[56:59], v[150:153], v[174:177], 0
	v_mfma_f32_16x16x32_bf16 v[52:55], v[142:145], v[182:185], 0
	v_mfma_f32_16x16x32_bf16 v[48:51], v[150:153], v[182:185], 0
	v_mfma_f32_16x16x32_bf16 v[40:43], v[142:145], v[194:197], 0
	v_mfma_f32_16x16x32_bf16 v[32:35], v[150:153], v[194:197], 0
	v_mfma_f32_16x16x32_bf16 v[24:27], v[142:145], v[202:205], 0
	v_mfma_f32_16x16x32_bf16 v[16:19], v[150:153], v[202:205], 0
	v_mfma_f32_16x16x32_bf16 v[60:63], v[146:149], v[178:181], v[60:63]
	v_mfma_f32_16x16x32_bf16 v[56:59], v[154:157], v[178:181], v[56:59]
	v_mfma_f32_16x16x32_bf16 v[52:55], v[146:149], v[186:189], v[52:55]
	v_mfma_f32_16x16x32_bf16 v[48:51], v[154:157], v[186:189], v[48:51]
	v_mfma_f32_16x16x32_bf16 v[40:43], v[146:149], v[198:201], v[40:43]
	v_mfma_f32_16x16x32_bf16 v[32:35], v[154:157], v[198:201], v[32:35]
	v_mfma_f32_16x16x32_bf16 v[24:27], v[146:149], v[206:209], v[24:27]
	v_mfma_f32_16x16x32_bf16 v[16:19], v[154:157], v[206:209], v[16:19]
	s_setprio 0
	s_setprio 1
	v_mfma_f32_16x16x32_bf16 v[44:47], v[158:161], v[174:177], 0
	v_mfma_f32_16x16x32_bf16 v[36:39], v[166:169], v[174:177], 0
	v_mfma_f32_16x16x32_bf16 v[28:31], v[158:161], v[182:185], 0
	v_mfma_f32_16x16x32_bf16 v[20:23], v[166:169], v[182:185], 0
	v_mfma_f32_16x16x32_bf16 v[12:15], v[158:161], v[194:197], 0
	v_mfma_f32_16x16x32_bf16 v[8:11], v[166:169], v[194:197], 0
	v_mfma_f32_16x16x32_bf16 v[4:7], v[158:161], v[202:205], 0
	v_mfma_f32_16x16x32_bf16 v[0:3], v[166:169], v[202:205], 0
	v_mfma_f32_16x16x32_bf16 v[44:47], v[162:165], v[178:181], v[44:47]
	v_mfma_f32_16x16x32_bf16 v[36:39], v[170:173], v[178:181], v[36:39]
	v_mfma_f32_16x16x32_bf16 v[28:31], v[162:165], v[186:189], v[28:31]
	v_mfma_f32_16x16x32_bf16 v[20:23], v[170:173], v[186:189], v[20:23]
	v_mfma_f32_16x16x32_bf16 v[12:15], v[162:165], v[198:201], v[12:15]
	v_mfma_f32_16x16x32_bf16 v[8:11], v[170:173], v[198:201], v[8:11]
	v_mfma_f32_16x16x32_bf16 v[4:7], v[162:165], v[206:209], v[4:7]
	v_mfma_f32_16x16x32_bf16 v[0:3], v[170:173], v[206:209], v[0:3]
	s_setprio 0
	s_barrier
	s_add_i32 s33, 0, 0x18000
	s_add_i32 s73, 0, 0x1c000
	v_add_u32_e32 v154, s33, v244
	v_add_u32_e32 v170, s73, v244
	ds_read_b128 v[142:145], v154
	ds_read_b128 v[146:149], v154 offset:1024
	ds_read_b128 v[150:153], v154 offset:2048
	ds_read_b128 v[154:157], v154 offset:3072
	ds_read_b128 v[158:161], v170
	ds_read_b128 v[162:165], v170 offset:1024
	ds_read_b128 v[166:169], v170 offset:2048
	ds_read_b128 v[170:173], v170 offset:3072
	s_add_u32 s54, s54, s14
	s_addc_u32 s55, s55, s15
	s_mov_b32 m0, s56
	v_lshl_add_u64 v[220:221], s[54:55], 0, v[128:129]
	ds_read_b128 v[174:177], v249 offset:32768
	ds_read_b128 v[178:181], v249 offset:33792
	ds_read_b128 v[182:185], v249 offset:34816
	ds_read_b128 v[186:189], v249 offset:35840
	ds_read_b128 v[194:197], v249 offset:36864
	ds_read_b128 v[198:201], v249 offset:37888
	ds_read_b128 v[202:205], v249 offset:38912
	ds_read_b128 v[206:209], v249 offset:39936
	global_load_lds_dwordx4 v[220:221], off
	v_lshl_add_u64 v[220:221], s[54:55], 0, v[132:133]
	s_mov_b32 m0, s57
	s_nop 0
	global_load_lds_dwordx4 v[220:221], off
	s_waitcnt vmcnt(8)
	s_waitcnt lgkmcnt(0)
	s_barrier
; #define PG8_STAGE(bufoff, gbase, voff) do { _Pragma("unroll") for (int _i = 0; _i < 2; ++_i) \
;         __builtin_amdgcn_global_load_lds((const unsigned*)((const char*)(gbase) + (voff)[_i]), (PG8_LAS unsigned*)(lds + (bufoff) + ldsw + _i * 8192), 16, 0, 0); } while (0)
; #define PG8_LDA(dst, b, h) do { _Pragma("unroll") for (int m = 0; m < 4; ++m) _Pragma("unroll") for (int k = 0; k < 2; ++k) dst[m][k] = *(const PG8_LAS bf16x8*)(lds + PG8_SA(b, h) + aoff + m * 2048 + k * 1024); } while (0)
; #define PG8_MMA(ai, bj, At, Bt) do { __builtin_amdgcn_s_setprio(1); _Pragma("unroll") for (int m = 0; m < 4; ++m) _Pragma("unroll") for (int n = 0; n < 2; ++n) _Pragma("unroll") for (int k = 0; k < 2; ++k) \
;         acc[ai][bj][m][n] = __builtin_amdgcn_mfma_f32_16x16x32_bf16(Bt[n][k], At[m][k], acc[ai][bj][m][n], 0, 0, 0); __builtin_amdgcn_s_setprio(0); } while (0)
; #define PG8_WAIT_V(n) asm volatile("s_waitcnt vmcnt(" #n ")" ::: "memory")
; #define PG8_WAIT_L(n) asm volatile("s_waitcnt lgkmcnt(" #n ")" ::: "memory")
; #define PG8_BAR __builtin_amdgcn_s_barrier()
; #define PG8_SCHED __builtin_amdgcn_sched_barrier(0)
; template <class Epi, class Sched, bool ALIGN_EPI = false, bool SP2 = false>
; __device__ __forceinline__ void gemm_phase(PG8_LAS unsigned char* lds, const Gemm g, const Sched& S, const Epi& E) {
;     ...
;             PG8_WAIT_V(8); PG8_WAIT_L(0); PG8_BAR; PG8_MMA(0, 0, At, B0); PG8_MMA(0, 1, At, B1); PG8_BAR; PG8_SCHED;
;             PG8_LDA(At, 1, 1); PG8_STAGE(PG8_SB(1, 0), b3, voffB); PG8_STAGE(PG8_SB(1, 1), b3 + hstep, voffB); PG8_STAGE(PG8_SA(1, 0), a3, voffA);
;             PG8_WAIT_V(8); PG8_WAIT_L(0); PG8_BAR; PG8_MMA(1, 0, At, B0); PG8_MMA(1, 1, At, B1); PG8_BAR; PG8_SCHED;
	s_setprio 1
	s_waitcnt lgkmcnt(0)
	v_mfma_f32_16x16x32_bf16 v[124:127], v[142:145], v[174:177], v[124:127]
	v_mfma_f32_16x16x32_bf16 v[120:123], v[150:153], v[174:177], v[120:123]
	v_mfma_f32_16x16x32_bf16 v[116:119], v[142:145], v[182:185], v[116:119]
	v_mfma_f32_16x16x32_bf16 v[112:115], v[150:153], v[182:185], v[112:115]
	v_mfma_f32_16x16x32_bf16 v[104:107], v[142:145], v[194:197], v[104:107]
	v_mfma_f32_16x16x32_bf16 v[96:99], v[150:153], v[194:197], v[96:99]
	v_mfma_f32_16x16x32_bf16 v[88:91], v[142:145], v[202:205], v[88:91]
	v_mfma_f32_16x16x32_bf16 v[80:83], v[150:153], v[202:205], v[80:83]
	v_mfma_f32_16x16x32_bf16 v[124:127], v[146:149], v[178:181], v[124:127]
	v_mfma_f32_16x16x32_bf16 v[120:123], v[154:157], v[178:181], v[120:123]
	v_mfma_f32_16x16x32_bf16 v[116:119], v[146:149], v[186:189], v[116:119]
	v_mfma_f32_16x16x32_bf16 v[112:115], v[154:157], v[186:189], v[112:115]
	v_mfma_f32_16x16x32_bf16 v[104:107], v[146:149], v[198:201], v[104:107]
	v_mfma_f32_16x16x32_bf16 v[96:99], v[154:157], v[198:201], v[96:99]
	v_mfma_f32_16x16x32_bf16 v[88:91], v[146:149], v[206:209], v[88:91]
	v_mfma_f32_16x16x32_bf16 v[80:83], v[154:157], v[206:209], v[80:83]
	s_setprio 0
	s_setprio 1
	v_mfma_f32_16x16x32_bf16 v[108:111], v[158:161], v[174:177], v[108:111]
	v_mfma_f32_16x16x32_bf16 v[100:103], v[166:169], v[174:177], v[100:103]
	v_mfma_f32_16x16x32_bf16 v[92:95], v[158:161], v[182:185], v[92:95]
	v_mfma_f32_16x16x32_bf16 v[84:87], v[166:169], v[182:185], v[84:87]
	v_mfma_f32_16x16x32_bf16 v[76:79], v[158:161], v[194:197], v[76:79]
	v_mfma_f32_16x16x32_bf16 v[72:75], v[166:169], v[194:197], v[72:75]
	v_mfma_f32_16x16x32_bf16 v[68:71], v[158:161], v[202:205], v[68:71]
	v_mfma_f32_16x16x32_bf16 v[64:67], v[166:169], v[202:205], v[64:67]
	v_mfma_f32_16x16x32_bf16 v[108:111], v[162:165], v[178:181], v[108:111]
	v_mfma_f32_16x16x32_bf16 v[100:103], v[170:173], v[178:181], v[100:103]
	v_mfma_f32_16x16x32_bf16 v[92:95], v[162:165], v[186:189], v[92:95]
	v_mfma_f32_16x16x32_bf16 v[84:87], v[170:173], v[186:189], v[84:87]
	v_mfma_f32_16x16x32_bf16 v[76:79], v[162:165], v[198:201], v[76:79]
	v_mfma_f32_16x16x32_bf16 v[72:75], v[170:173], v[198:201], v[72:75]
	v_mfma_f32_16x16x32_bf16 v[68:71], v[162:165], v[206:209], v[68:71]
	v_mfma_f32_16x16x32_bf16 v[64:67], v[170:173], v[206:209], v[64:67]
	s_setprio 0
	s_barrier
	s_add_i32 s33, s33, s3
	v_lshl_add_u64 v[190:191], v[190:191], 0, s[22:23]
	s_mov_b32 m0, s33
	ds_read_b128 v[174:177], v249 offset:49152
	ds_read_b128 v[178:181], v249 offset:50176
	ds_read_b128 v[182:185], v249 offset:51200
	ds_read_b128 v[186:189], v249 offset:52224
	ds_read_b128 v[194:197], v249 offset:53248
	ds_read_b128 v[198:201], v249 offset:54272
	ds_read_b128 v[202:205], v249 offset:55296
	ds_read_b128 v[206:209], v249 offset:56320
	global_load_lds_dwordx4 v[190:191], off
	v_lshl_add_u64 v[190:191], v[210:211], 0, s[22:23]
	s_add_i32 m0, s33, 0x2000
	s_add_i32 s33, s73, s3
	global_load_lds_dwordx4 v[190:191], off
	v_lshl_add_u64 v[190:191], v[212:213], 0, s[22:23]
	s_mov_b32 m0, s33
	s_nop 0
	global_load_lds_dwordx4 v[190:191], off
	v_lshl_add_u64 v[190:191], v[214:215], 0, s[22:23]
	s_add_i32 m0, s33, 0x2000
	s_nop 0
	global_load_lds_dwordx4 v[190:191], off
	v_lshl_add_u64 v[190:191], v[216:217], 0, s[22:23]
	s_mov_b32 m0, s58
	s_nop 0
	global_load_lds_dwordx4 v[190:191], off
	v_lshl_add_u64 v[190:191], v[218:219], 0, s[22:23]
	s_mov_b32 m0, s59
	s_nop 0
	global_load_lds_dwordx4 v[190:191], off
	s_waitcnt vmcnt(8)
	s_waitcnt lgkmcnt(0)
	s_barrier
	s_setprio 1
	s_waitcnt lgkmcnt(0)
	v_mfma_f32_16x16x32_bf16 v[60:63], v[142:145], v[174:177], v[60:63]
	v_mfma_f32_16x16x32_bf16 v[56:59], v[150:153], v[174:177], v[56:59]
	v_mfma_f32_16x16x32_bf16 v[52:55], v[142:145], v[182:185], v[52:55]
	v_mfma_f32_16x16x32_bf16 v[48:51], v[150:153], v[182:185], v[48:51]
	v_mfma_f32_16x16x32_bf16 v[40:43], v[142:145], v[194:197], v[40:43]
	v_mfma_f32_16x16x32_bf16 v[32:35], v[150:153], v[194:197], v[32:35]
	v_mfma_f32_16x16x32_bf16 v[24:27], v[142:145], v[202:205], v[24:27]
	v_mfma_f32_16x16x32_bf16 v[16:19], v[150:153], v[202:205], v[16:19]
	v_mfma_f32_16x16x32_bf16 v[60:63], v[146:149], v[178:181], v[60:63]
	v_mfma_f32_16x16x32_bf16 v[56:59], v[154:157], v[178:181], v[56:59]
	v_mfma_f32_16x16x32_bf16 v[52:55], v[146:149], v[186:189], v[52:55]
	v_mfma_f32_16x16x32_bf16 v[48:51], v[154:157], v[186:189], v[48:51]
	v_mfma_f32_16x16x32_bf16 v[40:43], v[146:149], v[198:201], v[40:43]
	v_mfma_f32_16x16x32_bf16 v[32:35], v[154:157], v[198:201], v[32:35]
	v_mfma_f32_16x16x32_bf16 v[24:27], v[146:149], v[206:209], v[24:27]
	v_mfma_f32_16x16x32_bf16 v[16:19], v[154:157], v[206:209], v[16:19]
	s_setprio 0
	s_setprio 1
	v_mfma_f32_16x16x32_bf16 v[44:47], v[158:161], v[174:177], v[44:47]
	v_mfma_f32_16x16x32_bf16 v[36:39], v[166:169], v[174:177], v[36:39]
	v_mfma_f32_16x16x32_bf16 v[28:31], v[158:161], v[182:185], v[28:31]
	v_mfma_f32_16x16x32_bf16 v[20:23], v[166:169], v[182:185], v[20:23]
	v_mfma_f32_16x16x32_bf16 v[12:15], v[158:161], v[194:197], v[12:15]
	v_mfma_f32_16x16x32_bf16 v[8:11], v[166:169], v[194:197], v[8:11]
	v_mfma_f32_16x16x32_bf16 v[4:7], v[158:161], v[202:205], v[4:7]
	v_mfma_f32_16x16x32_bf16 v[0:3], v[166:169], v[202:205], v[0:3]
	v_mfma_f32_16x16x32_bf16 v[44:47], v[162:165], v[178:181], v[44:47]
	v_mfma_f32_16x16x32_bf16 v[36:39], v[170:173], v[178:181], v[36:39]
	v_mfma_f32_16x16x32_bf16 v[28:31], v[162:165], v[186:189], v[28:31]
	v_mfma_f32_16x16x32_bf16 v[20:23], v[170:173], v[186:189], v[20:23]
	v_mfma_f32_16x16x32_bf16 v[12:15], v[162:165], v[198:201], v[12:15]
	v_mfma_f32_16x16x32_bf16 v[8:11], v[170:173], v[198:201], v[8:11]
	v_mfma_f32_16x16x32_bf16 v[4:7], v[162:165], v[206:209], v[4:7]
	v_mfma_f32_16x16x32_bf16 v[0:3], v[170:173], v[206:209], v[0:3]
	s_setprio 0
	s_barrier
	s_add_u32 s42, s42, 0x100
	s_addc_u32 s43, s43, 0
	s_add_u32 s4, s4, 0x100
	s_addc_u32 s5, s5, 0
	s_cmp_ge_i32 s72, s61
	s_mov_b32 s33, s72
	s_cbranch_scc0 .LBB0_1118
	s_branch .Lpx_k1118

; __device__ __forceinline__ unsigned cvt_pk_bf16(float lo, float hi) { unsigned r; asm volatile("v_cvt_pk_bf16_f32 %0, %1, %2" : "=v"(r) : "v"(lo), "v"(hi)); return r; }
; __device__ __forceinline__ unsigned cvt_pk_bf16(float lo, float hi) { const f32x2 v = {lo, hi}; const bf16x2_t b = __builtin_convertvector(v, bf16x2_t); return __builtin_bit_cast(unsigned, b); }
;     __device__ __forceinline__ void operator()(const f32x4 (&acc)[2][2][4][2], const Unit& u, int wr, int wc, int fr, int fq) const {
;         const int row0 = u.pm * BM + wr * 64 + fr, col0 = u.pn * BM + wc * 32 + 8 * fq;
;         u32x4 rb[2][4][2];
; #pragma unroll
;         for (int ai = 0; ai < 2; ++ai)
; #pragma unroll
;             for (int m = 0; m < 4; ++m) { const bf16_t* xq = XB + (size_t)(row0 + ai * HALF + m * 16) * 1024 + col0; rb[ai][m][0] = *(const u32x4*)xq; rb[ai][m][1] = *(const u32x4*)(xq + HALF); }
; #pragma unroll
;         for (int ai = 0; ai < 2; ++ai) {
; #pragma unroll
;             for (int m = 0; m < 4; ++m) {
;                 const int r = row0 + ai * HALF + m * 16;
;                 bf16_t* xp = XB + (size_t)r * 1024 + col0;
;                 const u32x4 b0 = rb[ai][m][0], b1 = rb[ai][m][1];
;                 float ss = 0.f;
; #pragma unroll
;                 for (int bj = 0; bj < 2; ++bj) {
;                     const u32x4 b = bj ? b1 : b0;
;                     f32x4 v0, v1;
;                     v0[0] = __uint_as_float(b.x << 16); v0[1] = __uint_as_float(b.x & 0xffff0000u); v0[2] = __uint_as_float(b.y << 16); v0[3] = __uint_as_float(b.y & 0xffff0000u);
;                     v1[0] = __uint_as_float(b.z << 16); v1[1] = __uint_as_float(b.z & 0xffff0000u); v1[2] = __uint_as_float(b.w << 16); v1[3] = __uint_as_float(b.w & 0xffff0000u);
;                     v0 += acc[ai][bj][m][0] * alpha; v1 += acc[ai][bj][m][1] * alpha;
;                     ss += (v0[0] * v0[0] + v0[1] * v0[1]) + (v0[2] * v0[2] + v0[3] * v0[3]) + (v1[0] * v1[0] + v1[1] * v1[1]) + (v1[2] * v1[2] + v1[3] * v1[3]);
;                     u32x4 w; w.x = cvt_pk_bf16(v0[0], v0[1]); w.y = cvt_pk_bf16(v0[2], v0[3]); w.z = cvt_pk_bf16(v1[0], v1[1]); w.w = cvt_pk_bf16(v1[2], v1[3]);
;                     *(u32x4*)(xp + bj * HALF) = w;
.Lpx_k1118:
	v_pk_mul_f32 v[220:221], v[126:127], 0.5 op_sel_hi:[1,0]
	v_pk_mul_f32 v[222:223], v[124:125], 0.5 op_sel_hi:[1,0]
	v_pk_mul_f32 v[224:225], v[122:123], 0.5 op_sel_hi:[1,0]
	v_pk_mul_f32 v[226:227], v[120:121], 0.5 op_sel_hi:[1,0]
	v_pk_mul_f32 v[214:215], v[110:111], 0.5 op_sel_hi:[1,0]
	v_pk_mul_f32 v[212:213], v[108:109], 0.5 op_sel_hi:[1,0]
	v_pk_mul_f32 v[210:211], v[102:103], 0.5 op_sel_hi:[1,0]
	v_pk_mul_f32 v[206:207], v[100:101], 0.5 op_sel_hi:[1,0]
	v_pk_mul_f32 v[198:199], v[118:119], 0.5 op_sel_hi:[1,0]
	v_pk_mul_f32 v[196:197], v[116:117], 0.5 op_sel_hi:[1,0]
	v_pk_mul_f32 v[194:195], v[114:115], 0.5 op_sel_hi:[1,0]
	v_pk_mul_f32 v[190:191], v[112:113], 0.5 op_sel_hi:[1,0]
	v_pk_mul_f32 v[188:189], v[94:95], 0.5 op_sel_hi:[1,0]
	v_pk_mul_f32 v[186:187], v[92:93], 0.5 op_sel_hi:[1,0]
	v_pk_mul_f32 v[184:185], v[86:87], 0.5 op_sel_hi:[1,0]
	v_pk_mul_f32 v[182:183], v[84:85], 0.5 op_sel_hi:[1,0]
	v_pk_mul_f32 v[176:177], v[106:107], 0.5 op_sel_hi:[1,0]
	v_pk_mul_f32 v[174:175], v[104:105], 0.5 op_sel_hi:[1,0]
	v_pk_mul_f32 v[172:173], v[98:99], 0.5 op_sel_hi:[1,0]
	v_pk_mul_f32 v[170:171], v[96:97], 0.5 op_sel_hi:[1,0]
	v_pk_mul_f32 v[168:169], v[78:79], 0.5 op_sel_hi:[1,0]
	v_pk_mul_f32 v[166:167], v[76:77], 0.5 op_sel_hi:[1,0]
	v_pk_mul_f32 v[164:165], v[74:75], 0.5 op_sel_hi:[1,0]
	v_pk_mul_f32 v[162:163], v[72:73], 0.5 op_sel_hi:[1,0]
	v_pk_mul_f32 v[158:159], v[90:91], 0.5 op_sel_hi:[1,0]
	v_pk_mul_f32 v[156:157], v[88:89], 0.5 op_sel_hi:[1,0]
	v_pk_mul_f32 v[154:155], v[82:83], 0.5 op_sel_hi:[1,0]
	v_pk_mul_f32 v[152:153], v[80:81], 0.5 op_sel_hi:[1,0]
	v_pk_mul_f32 v[148:149], v[70:71], 0.5 op_sel_hi:[1,0]
	v_pk_mul_f32 v[146:147], v[68:69], 0.5 op_sel_hi:[1,0]
	v_pk_mul_f32 v[144:145], v[66:67], 0.5 op_sel_hi:[1,0]
	v_pk_mul_f32 v[142:143], v[64:65], 0.5 op_sel_hi:[1,0]
	v_pk_mul_f32 v[126:127], v[62:63], 0.5 op_sel_hi:[1,0]
	v_pk_mul_f32 v[124:125], v[60:61], 0.5 op_sel_hi:[1,0]
	v_pk_mul_f32 v[122:123], v[58:59], 0.5 op_sel_hi:[1,0]
	v_pk_mul_f32 v[120:121], v[56:57], 0.5 op_sel_hi:[1,0]
	v_pk_mul_f32 v[118:119], v[46:47], 0.5 op_sel_hi:[1,0]
	v_pk_mul_f32 v[116:117], v[44:45], 0.5 op_sel_hi:[1,0]
	v_pk_mul_f32 v[114:115], v[38:39], 0.5 op_sel_hi:[1,0]
	v_pk_mul_f32 v[112:113], v[36:37], 0.5 op_sel_hi:[1,0]
	v_pk_mul_f32 v[110:111], v[54:55], 0.5 op_sel_hi:[1,0]
	v_pk_mul_f32 v[108:109], v[52:53], 0.5 op_sel_hi:[1,0]
	v_pk_mul_f32 v[106:107], v[50:51], 0.5 op_sel_hi:[1,0]
	v_pk_mul_f32 v[104:105], v[48:49], 0.5 op_sel_hi:[1,0]
	v_pk_mul_f32 v[102:103], v[30:31], 0.5 op_sel_hi:[1,0]
	v_pk_mul_f32 v[100:101], v[28:29], 0.5 op_sel_hi:[1,0]
	v_pk_mul_f32 v[98:99], v[22:23], 0.5 op_sel_hi:[1,0]
	v_pk_mul_f32 v[96:97], v[20:21], 0.5 op_sel_hi:[1,0]
	v_pk_mul_f32 v[94:95], v[42:43], 0.5 op_sel_hi:[1,0]
	v_pk_mul_f32 v[92:93], v[40:41], 0.5 op_sel_hi:[1,0]
	v_pk_mul_f32 v[90:91], v[34:35], 0.5 op_sel_hi:[1,0]
	v_pk_mul_f32 v[88:89], v[32:33], 0.5 op_sel_hi:[1,0]
	v_pk_mul_f32 v[86:87], v[14:15], 0.5 op_sel_hi:[1,0]
	v_pk_mul_f32 v[84:85], v[12:13], 0.5 op_sel_hi:[1,0]
	v_pk_mul_f32 v[82:83], v[10:11], 0.5 op_sel_hi:[1,0]
	v_pk_mul_f32 v[80:81], v[8:9], 0.5 op_sel_hi:[1,0]
	v_pk_mul_f32 v[78:79], v[26:27], 0.5 op_sel_hi:[1,0]
	v_pk_mul_f32 v[76:77], v[24:25], 0.5 op_sel_hi:[1,0]
	v_pk_mul_f32 v[74:75], v[18:19], 0.5 op_sel_hi:[1,0]
	v_pk_mul_f32 v[72:73], v[16:17], 0.5 op_sel_hi:[1,0]
	v_pk_mul_f32 v[70:71], v[6:7], 0.5 op_sel_hi:[1,0]
	v_pk_mul_f32 v[68:69], v[4:5], 0.5 op_sel_hi:[1,0]
	v_pk_mul_f32 v[66:67], v[2:3], 0.5 op_sel_hi:[1,0]
	v_pk_mul_f32 v[64:65], v[0:1], 0.5 op_sel_hi:[1,0]

;     __host__ __device__ bool next(int i, Unit& u) const { const int idx = first + i; if (idx >= last) return false; u.pm = idx >> 2; u.pn = idx & 3; return true; }
; #define PG8_STAGE(bufoff, gbase, voff) do { _Pragma("unroll") for (int _i = 0; _i < 2; ++_i) \
;         __builtin_amdgcn_global_load_lds((const unsigned*)((const char*)(gbase) + (voff)[_i]), (PG8_LAS unsigned*)(lds + (bufoff) + ldsw + _i * 8192), 16, 0, 0); } while (0)
; #define PG8_LDA(dst, b, h) do { _Pragma("unroll") for (int m = 0; m < 4; ++m) _Pragma("unroll") for (int k = 0; k < 2; ++k) dst[m][k] = *(const PG8_LAS bf16x8*)(lds + PG8_SA(b, h) + aoff + m * 2048 + k * 1024); } while (0)
; #define PG8_LDB(dst, b, h) do { _Pragma("unroll") for (int n = 0; n < 2; ++n) _Pragma("unroll") for (int k = 0; k < 2; ++k) dst[n][k] = *(const PG8_LAS bf16x8*)(lds + PG8_SB(b, h) + boff + n * 2048 + k * 1024); } while (0)
; #define PG8_WAIT_V(n) asm volatile("s_waitcnt vmcnt(" #n ")" ::: "memory")
; template <class Epi, class Sched, bool ALIGN_EPI = false, bool SP2 = false>
; __device__ __forceinline__ void gemm_phase(PG8_LAS unsigned char* lds, const Gemm g, const Sched& S, const Epi& E) {
;     ...
;     for (;;) {
;         const bool has_next = S.next(ui + 1, nxt);
;         const char* nA = has_next ? (const char*)g.A + (size_t)nxt.pm * tstep : cA; const char* nB = has_next ? (const char*)g.Bt + (size_t)nxt.pn * tstep : cB;
;         asm volatile(".p2align 8");
;         for (int t = 0; t < nt; t += 2) {
;             const bool last = (t == nt - 2);
;             const char* a1 = cA + (size_t)(t + 1) * kstep;
;             const char* a2 = last ? nA : cA + (size_t)(t + 2) * kstep; const char* b2 = last ? nB : cB + (size_t)(t + 2) * kstep;
;             const char* a3 = a2 + kstep; const char* b3 = b2 + kstep;
;             if (last && has_next) S.a_ready(nxt);
;             if constexpr (SP2) {
;             PG8_LDB(B0, 0, 0); PG8_LDB(B1, 0, 1); PG8_SCHED; PG8_LDA(At, 0, 0); PG8_STAGE(PG8_SA(1, 1), a1 + hstep, voffA);
;             PG8_WAIT_V(8); PG8_WAIT_L(0); PG8_BAR; PG8_MMA(0, 0, At, B0); PG8_MMA(0, 1, At, B1); PG8_BAR; PG8_SCHED;
;             PG8_LDA(At, 0, 1); PG8_STAGE(PG8_SB(0, 0), b2, voffB); PG8_STAGE(PG8_SB(0, 1), b2 + hstep, voffB); PG8_STAGE(PG8_SA(0, 0), a2, voffA);
;             PG8_WAIT_V(8); PG8_WAIT_L(0); PG8_BAR; PG8_MMA(1, 0, At, B0); PG8_MMA(1, 1, At, B1); PG8_BAR; PG8_SCHED;
.LBB0_1251:
	s_andn2_b64 vcc, exec, s[16:17]
	.p2align 8
	s_cbranch_vccnz .Lpz_k1253
	s_add_u32 s22, s22, 0x80
	s_addc_u32 s23, s23, 0
	s_add_u32 s53, s26, 0x100
	s_addc_u32 s54, s27, 0
	s_mov_b32 s26, 0
.Lpeel_k1253:
	ds_read_b128 v[124:127], v214
	ds_read_b128 v[132:135], v214 offset:1024
	ds_read_b128 v[136:139], v214 offset:2048
	ds_read_b128 v[140:143], v214 offset:3072
	ds_read_b128 v[144:147], v215
	ds_read_b128 v[148:151], v215 offset:1024
	ds_read_b128 v[152:155], v215 offset:2048
	ds_read_b128 v[156:159], v215 offset:3072
	s_add_i32 s55, s26, 2
	s_add_u32 s56, s22, 0x80
	s_addc_u32 s27, s23, 0
	s_cmp_eq_u32 s41, s26
	s_cselect_b32 s26, s4, s56
	s_cselect_b32 s27, s5, s27
	s_cselect_b32 s57, s21, s54
	s_cselect_b32 s56, s20, s53
	v_lshl_add_u64 v[220:221], s[22:23], 0, v[186:187]
	s_add_i32 m0, s29, 0xc000
	ds_read_b128 v[160:163], v216
	ds_read_b128 v[164:167], v216 offset:1024
	ds_read_b128 v[168:171], v216 offset:2048
	ds_read_b128 v[172:175], v216 offset:3072
	ds_read_b128 v[196:199], v216 offset:4096
	ds_read_b128 v[200:203], v216 offset:5120
	ds_read_b128 v[204:207], v216 offset:6144
	ds_read_b128 v[208:211], v216 offset:7168
	global_load_lds_dwordx4 v[220:221], off
	v_lshl_add_u64 v[220:221], s[22:23], 0, v[188:189]
	s_add_i32 m0, s29, 0xe000
	s_nop 0
	global_load_lds_dwordx4 v[220:221], off
	s_waitcnt vmcnt(8)
	s_waitcnt lgkmcnt(0)
	s_barrier
	s_setprio 1
	s_waitcnt lgkmcnt(0)
	v_mfma_f32_16x16x32_bf16 v[128:131], v[124:127], v[160:163], 0
	v_mfma_f32_16x16x32_bf16 v[120:123], v[136:139], v[160:163], 0
	v_mfma_f32_16x16x32_bf16 v[108:111], v[124:127], v[168:171], 0
	v_mfma_f32_16x16x32_bf16 v[104:107], v[136:139], v[168:171], 0
	v_mfma_f32_16x16x32_bf16 v[92:95], v[124:127], v[196:199], 0
	v_mfma_f32_16x16x32_bf16 v[88:91], v[136:139], v[196:199], 0
	v_mfma_f32_16x16x32_bf16 v[76:79], v[124:127], v[204:207], 0
	v_mfma_f32_16x16x32_bf16 v[72:75], v[136:139], v[204:207], 0
	v_mfma_f32_16x16x32_bf16 v[128:131], v[132:135], v[164:167], v[128:131]
	v_mfma_f32_16x16x32_bf16 v[120:123], v[140:143], v[164:167], v[120:123]
	v_mfma_f32_16x16x32_bf16 v[108:111], v[132:135], v[172:175], v[108:111]
	v_mfma_f32_16x16x32_bf16 v[104:107], v[140:143], v[172:175], v[104:107]
	v_mfma_f32_16x16x32_bf16 v[92:95], v[132:135], v[200:203], v[92:95]
	v_mfma_f32_16x16x32_bf16 v[88:91], v[140:143], v[200:203], v[88:91]
	v_mfma_f32_16x16x32_bf16 v[76:79], v[132:135], v[208:211], v[76:79]
	v_mfma_f32_16x16x32_bf16 v[72:75], v[140:143], v[208:211], v[72:75]
	s_setprio 0
	s_setprio 1
	v_mfma_f32_16x16x32_bf16 v[116:119], v[144:147], v[160:163], 0
	v_mfma_f32_16x16x32_bf16 v[112:115], v[152:155], v[160:163], 0
	v_mfma_f32_16x16x32_bf16 v[100:103], v[144:147], v[168:171], 0
	v_mfma_f32_16x16x32_bf16 v[96:99], v[152:155], v[168:171], 0
	v_mfma_f32_16x16x32_bf16 v[84:87], v[144:147], v[196:199], 0
	v_mfma_f32_16x16x32_bf16 v[80:83], v[152:155], v[196:199], 0
	v_mfma_f32_16x16x32_bf16 v[68:71], v[144:147], v[204:207], 0
	v_mfma_f32_16x16x32_bf16 v[64:67], v[152:155], v[204:207], 0
	v_mfma_f32_16x16x32_bf16 v[116:119], v[148:151], v[164:167], v[116:119]
	v_mfma_f32_16x16x32_bf16 v[112:115], v[156:159], v[164:167], v[112:115]
	v_mfma_f32_16x16x32_bf16 v[100:103], v[148:151], v[172:175], v[100:103]
	v_mfma_f32_16x16x32_bf16 v[96:99], v[156:159], v[172:175], v[96:99]
	v_mfma_f32_16x16x32_bf16 v[84:87], v[148:151], v[200:203], v[84:87]
	v_mfma_f32_16x16x32_bf16 v[80:83], v[156:159], v[200:203], v[80:83]
	v_mfma_f32_16x16x32_bf16 v[68:71], v[148:151], v[208:211], v[68:71]
	v_mfma_f32_16x16x32_bf16 v[64:67], v[156:159], v[208:211], v[64:67]
	s_setprio 0
	s_barrier
	s_add_i32 s58, s43, s28
	v_lshl_add_u64 v[220:221], s[56:57], 0, v[178:179]
	s_mov_b32 m0, s58
	ds_read_b128 v[160:163], v216 offset:16384
	ds_read_b128 v[164:167], v216 offset:17408
	ds_read_b128 v[168:171], v216 offset:18432
	ds_read_b128 v[172:175], v216 offset:19456
	ds_read_b128 v[196:199], v216 offset:20480
	ds_read_b128 v[200:203], v216 offset:21504
	ds_read_b128 v[204:207], v216 offset:22528
	ds_read_b128 v[208:211], v216 offset:23552
	global_load_lds_dwordx4 v[220:221], off
	s_add_i32 m0, s58, 0x2000
	v_lshl_add_u64 v[222:223], s[56:57], 0, v[182:183]
	s_add_u32 s56, s56, s8
	s_addc_u32 s57, s57, s9
	s_add_i32 s58, s48, s28
	global_load_lds_dwordx4 v[222:223], off
	v_lshl_add_u64 v[224:225], s[56:57], 0, v[178:179]
	s_mov_b32 m0, s58
	v_lshl_add_u64 v[226:227], s[56:57], 0, v[182:183]
	global_load_lds_dwordx4 v[224:225], off
	s_add_i32 m0, s58, 0x2000
	v_lshl_add_u64 v[228:229], s[26:27], 0, v[176:177]
	global_load_lds_dwordx4 v[226:227], off
	s_mov_b32 m0, s29
	v_lshl_add_u64 v[230:231], s[26:27], 0, v[180:181]
	global_load_lds_dwordx4 v[228:229], off
	s_mov_b32 m0, s31
	s_nop 0
	global_load_lds_dwordx4 v[230:231], off
	s_waitcnt vmcnt(8)
	s_waitcnt lgkmcnt(0)
	s_barrier
; #define PG8_STAGE(bufoff, gbase, voff) do { _Pragma("unroll") for (int _i = 0; _i < 2; ++_i) \
;         __builtin_amdgcn_global_load_lds((const unsigned*)((const char*)(gbase) + (voff)[_i]), (PG8_LAS unsigned*)(lds + (bufoff) + ldsw + _i * 8192), 16, 0, 0); } while (0)
; #define PG8_LDA(dst, b, h) do { _Pragma("unroll") for (int m = 0; m < 4; ++m) _Pragma("unroll") for (int k = 0; k < 2; ++k) dst[m][k] = *(const PG8_LAS bf16x8*)(lds + PG8_SA(b, h) + aoff + m * 2048 + k * 1024); } while (0)
; #define PG8_LDB(dst, b, h) do { _Pragma("unroll") for (int n = 0; n < 2; ++n) _Pragma("unroll") for (int k = 0; k < 2; ++k) dst[n][k] = *(const PG8_LAS bf16x8*)(lds + PG8_SB(b, h) + boff + n * 2048 + k * 1024); } while (0)
; #define PG8_MMA(ai, bj, At, Bt) do { __builtin_amdgcn_s_setprio(1); _Pragma("unroll") for (int m = 0; m < 4; ++m) _Pragma("unroll") for (int n = 0; n < 2; ++n) _Pragma("unroll") for (int k = 0; k < 2; ++k) \
;         acc[ai][bj][m][n] = __builtin_amdgcn_mfma_f32_16x16x32_bf16(Bt[n][k], At[m][k], acc[ai][bj][m][n], 0, 0, 0); __builtin_amdgcn_s_setprio(0); } while (0)
; #define PG8_WAIT_V(n) asm volatile("s_waitcnt vmcnt(" #n ")" ::: "memory")
; #define PG8_WAIT_L(n) asm volatile("s_waitcnt lgkmcnt(" #n ")" ::: "memory")
; #define PG8_BAR __builtin_amdgcn_s_barrier()
; #define PG8_SCHED __builtin_amdgcn_sched_barrier(0)
; template <class Epi, class Sched, bool ALIGN_EPI = false, bool SP2 = false>
; __device__ __forceinline__ void gemm_phase(PG8_LAS unsigned char* lds, const Gemm g, const Sched& S, const Epi& E) {
;     ...
;             PG8_WAIT_V(8); PG8_WAIT_L(0); PG8_BAR; PG8_MMA(1, 0, At, B0); PG8_MMA(1, 1, At, B1); PG8_BAR; PG8_SCHED;
;             PG8_LDB(B0, 1, 0); PG8_LDB(B1, 1, 1); PG8_SCHED; PG8_LDA(At, 1, 0); PG8_STAGE(PG8_SA(0, 1), a2 + hstep, voffA);
;             PG8_WAIT_V(8); PG8_WAIT_L(0); PG8_BAR; PG8_MMA(0, 0, At, B0); PG8_MMA(0, 1, At, B1); PG8_BAR; PG8_SCHED;
	s_setprio 1
	s_waitcnt lgkmcnt(0)
	v_mfma_f32_16x16x32_bf16 v[60:63], v[124:127], v[160:163], 0
	v_mfma_f32_16x16x32_bf16 v[56:59], v[136:139], v[160:163], 0
	v_mfma_f32_16x16x32_bf16 v[44:47], v[124:127], v[168:171], 0
	v_mfma_f32_16x16x32_bf16 v[40:43], v[136:139], v[168:171], 0
	v_mfma_f32_16x16x32_bf16 v[28:31], v[124:127], v[196:199], 0
	v_mfma_f32_16x16x32_bf16 v[24:27], v[136:139], v[196:199], 0
	v_mfma_f32_16x16x32_bf16 v[12:15], v[124:127], v[204:207], 0
	v_mfma_f32_16x16x32_bf16 v[8:11], v[136:139], v[204:207], 0
	v_mfma_f32_16x16x32_bf16 v[60:63], v[132:135], v[164:167], v[60:63]
	v_mfma_f32_16x16x32_bf16 v[56:59], v[140:143], v[164:167], v[56:59]
	v_mfma_f32_16x16x32_bf16 v[44:47], v[132:135], v[172:175], v[44:47]
	v_mfma_f32_16x16x32_bf16 v[40:43], v[140:143], v[172:175], v[40:43]
	v_mfma_f32_16x16x32_bf16 v[28:31], v[132:135], v[200:203], v[28:31]
	v_mfma_f32_16x16x32_bf16 v[24:27], v[140:143], v[200:203], v[24:27]
	v_mfma_f32_16x16x32_bf16 v[12:15], v[132:135], v[208:211], v[12:15]
	v_mfma_f32_16x16x32_bf16 v[8:11], v[140:143], v[208:211], v[8:11]
	s_setprio 0
	s_setprio 1
	v_mfma_f32_16x16x32_bf16 v[52:55], v[144:147], v[160:163], 0
	v_mfma_f32_16x16x32_bf16 v[48:51], v[152:155], v[160:163], 0
	v_mfma_f32_16x16x32_bf16 v[36:39], v[144:147], v[168:171], 0
	v_mfma_f32_16x16x32_bf16 v[32:35], v[152:155], v[168:171], 0
	v_mfma_f32_16x16x32_bf16 v[20:23], v[144:147], v[196:199], 0
	v_mfma_f32_16x16x32_bf16 v[16:19], v[152:155], v[196:199], 0
	v_mfma_f32_16x16x32_bf16 v[4:7], v[144:147], v[204:207], 0
	v_mfma_f32_16x16x32_bf16 v[0:3], v[152:155], v[204:207], 0
	v_mfma_f32_16x16x32_bf16 v[52:55], v[148:151], v[164:167], v[52:55]
	v_mfma_f32_16x16x32_bf16 v[48:51], v[156:159], v[164:167], v[48:51]
	v_mfma_f32_16x16x32_bf16 v[36:39], v[148:151], v[172:175], v[36:39]
	v_mfma_f32_16x16x32_bf16 v[32:35], v[156:159], v[172:175], v[32:35]
	v_mfma_f32_16x16x32_bf16 v[20:23], v[148:151], v[200:203], v[20:23]
	v_mfma_f32_16x16x32_bf16 v[16:19], v[156:159], v[200:203], v[16:19]
	v_mfma_f32_16x16x32_bf16 v[4:7], v[148:151], v[208:211], v[4:7]
	v_mfma_f32_16x16x32_bf16 v[0:3], v[156:159], v[208:211], v[0:3]
	s_setprio 0
	s_barrier
	s_add_i32 s56, 0, 0x18000
	s_add_i32 s57, 0, 0x1c000
	v_add_u32_e32 v140, s56, v212
	v_add_u32_e32 v156, s57, v212
	ds_read_b128 v[124:127], v140
	ds_read_b128 v[132:135], v140 offset:1024
	ds_read_b128 v[136:139], v140 offset:2048
	ds_read_b128 v[140:143], v140 offset:3072
	ds_read_b128 v[144:147], v156
	ds_read_b128 v[148:151], v156 offset:1024
	ds_read_b128 v[152:155], v156 offset:2048
	ds_read_b128 v[156:159], v156 offset:3072
	s_add_u32 s26, s26, s8
	s_addc_u32 s27, s27, s9
	s_mov_b32 m0, s33
	v_lshl_add_u64 v[232:233], s[26:27], 0, v[176:177]
	ds_read_b128 v[160:163], v216 offset:32768
	ds_read_b128 v[164:167], v216 offset:33792
	ds_read_b128 v[168:171], v216 offset:34816
	ds_read_b128 v[172:175], v216 offset:35840
	ds_read_b128 v[196:199], v216 offset:36864
	ds_read_b128 v[200:203], v216 offset:37888
	ds_read_b128 v[204:207], v216 offset:38912
	ds_read_b128 v[208:211], v216 offset:39936
	global_load_lds_dwordx4 v[232:233], off
	v_lshl_add_u64 v[232:233], s[26:27], 0, v[180:181]
	s_mov_b32 m0, s36
	s_nop 0
	global_load_lds_dwordx4 v[232:233], off
	s_waitcnt vmcnt(8)
	s_waitcnt lgkmcnt(0)
	s_barrier
	s_setprio 1
	s_waitcnt lgkmcnt(0)
	v_mfma_f32_16x16x32_bf16 v[128:131], v[124:127], v[160:163], v[128:131]
	v_mfma_f32_16x16x32_bf16 v[120:123], v[136:139], v[160:163], v[120:123]
	v_mfma_f32_16x16x32_bf16 v[108:111], v[124:127], v[168:171], v[108:111]
	v_mfma_f32_16x16x32_bf16 v[104:107], v[136:139], v[168:171], v[104:107]
	v_mfma_f32_16x16x32_bf16 v[92:95], v[124:127], v[196:199], v[92:95]
	v_mfma_f32_16x16x32_bf16 v[88:91], v[136:139], v[196:199], v[88:91]
	v_mfma_f32_16x16x32_bf16 v[76:79], v[124:127], v[204:207], v[76:79]
	v_mfma_f32_16x16x32_bf16 v[72:75], v[136:139], v[204:207], v[72:75]
	v_mfma_f32_16x16x32_bf16 v[128:131], v[132:135], v[164:167], v[128:131]
	v_mfma_f32_16x16x32_bf16 v[120:123], v[140:143], v[164:167], v[120:123]
	v_mfma_f32_16x16x32_bf16 v[108:111], v[132:135], v[172:175], v[108:111]
	v_mfma_f32_16x16x32_bf16 v[104:107], v[140:143], v[172:175], v[104:107]
	v_mfma_f32_16x16x32_bf16 v[92:95], v[132:135], v[200:203], v[92:95]
	v_mfma_f32_16x16x32_bf16 v[88:91], v[140:143], v[200:203], v[88:91]
	v_mfma_f32_16x16x32_bf16 v[76:79], v[132:135], v[208:211], v[76:79]
	v_mfma_f32_16x16x32_bf16 v[72:75], v[140:143], v[208:211], v[72:75]
	s_setprio 0
	s_setprio 1
	v_mfma_f32_16x16x32_bf16 v[116:119], v[144:147], v[160:163], v[116:119]
	v_mfma_f32_16x16x32_bf16 v[112:115], v[152:155], v[160:163], v[112:115]
	v_mfma_f32_16x16x32_bf16 v[100:103], v[144:147], v[168:171], v[100:103]
	v_mfma_f32_16x16x32_bf16 v[96:99], v[152:155], v[168:171], v[96:99]
	v_mfma_f32_16x16x32_bf16 v[84:87], v[144:147], v[196:199], v[84:87]
	v_mfma_f32_16x16x32_bf16 v[80:83], v[152:155], v[196:199], v[80:83]
	v_mfma_f32_16x16x32_bf16 v[68:71], v[144:147], v[204:207], v[68:71]
	v_mfma_f32_16x16x32_bf16 v[64:67], v[152:155], v[204:207], v[64:67]
	v_mfma_f32_16x16x32_bf16 v[116:119], v[148:151], v[164:167], v[116:119]
	v_mfma_f32_16x16x32_bf16 v[112:115], v[156:159], v[164:167], v[112:115]
	v_mfma_f32_16x16x32_bf16 v[100:103], v[148:151], v[172:175], v[100:103]
	v_mfma_f32_16x16x32_bf16 v[96:99], v[156:159], v[172:175], v[96:99]
	v_mfma_f32_16x16x32_bf16 v[84:87], v[148:151], v[200:203], v[84:87]
	v_mfma_f32_16x16x32_bf16 v[80:83], v[156:159], v[200:203], v[80:83]
	v_mfma_f32_16x16x32_bf16 v[68:71], v[148:151], v[208:211], v[68:71]
	v_mfma_f32_16x16x32_bf16 v[64:67], v[156:159], v[208:211], v[64:67]
	s_setprio 0
	s_barrier
; #define PG8_STAGE(bufoff, gbase, voff) do { _Pragma("unroll") for (int _i = 0; _i < 2; ++_i) \
;         __builtin_amdgcn_global_load_lds((const unsigned*)((const char*)(gbase) + (voff)[_i]), (PG8_LAS unsigned*)(lds + (bufoff) + ldsw + _i * 8192), 16, 0, 0); } while (0)
; #define PG8_LDA(dst, b, h) do { _Pragma("unroll") for (int m = 0; m < 4; ++m) _Pragma("unroll") for (int k = 0; k < 2; ++k) dst[m][k] = *(const PG8_LAS bf16x8*)(lds + PG8_SA(b, h) + aoff + m * 2048 + k * 1024); } while (0)
; #define PG8_MMA(ai, bj, At, Bt) do { __builtin_amdgcn_s_setprio(1); _Pragma("unroll") for (int m = 0; m < 4; ++m) _Pragma("unroll") for (int n = 0; n < 2; ++n) _Pragma("unroll") for (int k = 0; k < 2; ++k) \
;         acc[ai][bj][m][n] = __builtin_amdgcn_mfma_f32_16x16x32_bf16(Bt[n][k], At[m][k], acc[ai][bj][m][n], 0, 0, 0); __builtin_amdgcn_s_setprio(0); } while (0)
; #define PG8_WAIT_V(n) asm volatile("s_waitcnt vmcnt(" #n ")" ::: "memory")
; #define PG8_WAIT_L(n) asm volatile("s_waitcnt lgkmcnt(" #n ")" ::: "memory")
; #define PG8_BAR __builtin_amdgcn_s_barrier()
; #define PG8_SCHED __builtin_amdgcn_sched_barrier(0)
; template <class Epi, class Sched, bool ALIGN_EPI = false, bool SP2 = false>
; __device__ __forceinline__ void gemm_phase(PG8_LAS unsigned char* lds, const Gemm g, const Sched& S, const Epi& E) {
;     ...
;                 for (int n = 0; n < 2; ++n) acc[a][b][m][n] = (f32x4){0.f, 0.f, 0.f, 0.f};
;     ...
;             PG8_LDA(At, 1, 1); PG8_STAGE(PG8_SB(1, 0), b3, voffB); PG8_STAGE(PG8_SB(1, 1), b3 + hstep, voffB); PG8_STAGE(PG8_SA(1, 0), a3, voffA);
;             PG8_WAIT_V(8); PG8_WAIT_L(0); PG8_BAR; PG8_MMA(1, 0, At, B0); PG8_MMA(1, 1, At, B1); PG8_BAR; PG8_SCHED;
	s_add_i32 s26, s56, s28
	v_lshl_add_u64 v[220:221], v[220:221], 0, s[14:15]
	s_mov_b32 m0, s26
	ds_read_b128 v[160:163], v216 offset:49152
	ds_read_b128 v[164:167], v216 offset:50176
	ds_read_b128 v[168:171], v216 offset:51200
	ds_read_b128 v[172:175], v216 offset:52224
	ds_read_b128 v[196:199], v216 offset:53248
	ds_read_b128 v[200:203], v216 offset:54272
	ds_read_b128 v[204:207], v216 offset:55296
	ds_read_b128 v[208:211], v216 offset:56320
	global_load_lds_dwordx4 v[220:221], off
	v_lshl_add_u64 v[220:221], v[222:223], 0, s[14:15]
	s_add_i32 m0, s26, 0x2000
	s_add_i32 s26, s57, s28
	global_load_lds_dwordx4 v[220:221], off
	v_lshl_add_u64 v[220:221], v[224:225], 0, s[14:15]
	s_mov_b32 m0, s26
	s_nop 0
	global_load_lds_dwordx4 v[220:221], off
	v_lshl_add_u64 v[220:221], v[226:227], 0, s[14:15]
	s_add_i32 m0, s26, 0x2000
	s_nop 0
	global_load_lds_dwordx4 v[220:221], off
	v_lshl_add_u64 v[220:221], v[228:229], 0, s[14:15]
	s_mov_b32 m0, s38
	s_nop 0
	global_load_lds_dwordx4 v[220:221], off
	v_lshl_add_u64 v[220:221], v[230:231], 0, s[14:15]
	s_mov_b32 m0, s39
	s_nop 0
	global_load_lds_dwordx4 v[220:221], off
	s_waitcnt vmcnt(8)
	s_waitcnt lgkmcnt(0)
	s_barrier
	s_setprio 1
	s_waitcnt lgkmcnt(0)
	v_mfma_f32_16x16x32_bf16 v[60:63], v[124:127], v[160:163], v[60:63]
	v_mfma_f32_16x16x32_bf16 v[56:59], v[136:139], v[160:163], v[56:59]
	v_mfma_f32_16x16x32_bf16 v[44:47], v[124:127], v[168:171], v[44:47]
	v_mfma_f32_16x16x32_bf16 v[40:43], v[136:139], v[168:171], v[40:43]
	v_mfma_f32_16x16x32_bf16 v[28:31], v[124:127], v[196:199], v[28:31]
	v_mfma_f32_16x16x32_bf16 v[24:27], v[136:139], v[196:199], v[24:27]
	v_mfma_f32_16x16x32_bf16 v[12:15], v[124:127], v[204:207], v[12:15]
	v_mfma_f32_16x16x32_bf16 v[8:11], v[136:139], v[204:207], v[8:11]
	v_mfma_f32_16x16x32_bf16 v[60:63], v[132:135], v[164:167], v[60:63]
	v_mfma_f32_16x16x32_bf16 v[56:59], v[140:143], v[164:167], v[56:59]
	v_mfma_f32_16x16x32_bf16 v[44:47], v[132:135], v[172:175], v[44:47]
	v_mfma_f32_16x16x32_bf16 v[40:43], v[140:143], v[172:175], v[40:43]
	v_mfma_f32_16x16x32_bf16 v[28:31], v[132:135], v[200:203], v[28:31]
	v_mfma_f32_16x16x32_bf16 v[24:27], v[140:143], v[200:203], v[24:27]
	v_mfma_f32_16x16x32_bf16 v[12:15], v[132:135], v[208:211], v[12:15]
	v_mfma_f32_16x16x32_bf16 v[8:11], v[140:143], v[208:211], v[8:11]
	s_setprio 0
	s_setprio 1
	v_mfma_f32_16x16x32_bf16 v[52:55], v[144:147], v[160:163], v[52:55]
	v_mfma_f32_16x16x32_bf16 v[48:51], v[152:155], v[160:163], v[48:51]
	v_mfma_f32_16x16x32_bf16 v[36:39], v[144:147], v[168:171], v[36:39]
	v_mfma_f32_16x16x32_bf16 v[32:35], v[152:155], v[168:171], v[32:35]
	v_mfma_f32_16x16x32_bf16 v[20:23], v[144:147], v[196:199], v[20:23]
	v_mfma_f32_16x16x32_bf16 v[16:19], v[152:155], v[196:199], v[16:19]
	v_mfma_f32_16x16x32_bf16 v[4:7], v[144:147], v[204:207], v[4:7]
	v_mfma_f32_16x16x32_bf16 v[0:3], v[152:155], v[204:207], v[0:3]
	v_mfma_f32_16x16x32_bf16 v[52:55], v[148:151], v[164:167], v[52:55]
	v_mfma_f32_16x16x32_bf16 v[48:51], v[156:159], v[164:167], v[48:51]
	v_mfma_f32_16x16x32_bf16 v[36:39], v[148:151], v[172:175], v[36:39]
	v_mfma_f32_16x16x32_bf16 v[32:35], v[156:159], v[172:175], v[32:35]
	v_mfma_f32_16x16x32_bf16 v[20:23], v[148:151], v[200:203], v[20:23]
	v_mfma_f32_16x16x32_bf16 v[16:19], v[156:159], v[200:203], v[16:19]
	v_mfma_f32_16x16x32_bf16 v[4:7], v[148:151], v[208:211], v[4:7]
	v_mfma_f32_16x16x32_bf16 v[0:3], v[156:159], v[208:211], v[0:3]
	s_setprio 0
	s_barrier
	s_add_u32 s22, s22, 0x100
	s_addc_u32 s23, s23, 0
	s_add_u32 s53, s53, 0x100
	s_addc_u32 s54, s54, 0
	s_cmp_ge_i32 s55, s40
	s_mov_b32 s26, s55
	s_cbranch_scc0 .LBB0_1253
	s_branch .Lpx_k1253
.Lpz_k1253:
	v_mov_b64_e32 v[0:1], 0
	v_mov_b64_e32 v[2:3], 0
	v_mov_b64_e32 v[4:5], 0
	v_mov_b64_e32 v[6:7], 0
	v_mov_b64_e32 v[8:9], 0
	v_mov_b64_e32 v[10:11], 0
	v_mov_b64_e32 v[12:13], 0
	v_mov_b64_e32 v[14:15], 0
	v_mov_b64_e32 v[16:17], 0
	v_mov_b64_e32 v[18:19], 0
	v_mov_b64_e32 v[20:21], 0
	v_mov_b64_e32 v[22:23], 0
	v_mov_b64_e32 v[24:25], 0
	v_mov_b64_e32 v[26:27], 0
	v_mov_b64_e32 v[28:29], 0
	v_mov_b64_e32 v[30:31], 0
	v_mov_b64_e32 v[32:33], 0
	v_mov_b64_e32 v[34:35], 0
	v_mov_b64_e32 v[36:37], 0
	v_mov_b64_e32 v[38:39], 0
	v_mov_b64_e32 v[40:41], 0
	v_mov_b64_e32 v[42:43], 0
	v_mov_b64_e32 v[44:45], 0
	v_mov_b64_e32 v[46:47], 0
	v_mov_b64_e32 v[48:49], 0
	v_mov_b64_e32 v[50:51], 0
	v_mov_b64_e32 v[52:53], 0
	v_mov_b64_e32 v[54:55], 0
	v_mov_b64_e32 v[56:57], 0
	v_mov_b64_e32 v[58:59], 0
	v_mov_b64_e32 v[60:61], 0
	v_mov_b64_e32 v[62:63], 0
	v_mov_b64_e32 v[64:65], 0
	v_mov_b64_e32 v[66:67], 0
	v_mov_b64_e32 v[68:69], 0
	v_mov_b64_e32 v[70:71], 0
	v_mov_b64_e32 v[72:73], 0
	v_mov_b64_e32 v[74:75], 0
	v_mov_b64_e32 v[76:77], 0
	v_mov_b64_e32 v[78:79], 0
	v_mov_b64_e32 v[80:81], 0
	v_mov_b64_e32 v[82:83], 0
	v_mov_b64_e32 v[84:85], 0
	v_mov_b64_e32 v[86:87], 0
	v_mov_b64_e32 v[88:89], 0
	v_mov_b64_e32 v[90:91], 0
	v_mov_b64_e32 v[92:93], 0
	v_mov_b64_e32 v[94:95], 0
	v_mov_b64_e32 v[96:97], 0
	v_mov_b64_e32 v[98:99], 0
	v_mov_b64_e32 v[100:101], 0
	v_mov_b64_e32 v[102:103], 0
	v_mov_b64_e32 v[104:105], 0
	v_mov_b64_e32 v[106:107], 0
	v_mov_b64_e32 v[108:109], 0
	v_mov_b64_e32 v[110:111], 0
	v_mov_b64_e32 v[112:113], 0
	v_mov_b64_e32 v[114:115], 0
	v_mov_b64_e32 v[116:117], 0
	v_mov_b64_e32 v[118:119], 0
	v_mov_b64_e32 v[120:121], 0
	v_mov_b64_e32 v[122:123], 0
	v_mov_b64_e32 v[128:129], 0
	v_mov_b64_e32 v[130:131], 0
	s_branch .LBB0_1254

; #define PG8_BAR __builtin_amdgcn_s_barrier()
; template <class Epi, class Sched, bool ALIGN_EPI = false, bool SP2 = false>
; __device__ __forceinline__ void gemm_phase(PG8_LAS unsigned char* lds, const Gemm g, const Sched& S, const Epi& E) {
;     ...
;         }
;         if constexpr (ALIGN_EPI) { if (wr == 0) PG8_BAR; }
.Lpx_k1253:
.LBB0_1254:
	s_and_b64 vcc, exec, s[18:19]
	s_cbranch_vccz .LBB0_1256
	s_barrier
